# speedup vs baseline: 1.0009x; 1.0009x over previous
; #define STAGE(P, BASE, br, kt) do { const char* _g = (const char*)((BASE) + (size_t)(br) * K + (size_t)(kt) * G_BK); \
;     _Pragma("unroll") for (int _i = 0; _i < 2; ++_i) { \
;       __builtin_amdgcn_global_load_lds((const unsigned*)(_g + (size_t)_i * 128 * K + sg_off), (unsigned*)((char*)(P) + wid * 1024 + _i * 8192), 16, 0, 0); } } while (0)
; #define LDA(dst, b, h) _Pragma("unroll") for (int m = 0; m < 4; ++m) _Pragma("unroll") for (int k = 0; k < 2; ++k) \
;     dst[m][k] = *reinterpret_cast<const bf16x8*>((const char*)shm + aoff + (((b) * 2 + (h)) * 16384 + m * 2048 + k * 1024))
; #define LDB(dst, b, h) _Pragma("unroll") for (int n = 0; n < 2; ++n) _Pragma("unroll") for (int k = 0; k < 2; ++k) \
;     dst[n][k] = *reinterpret_cast<const bf16x8*>((const char*)shm + boff + (((b) * 2 + (h)) * 16384 + n * 2048 + k * 1024))
; #define WAIT_V(n) asm volatile("s_waitcnt vmcnt(" #n ")" ::: "memory")
; #define WAIT_L(n) asm volatile("s_waitcnt lgkmcnt(" #n ")" ::: "memory")
; #define BAR __builtin_amdgcn_s_barrier()
; #define SCHED __builtin_amdgcn_sched_barrier(0)
; template <class Epi>
; __device__ __forceinline__ void gemm_phase(const bfr* __restrict__ A, int lda, const bfr* __restrict__ Bt, int K,
;                                            int nM, int nN, const Epi& epi, bfr* shm, int wv, int nMfull, int ksplit) {
;     ...
;     for (int t = 0; t < nt - 2; t += 2) {
;       LDB(B0, 0, 0); SCHED; LDA(At, 0, 0); STAGE(SA(1, 1), Ak, brow + G_HALF, t + 1);
;       WAIT_L(8); BAR; WAIT_L(0); MMA(0, 0, At, B0); BAR; SCHED;
;       LDB(B1, 0, 1); STAGE(SB(0, 0), Bk, bcol, t + 2);
;       BAR; WAIT_L(0); MMA(0, 1, At, B1); BAR;
;       LDA(At, 0, 1); STAGE(SA(0, 0), Ak, brow, t + 2);
;       BAR; WAIT_L(0); MMA(1, 0, At, B0); BAR; SCHED;
;       STAGE(SB(0, 1), Bk, bcol + G_HALF, t + 2);
;       WAIT_V(6); BAR; MMA(1, 1, At, B1); BAR;
;       LDB(B0, 1, 0); SCHED; LDA(At, 1, 0); STAGE(SA(0, 1), Ak, brow + G_HALF, t + 2);
;       WAIT_L(8); BAR; WAIT_L(0); MMA(0, 0, At, B0); BAR; SCHED;
;       LDB(B1, 1, 1); STAGE(SB(1, 0), Bk, bcol, t + 3);
;       BAR; WAIT_L(0); MMA(0, 1, At, B1); BAR;
;       LDA(At, 1, 1); STAGE(SA(1, 0), Ak, brow, t + 3);
;       BAR; WAIT_L(0); MMA(1, 0, At, B0); BAR; SCHED;
;       STAGE(SB(1, 1), Bk, bcol + G_HALF, t + 3);
;       WAIT_V(6); BAR; MMA(1, 1, At, B1); BAR;
;     }
.LBB0_195:
	ds_read_b128 v[142:145], v139
	ds_read_b128 v[146:149], v139 offset:1024
	ds_read_b128 v[150:153], v139 offset:2048
	ds_read_b128 v[154:157], v139 offset:3072
	ds_read_b128 v[158:161], v138
	ds_read_b128 v[162:165], v138 offset:1024
	ds_read_b128 v[166:169], v138 offset:2048
	ds_read_b128 v[170:173], v138 offset:3072
	ds_read_b128 v[174:177], v138 offset:4096
	ds_read_b128 v[178:181], v138 offset:5120
	ds_read_b128 v[182:185], v138 offset:6144
	ds_read_b128 v[186:189], v138 offset:7168
	ds_read_b128 v[190:193], v139 offset:16384
	ds_read_b128 v[194:197], v139 offset:17408
	ds_read_b128 v[198:201], v139 offset:18432
	ds_read_b128 v[202:205], v139 offset:19456
	v_lshl_add_u64 v[136:137], s[38:39], 0, v[134:135]
	v_lshl_add_u64 v[206:207], s[36:37], 0, v[134:135]
	s_mov_b32 m0, s54
	s_mov_b64 s[46:47], 0x40080
	v_lshl_add_u64 v[210:211], v[136:137], 0, s[46:47]
	global_load_lds_dwordx4 v[210:211], off
	s_mov_b32 m0, s55
	s_mov_b64 s[46:47], 0x60080
	v_lshl_add_u64 v[212:213], v[136:137], 0, s[46:47]
	global_load_lds_dwordx4 v[212:213], off
	s_waitcnt lgkmcnt(0)
	s_barrier
	v_mfma_f32_16x16x32_bf16 v[124:127], v[158:161], v[142:145], v[124:127]
	v_mfma_f32_16x16x32_bf16 v[120:123], v[158:161], v[150:153], v[120:123]
	v_mfma_f32_16x16x32_bf16 v[116:119], v[166:169], v[142:145], v[116:119]
	v_mfma_f32_16x16x32_bf16 v[112:115], v[166:169], v[150:153], v[112:115]
	v_mfma_f32_16x16x32_bf16 v[108:111], v[174:177], v[142:145], v[108:111]
	v_mfma_f32_16x16x32_bf16 v[104:107], v[174:177], v[150:153], v[104:107]
	v_mfma_f32_16x16x32_bf16 v[100:103], v[182:185], v[142:145], v[100:103]
	v_mfma_f32_16x16x32_bf16 v[96:99], v[182:185], v[150:153], v[96:99]
	v_mfma_f32_16x16x32_bf16 v[124:127], v[162:165], v[146:149], v[124:127]
	v_mfma_f32_16x16x32_bf16 v[120:123], v[162:165], v[154:157], v[120:123]
	v_mfma_f32_16x16x32_bf16 v[116:119], v[170:173], v[146:149], v[116:119]
	v_mfma_f32_16x16x32_bf16 v[112:115], v[170:173], v[154:157], v[112:115]
	v_mfma_f32_16x16x32_bf16 v[108:111], v[178:181], v[146:149], v[108:111]
	v_mfma_f32_16x16x32_bf16 v[104:107], v[178:181], v[154:157], v[104:107]
	v_mfma_f32_16x16x32_bf16 v[100:103], v[186:189], v[146:149], v[100:103]
	v_mfma_f32_16x16x32_bf16 v[96:99], v[186:189], v[154:157], v[96:99]
	v_mfma_f32_16x16x32_bf16 v[92:95], v[158:161], v[190:193], v[92:95]
	v_mfma_f32_16x16x32_bf16 v[88:91], v[158:161], v[198:201], v[88:91]
	v_mfma_f32_16x16x32_bf16 v[84:87], v[166:169], v[190:193], v[84:87]
	v_mfma_f32_16x16x32_bf16 v[80:83], v[166:169], v[198:201], v[80:83]
	v_mfma_f32_16x16x32_bf16 v[76:79], v[174:177], v[190:193], v[76:79]
	v_mfma_f32_16x16x32_bf16 v[72:75], v[174:177], v[198:201], v[72:75]
	v_mfma_f32_16x16x32_bf16 v[68:71], v[182:185], v[190:193], v[68:71]
	v_mfma_f32_16x16x32_bf16 v[64:67], v[182:185], v[198:201], v[64:67]
	v_mfma_f32_16x16x32_bf16 v[92:95], v[162:165], v[194:197], v[92:95]
	v_mfma_f32_16x16x32_bf16 v[88:91], v[162:165], v[202:205], v[88:91]
	v_mfma_f32_16x16x32_bf16 v[84:87], v[170:173], v[194:197], v[84:87]
	v_mfma_f32_16x16x32_bf16 v[80:83], v[170:173], v[202:205], v[80:83]
	v_mfma_f32_16x16x32_bf16 v[76:79], v[178:181], v[194:197], v[76:79]
	v_mfma_f32_16x16x32_bf16 v[72:75], v[178:181], v[202:205], v[72:75]
	v_mfma_f32_16x16x32_bf16 v[68:71], v[186:189], v[194:197], v[68:71]
	v_mfma_f32_16x16x32_bf16 v[64:67], v[186:189], v[202:205], v[64:67]
	s_barrier
	ds_read_b128 v[158:161], v138 offset:16384
	ds_read_b128 v[162:165], v138 offset:17408
	ds_read_b128 v[166:169], v138 offset:18432
	ds_read_b128 v[170:173], v138 offset:19456
	ds_read_b128 v[174:177], v138 offset:20480
	ds_read_b128 v[178:181], v138 offset:21504
	ds_read_b128 v[182:185], v138 offset:22528
	ds_read_b128 v[186:189], v138 offset:23552
	s_mov_b32 m0, s24
	v_lshl_add_u64 v[214:215], v[206:207], 0, s[10:11]
	global_load_lds_dwordx4 v[214:215], off
	s_mov_b32 m0, s25
	v_lshl_add_u64 v[210:211], v[206:207], 0, s[12:13]
	global_load_lds_dwordx4 v[210:211], off
	s_mov_b32 m0, s23
	v_lshl_add_u64 v[212:213], v[136:137], 0, s[10:11]
	global_load_lds_dwordx4 v[212:213], off
	s_mov_b32 m0, s26
	v_lshl_add_u64 v[214:215], v[136:137], 0, s[12:13]
	global_load_lds_dwordx4 v[214:215], off
	s_mov_b32 m0, s27
	v_lshl_add_u64 v[210:211], v[206:207], 0, s[14:15]
	global_load_lds_dwordx4 v[210:211], off
	s_mov_b32 m0, s28
	v_lshl_add_u64 v[212:213], v[206:207], 0, s[16:17]
	global_load_lds_dwordx4 v[212:213], off
	s_waitcnt vmcnt(6)
	s_waitcnt lgkmcnt(0)
	s_barrier
	v_mfma_f32_16x16x32_bf16 v[60:63], v[158:161], v[142:145], v[60:63]
	v_mfma_f32_16x16x32_bf16 v[56:59], v[158:161], v[150:153], v[56:59]
	v_mfma_f32_16x16x32_bf16 v[52:55], v[166:169], v[142:145], v[52:55]
	v_mfma_f32_16x16x32_bf16 v[48:51], v[166:169], v[150:153], v[48:51]
	v_mfma_f32_16x16x32_bf16 v[44:47], v[174:177], v[142:145], v[44:47]
	v_mfma_f32_16x16x32_bf16 v[40:43], v[174:177], v[150:153], v[40:43]
	v_mfma_f32_16x16x32_bf16 v[36:39], v[182:185], v[142:145], v[36:39]
	v_mfma_f32_16x16x32_bf16 v[32:35], v[182:185], v[150:153], v[32:35]
	v_mfma_f32_16x16x32_bf16 v[60:63], v[162:165], v[146:149], v[60:63]
	v_mfma_f32_16x16x32_bf16 v[56:59], v[162:165], v[154:157], v[56:59]
	v_mfma_f32_16x16x32_bf16 v[52:55], v[170:173], v[146:149], v[52:55]
	v_mfma_f32_16x16x32_bf16 v[48:51], v[170:173], v[154:157], v[48:51]
	v_mfma_f32_16x16x32_bf16 v[44:47], v[178:181], v[146:149], v[44:47]
	v_mfma_f32_16x16x32_bf16 v[40:43], v[178:181], v[154:157], v[40:43]
	v_mfma_f32_16x16x32_bf16 v[36:39], v[186:189], v[146:149], v[36:39]
	v_mfma_f32_16x16x32_bf16 v[32:35], v[186:189], v[154:157], v[32:35]
	v_mfma_f32_16x16x32_bf16 v[28:31], v[158:161], v[190:193], v[28:31]
	v_mfma_f32_16x16x32_bf16 v[24:27], v[158:161], v[198:201], v[24:27]
	v_mfma_f32_16x16x32_bf16 v[20:23], v[166:169], v[190:193], v[20:23]
	v_mfma_f32_16x16x32_bf16 v[16:19], v[166:169], v[198:201], v[16:19]
	v_mfma_f32_16x16x32_bf16 v[12:15], v[174:177], v[190:193], v[12:15]
	v_mfma_f32_16x16x32_bf16 v[8:11], v[174:177], v[198:201], v[8:11]
	v_mfma_f32_16x16x32_bf16 v[4:7], v[182:185], v[190:193], v[4:7]
	v_mfma_f32_16x16x32_bf16 v[0:3], v[182:185], v[198:201], v[0:3]
	v_mfma_f32_16x16x32_bf16 v[28:31], v[162:165], v[194:197], v[28:31]
	v_mfma_f32_16x16x32_bf16 v[24:27], v[162:165], v[202:205], v[24:27]
	v_mfma_f32_16x16x32_bf16 v[20:23], v[170:173], v[194:197], v[20:23]
	v_mfma_f32_16x16x32_bf16 v[16:19], v[170:173], v[202:205], v[16:19]
	v_mfma_f32_16x16x32_bf16 v[12:15], v[178:181], v[194:197], v[12:15]
	v_mfma_f32_16x16x32_bf16 v[8:11], v[178:181], v[202:205], v[8:11]
	v_mfma_f32_16x16x32_bf16 v[4:7], v[186:189], v[194:197], v[4:7]
	v_mfma_f32_16x16x32_bf16 v[0:3], v[186:189], v[202:205], v[0:3]
	s_barrier
; #define STAGE(P, BASE, br, kt) do { const char* _g = (const char*)((BASE) + (size_t)(br) * K + (size_t)(kt) * G_BK); \
;     _Pragma("unroll") for (int _i = 0; _i < 2; ++_i) { \
;       __builtin_amdgcn_global_load_lds((const unsigned*)(_g + (size_t)_i * 128 * K + sg_off), (unsigned*)((char*)(P) + wid * 1024 + _i * 8192), 16, 0, 0); } } while (0)
; #define LDA(dst, b, h) _Pragma("unroll") for (int m = 0; m < 4; ++m) _Pragma("unroll") for (int k = 0; k < 2; ++k) \
;     dst[m][k] = *reinterpret_cast<const bf16x8*>((const char*)shm + aoff + (((b) * 2 + (h)) * 16384 + m * 2048 + k * 1024))
; #define LDB(dst, b, h) _Pragma("unroll") for (int n = 0; n < 2; ++n) _Pragma("unroll") for (int k = 0; k < 2; ++k) \
;     dst[n][k] = *reinterpret_cast<const bf16x8*>((const char*)shm + boff + (((b) * 2 + (h)) * 16384 + n * 2048 + k * 1024))
; #define WAIT_V(n) asm volatile("s_waitcnt vmcnt(" #n ")" ::: "memory")
; #define WAIT_L(n) asm volatile("s_waitcnt lgkmcnt(" #n ")" ::: "memory")
; #define BAR __builtin_amdgcn_s_barrier()
; #define SCHED __builtin_amdgcn_sched_barrier(0)
; template <class Epi>
; __device__ __forceinline__ void gemm_phase(const bfr* __restrict__ A, int lda, const bfr* __restrict__ Bt, int K,
;                                            int nM, int nN, const Epi& epi, bfr* shm, int wv, int nMfull, int ksplit) {
;     ...
;     for (int t = 0; t < nt - 2; t += 2) {
;       LDB(B0, 0, 0); SCHED; LDA(At, 0, 0); STAGE(SA(1, 1), Ak, brow + G_HALF, t + 1);
;       WAIT_L(8); BAR; WAIT_L(0); MMA(0, 0, At, B0); BAR; SCHED;
;       LDB(B1, 0, 1); STAGE(SB(0, 0), Bk, bcol, t + 2);
;       BAR; WAIT_L(0); MMA(0, 1, At, B1); BAR;
;       LDA(At, 0, 1); STAGE(SA(0, 0), Ak, brow, t + 2);
;       BAR; WAIT_L(0); MMA(1, 0, At, B0); BAR; SCHED;
;       STAGE(SB(0, 1), Bk, bcol + G_HALF, t + 2);
;       WAIT_V(6); BAR; MMA(1, 1, At, B1); BAR;
;       LDB(B0, 1, 0); SCHED; LDA(At, 1, 0); STAGE(SA(0, 1), Ak, brow + G_HALF, t + 2);
;       WAIT_L(8); BAR; WAIT_L(0); MMA(0, 0, At, B0); BAR; SCHED;
;       LDB(B1, 1, 1); STAGE(SB(1, 0), Bk, bcol, t + 3);
;       BAR; WAIT_L(0); MMA(0, 1, At, B1); BAR;
;       LDA(At, 1, 1); STAGE(SA(1, 0), Ak, brow, t + 3);
;       BAR; WAIT_L(0); MMA(1, 0, At, B0); BAR; SCHED;
;       STAGE(SB(1, 1), Bk, bcol + G_HALF, t + 3);
;       WAIT_V(6); BAR; MMA(1, 1, At, B1); BAR;
;     }
	ds_read_b128 v[142:145], v139 offset:32768
	ds_read_b128 v[146:149], v139 offset:33792
	ds_read_b128 v[150:153], v139 offset:34816
	ds_read_b128 v[154:157], v139 offset:35840
	ds_read_b128 v[158:161], v138 offset:32768
	ds_read_b128 v[162:165], v138 offset:33792
	ds_read_b128 v[166:169], v138 offset:34816
	ds_read_b128 v[170:173], v138 offset:35840
	ds_read_b128 v[174:177], v138 offset:36864
	ds_read_b128 v[178:181], v138 offset:37888
	ds_read_b128 v[182:185], v138 offset:38912
	ds_read_b128 v[186:189], v138 offset:39936
	ds_read_b128 v[190:193], v139 offset:49152
	ds_read_b128 v[194:197], v139 offset:50176
	ds_read_b128 v[198:201], v139 offset:51200
	ds_read_b128 v[202:205], v139 offset:52224
	s_mov_b32 m0, s29
	v_lshl_add_u64 v[214:215], v[136:137], 0, s[14:15]
	global_load_lds_dwordx4 v[214:215], off
	s_mov_b32 m0, s33
	v_lshl_add_u64 v[210:211], v[136:137], 0, s[16:17]
	global_load_lds_dwordx4 v[210:211], off
	s_waitcnt lgkmcnt(0)
	s_barrier
	v_mfma_f32_16x16x32_bf16 v[124:127], v[158:161], v[142:145], v[124:127]
	v_mfma_f32_16x16x32_bf16 v[120:123], v[158:161], v[150:153], v[120:123]
	v_mfma_f32_16x16x32_bf16 v[116:119], v[166:169], v[142:145], v[116:119]
	v_mfma_f32_16x16x32_bf16 v[112:115], v[166:169], v[150:153], v[112:115]
	v_mfma_f32_16x16x32_bf16 v[108:111], v[174:177], v[142:145], v[108:111]
	v_mfma_f32_16x16x32_bf16 v[104:107], v[174:177], v[150:153], v[104:107]
	v_mfma_f32_16x16x32_bf16 v[100:103], v[182:185], v[142:145], v[100:103]
	v_mfma_f32_16x16x32_bf16 v[96:99], v[182:185], v[150:153], v[96:99]
	v_mfma_f32_16x16x32_bf16 v[124:127], v[162:165], v[146:149], v[124:127]
	v_mfma_f32_16x16x32_bf16 v[120:123], v[162:165], v[154:157], v[120:123]
	v_mfma_f32_16x16x32_bf16 v[116:119], v[170:173], v[146:149], v[116:119]
	v_mfma_f32_16x16x32_bf16 v[112:115], v[170:173], v[154:157], v[112:115]
	v_mfma_f32_16x16x32_bf16 v[108:111], v[178:181], v[146:149], v[108:111]
	v_mfma_f32_16x16x32_bf16 v[104:107], v[178:181], v[154:157], v[104:107]
	v_mfma_f32_16x16x32_bf16 v[100:103], v[186:189], v[146:149], v[100:103]
	v_mfma_f32_16x16x32_bf16 v[96:99], v[186:189], v[154:157], v[96:99]
	v_mfma_f32_16x16x32_bf16 v[92:95], v[158:161], v[190:193], v[92:95]
	v_mfma_f32_16x16x32_bf16 v[88:91], v[158:161], v[198:201], v[88:91]
	v_mfma_f32_16x16x32_bf16 v[84:87], v[166:169], v[190:193], v[84:87]
	v_mfma_f32_16x16x32_bf16 v[80:83], v[166:169], v[198:201], v[80:83]
	v_mfma_f32_16x16x32_bf16 v[76:79], v[174:177], v[190:193], v[76:79]
	v_mfma_f32_16x16x32_bf16 v[72:75], v[174:177], v[198:201], v[72:75]
	v_mfma_f32_16x16x32_bf16 v[68:71], v[182:185], v[190:193], v[68:71]
	v_mfma_f32_16x16x32_bf16 v[64:67], v[182:185], v[198:201], v[64:67]
	v_mfma_f32_16x16x32_bf16 v[92:95], v[162:165], v[194:197], v[92:95]
	v_mfma_f32_16x16x32_bf16 v[88:91], v[162:165], v[202:205], v[88:91]
	v_mfma_f32_16x16x32_bf16 v[84:87], v[170:173], v[194:197], v[84:87]
	v_mfma_f32_16x16x32_bf16 v[80:83], v[170:173], v[202:205], v[80:83]
	v_mfma_f32_16x16x32_bf16 v[76:79], v[178:181], v[194:197], v[76:79]
	v_mfma_f32_16x16x32_bf16 v[72:75], v[178:181], v[202:205], v[72:75]
	v_mfma_f32_16x16x32_bf16 v[68:71], v[186:189], v[194:197], v[68:71]
	v_mfma_f32_16x16x32_bf16 v[64:67], v[186:189], v[202:205], v[64:67]
	s_barrier
	ds_read_b128 v[158:161], v138 offset:49152
	ds_read_b128 v[162:165], v138 offset:50176
	ds_read_b128 v[166:169], v138 offset:51200
	ds_read_b128 v[170:173], v138 offset:52224
	ds_read_b128 v[174:177], v138 offset:53248
	ds_read_b128 v[178:181], v138 offset:54272
	ds_read_b128 v[182:185], v138 offset:55296
	ds_read_b128 v[186:189], v138 offset:56320
	s_mov_b32 m0, s48
	v_lshl_add_u64 v[212:213], v[206:207], 0, s[18:19]
	global_load_lds_dwordx4 v[212:213], off
	s_mov_b32 m0, s49
	v_lshl_add_u64 v[214:215], v[206:207], 0, s[20:21]
	global_load_lds_dwordx4 v[214:215], off
	s_mov_b32 m0, s50
	v_lshl_add_u64 v[210:211], v[136:137], 0, s[18:19]
	global_load_lds_dwordx4 v[210:211], off
	s_mov_b32 m0, s51
	v_lshl_add_u64 v[212:213], v[136:137], 0, s[20:21]
	global_load_lds_dwordx4 v[212:213], off
	s_mov_b32 m0, s52
	s_mov_b64 s[46:47], 0x40180
	v_lshl_add_u64 v[214:215], v[206:207], 0, s[46:47]
	global_load_lds_dwordx4 v[214:215], off
	s_mov_b32 m0, s53
	s_mov_b64 s[46:47], 0x60180
	v_lshl_add_u64 v[210:211], v[206:207], 0, s[46:47]
	global_load_lds_dwordx4 v[210:211], off
	s_waitcnt vmcnt(6)
	s_waitcnt lgkmcnt(0)
	s_barrier
	v_mfma_f32_16x16x32_bf16 v[60:63], v[158:161], v[142:145], v[60:63]
	v_mfma_f32_16x16x32_bf16 v[56:59], v[158:161], v[150:153], v[56:59]
	v_mfma_f32_16x16x32_bf16 v[52:55], v[166:169], v[142:145], v[52:55]
	v_mfma_f32_16x16x32_bf16 v[48:51], v[166:169], v[150:153], v[48:51]
	v_mfma_f32_16x16x32_bf16 v[44:47], v[174:177], v[142:145], v[44:47]
	v_mfma_f32_16x16x32_bf16 v[40:43], v[174:177], v[150:153], v[40:43]
	v_mfma_f32_16x16x32_bf16 v[36:39], v[182:185], v[142:145], v[36:39]
	v_mfma_f32_16x16x32_bf16 v[32:35], v[182:185], v[150:153], v[32:35]
	v_mfma_f32_16x16x32_bf16 v[60:63], v[162:165], v[146:149], v[60:63]
	v_mfma_f32_16x16x32_bf16 v[56:59], v[162:165], v[154:157], v[56:59]
	v_mfma_f32_16x16x32_bf16 v[52:55], v[170:173], v[146:149], v[52:55]
	v_mfma_f32_16x16x32_bf16 v[48:51], v[170:173], v[154:157], v[48:51]
	v_mfma_f32_16x16x32_bf16 v[44:47], v[178:181], v[146:149], v[44:47]
	v_mfma_f32_16x16x32_bf16 v[40:43], v[178:181], v[154:157], v[40:43]
	v_mfma_f32_16x16x32_bf16 v[36:39], v[186:189], v[146:149], v[36:39]
	v_mfma_f32_16x16x32_bf16 v[32:35], v[186:189], v[154:157], v[32:35]
	v_mfma_f32_16x16x32_bf16 v[28:31], v[158:161], v[190:193], v[28:31]
	v_mfma_f32_16x16x32_bf16 v[24:27], v[158:161], v[198:201], v[24:27]
	v_mfma_f32_16x16x32_bf16 v[20:23], v[166:169], v[190:193], v[20:23]
	v_mfma_f32_16x16x32_bf16 v[16:19], v[166:169], v[198:201], v[16:19]
	v_mfma_f32_16x16x32_bf16 v[12:15], v[174:177], v[190:193], v[12:15]
	v_mfma_f32_16x16x32_bf16 v[8:11], v[174:177], v[198:201], v[8:11]
	v_mfma_f32_16x16x32_bf16 v[4:7], v[182:185], v[190:193], v[4:7]
	v_mfma_f32_16x16x32_bf16 v[0:3], v[182:185], v[198:201], v[0:3]
	v_mfma_f32_16x16x32_bf16 v[28:31], v[162:165], v[194:197], v[28:31]
	v_mfma_f32_16x16x32_bf16 v[24:27], v[162:165], v[202:205], v[24:27]
	v_mfma_f32_16x16x32_bf16 v[20:23], v[170:173], v[194:197], v[20:23]
	v_mfma_f32_16x16x32_bf16 v[16:19], v[170:173], v[202:205], v[16:19]
	v_mfma_f32_16x16x32_bf16 v[12:15], v[178:181], v[194:197], v[12:15]
	v_mfma_f32_16x16x32_bf16 v[8:11], v[178:181], v[202:205], v[8:11]
	v_mfma_f32_16x16x32_bf16 v[4:7], v[186:189], v[194:197], v[4:7]
	v_mfma_f32_16x16x32_bf16 v[0:3], v[186:189], v[202:205], v[0:3]
	s_add_i32 s40, s40, 2
	s_add_u32 s36, s36, 0x100
	s_addc_u32 s37, s37, 0
	s_add_u32 s38, s38, 0x100
	s_addc_u32 s39, s39, 0
	s_cmp_ge_i32 s40, s31
	s_barrier
	s_cbranch_scc0 .LBB0_195

; #define STAGE(P, BASE, br, kt) do { const char* _g = (const char*)((BASE) + (size_t)(br) * K + (size_t)(kt) * G_BK); \
;     _Pragma("unroll") for (int _i = 0; _i < 2; ++_i) { \
;       __builtin_amdgcn_global_load_lds((const unsigned*)(_g + (size_t)_i * 128 * K + sg_off), (unsigned*)((char*)(P) + wid * 1024 + _i * 8192), 16, 0, 0); } } while (0)
; #define LDA(dst, b, h) _Pragma("unroll") for (int m = 0; m < 4; ++m) _Pragma("unroll") for (int k = 0; k < 2; ++k) \
;     dst[m][k] = *reinterpret_cast<const bf16x8*>((const char*)shm + aoff + (((b) * 2 + (h)) * 16384 + m * 2048 + k * 1024))
; #define LDB(dst, b, h) _Pragma("unroll") for (int n = 0; n < 2; ++n) _Pragma("unroll") for (int k = 0; k < 2; ++k) \
;     dst[n][k] = *reinterpret_cast<const bf16x8*>((const char*)shm + boff + (((b) * 2 + (h)) * 16384 + n * 2048 + k * 1024))
; #define WAIT_V(n) asm volatile("s_waitcnt vmcnt(" #n ")" ::: "memory")
; #define WAIT_L(n) asm volatile("s_waitcnt lgkmcnt(" #n ")" ::: "memory")
; #define BAR __builtin_amdgcn_s_barrier()
; #define SCHED __builtin_amdgcn_sched_barrier(0)
; template <class Epi>
; __device__ __forceinline__ void gemm_phase(const bfr* __restrict__ A, int lda, const bfr* __restrict__ Bt, int K,
;                                            int nM, int nN, const Epi& epi, bfr* shm, int wv, int nMfull, int ksplit) {
;     ...
;     for (int t = 0; t < nt - 2; t += 2) {
;       LDB(B0, 0, 0); SCHED; LDA(At, 0, 0); STAGE(SA(1, 1), Ak, brow + G_HALF, t + 1);
;       WAIT_L(8); BAR; WAIT_L(0); MMA(0, 0, At, B0); BAR; SCHED;
;       LDB(B1, 0, 1); STAGE(SB(0, 0), Bk, bcol, t + 2);
;       BAR; WAIT_L(0); MMA(0, 1, At, B1); BAR;
;       LDA(At, 0, 1); STAGE(SA(0, 0), Ak, brow, t + 2);
;       BAR; WAIT_L(0); MMA(1, 0, At, B0); BAR; SCHED;
;       STAGE(SB(0, 1), Bk, bcol + G_HALF, t + 2);
;       WAIT_V(6); BAR; MMA(1, 1, At, B1); BAR;
;       LDB(B0, 1, 0); SCHED; LDA(At, 1, 0); STAGE(SA(0, 1), Ak, brow + G_HALF, t + 2);
;       WAIT_L(8); BAR; WAIT_L(0); MMA(0, 0, At, B0); BAR; SCHED;
;       LDB(B1, 1, 1); STAGE(SB(1, 0), Bk, bcol, t + 3);
;       BAR; WAIT_L(0); MMA(0, 1, At, B1); BAR;
;       LDA(At, 1, 1); STAGE(SA(1, 0), Ak, brow, t + 3);
;       BAR; WAIT_L(0); MMA(1, 0, At, B0); BAR; SCHED;
;       STAGE(SB(1, 1), Bk, bcol + G_HALF, t + 3);
;       WAIT_V(6); BAR; MMA(1, 1, At, B1); BAR;
;     }
.LBB0_242:
	ds_read_b128 v[140:143], v178
	ds_read_b128 v[144:147], v178 offset:1024
	ds_read_b128 v[148:151], v178 offset:2048
	ds_read_b128 v[152:155], v178 offset:3072
	ds_read_b128 v[156:159], v129
	ds_read_b128 v[160:163], v129 offset:1024
	ds_read_b128 v[164:167], v129 offset:2048
	ds_read_b128 v[168:171], v129 offset:3072
	ds_read_b128 v[172:175], v129 offset:4096
	ds_read_b128 v[180:183], v129 offset:5120
	ds_read_b128 v[184:187], v129 offset:6144
	ds_read_b128 v[188:191], v129 offset:7168
	ds_read_b128 v[192:195], v178 offset:16384
	ds_read_b128 v[196:199], v178 offset:17408
	ds_read_b128 v[200:203], v178 offset:18432
	ds_read_b128 v[204:207], v178 offset:19456
	v_lshl_add_u64 v[176:177], s[44:45], 0, v[138:139]
	v_lshl_add_u64 v[208:209], s[38:39], 0, v[138:139]
	s_mov_b32 m0, s28
	v_lshl_add_u64 v[212:213], v[176:177], 0, s[16:17]
	global_load_lds_dwordx4 v[212:213], off
	s_mov_b32 m0, s29
	v_lshl_add_u64 v[214:215], v[176:177], 0, s[18:19]
	global_load_lds_dwordx4 v[214:215], off
	s_waitcnt lgkmcnt(0)
	s_barrier
	v_mfma_f32_16x16x32_bf16 v[124:127], v[156:159], v[140:143], v[124:127]
	v_mfma_f32_16x16x32_bf16 v[120:123], v[156:159], v[148:151], v[120:123]
	v_mfma_f32_16x16x32_bf16 v[116:119], v[164:167], v[140:143], v[116:119]
	v_mfma_f32_16x16x32_bf16 v[112:115], v[164:167], v[148:151], v[112:115]
	v_mfma_f32_16x16x32_bf16 v[108:111], v[172:175], v[140:143], v[108:111]
	v_mfma_f32_16x16x32_bf16 v[104:107], v[172:175], v[148:151], v[104:107]
	v_mfma_f32_16x16x32_bf16 v[100:103], v[184:187], v[140:143], v[100:103]
	v_mfma_f32_16x16x32_bf16 v[96:99], v[184:187], v[148:151], v[96:99]
	v_mfma_f32_16x16x32_bf16 v[124:127], v[160:163], v[144:147], v[124:127]
	v_mfma_f32_16x16x32_bf16 v[120:123], v[160:163], v[152:155], v[120:123]
	v_mfma_f32_16x16x32_bf16 v[116:119], v[168:171], v[144:147], v[116:119]
	v_mfma_f32_16x16x32_bf16 v[112:115], v[168:171], v[152:155], v[112:115]
	v_mfma_f32_16x16x32_bf16 v[108:111], v[180:183], v[144:147], v[108:111]
	v_mfma_f32_16x16x32_bf16 v[104:107], v[180:183], v[152:155], v[104:107]
	v_mfma_f32_16x16x32_bf16 v[100:103], v[188:191], v[144:147], v[100:103]
	v_mfma_f32_16x16x32_bf16 v[96:99], v[188:191], v[152:155], v[96:99]
	v_mfma_f32_16x16x32_bf16 v[92:95], v[156:159], v[192:195], v[92:95]
	v_mfma_f32_16x16x32_bf16 v[88:91], v[156:159], v[200:203], v[88:91]
	v_mfma_f32_16x16x32_bf16 v[84:87], v[164:167], v[192:195], v[84:87]
	v_mfma_f32_16x16x32_bf16 v[80:83], v[164:167], v[200:203], v[80:83]
	v_mfma_f32_16x16x32_bf16 v[76:79], v[172:175], v[192:195], v[76:79]
	v_mfma_f32_16x16x32_bf16 v[72:75], v[172:175], v[200:203], v[72:75]
	v_mfma_f32_16x16x32_bf16 v[68:71], v[184:187], v[192:195], v[68:71]
	v_mfma_f32_16x16x32_bf16 v[64:67], v[184:187], v[200:203], v[64:67]
	v_mfma_f32_16x16x32_bf16 v[92:95], v[160:163], v[196:199], v[92:95]
	v_mfma_f32_16x16x32_bf16 v[88:91], v[160:163], v[204:207], v[88:91]
	v_mfma_f32_16x16x32_bf16 v[84:87], v[168:171], v[196:199], v[84:87]
	v_mfma_f32_16x16x32_bf16 v[80:83], v[168:171], v[204:207], v[80:83]
	v_mfma_f32_16x16x32_bf16 v[76:79], v[180:183], v[196:199], v[76:79]
	v_mfma_f32_16x16x32_bf16 v[72:75], v[180:183], v[204:207], v[72:75]
	v_mfma_f32_16x16x32_bf16 v[68:71], v[188:191], v[196:199], v[68:71]
	v_mfma_f32_16x16x32_bf16 v[64:67], v[188:191], v[204:207], v[64:67]
	s_barrier
	ds_read_b128 v[156:159], v129 offset:16384
	ds_read_b128 v[160:163], v129 offset:17408
	ds_read_b128 v[164:167], v129 offset:18432
	ds_read_b128 v[168:171], v129 offset:19456
	ds_read_b128 v[172:175], v129 offset:20480
	ds_read_b128 v[180:183], v129 offset:21504
	ds_read_b128 v[184:187], v129 offset:22528
	ds_read_b128 v[188:191], v129 offset:23552
	s_mov_b32 m0, s33
	v_lshl_add_u64 v[216:217], v[208:209], 0, s[20:21]
	global_load_lds_dwordx4 v[216:217], off
	s_mov_b32 m0, s92
	v_lshl_add_u64 v[212:213], v[208:209], 0, s[30:31]
	global_load_lds_dwordx4 v[212:213], off
	s_mov_b32 m0, s26
	v_lshl_add_u64 v[214:215], v[176:177], 0, s[20:21]
	global_load_lds_dwordx4 v[214:215], off
	s_mov_b32 m0, s93
	v_lshl_add_u64 v[216:217], v[176:177], 0, s[30:31]
	global_load_lds_dwordx4 v[216:217], off
	s_mov_b32 m0, s10
	v_lshl_add_u64 v[212:213], v[208:209], 0, s[40:41]
	global_load_lds_dwordx4 v[212:213], off
	s_mov_b32 m0, s11
	v_lshl_add_u64 v[214:215], v[208:209], 0, s[42:43]
	global_load_lds_dwordx4 v[214:215], off
	s_waitcnt vmcnt(6)
	s_waitcnt lgkmcnt(0)
	s_barrier
	v_mfma_f32_16x16x32_bf16 v[60:63], v[156:159], v[140:143], v[60:63]
	v_mfma_f32_16x16x32_bf16 v[56:59], v[156:159], v[148:151], v[56:59]
	v_mfma_f32_16x16x32_bf16 v[52:55], v[164:167], v[140:143], v[52:55]
	v_mfma_f32_16x16x32_bf16 v[48:51], v[164:167], v[148:151], v[48:51]
	v_mfma_f32_16x16x32_bf16 v[44:47], v[172:175], v[140:143], v[44:47]
	v_mfma_f32_16x16x32_bf16 v[40:43], v[172:175], v[148:151], v[40:43]
	v_mfma_f32_16x16x32_bf16 v[36:39], v[184:187], v[140:143], v[36:39]
	v_mfma_f32_16x16x32_bf16 v[32:35], v[184:187], v[148:151], v[32:35]
	v_mfma_f32_16x16x32_bf16 v[60:63], v[160:163], v[144:147], v[60:63]
	v_mfma_f32_16x16x32_bf16 v[56:59], v[160:163], v[152:155], v[56:59]
	v_mfma_f32_16x16x32_bf16 v[52:55], v[168:171], v[144:147], v[52:55]
	v_mfma_f32_16x16x32_bf16 v[48:51], v[168:171], v[152:155], v[48:51]
	v_mfma_f32_16x16x32_bf16 v[44:47], v[180:183], v[144:147], v[44:47]
	v_mfma_f32_16x16x32_bf16 v[40:43], v[180:183], v[152:155], v[40:43]
	v_mfma_f32_16x16x32_bf16 v[36:39], v[188:191], v[144:147], v[36:39]
	v_mfma_f32_16x16x32_bf16 v[32:35], v[188:191], v[152:155], v[32:35]
	v_mfma_f32_16x16x32_bf16 v[28:31], v[156:159], v[192:195], v[28:31]
	v_mfma_f32_16x16x32_bf16 v[24:27], v[156:159], v[200:203], v[24:27]
	v_mfma_f32_16x16x32_bf16 v[20:23], v[164:167], v[192:195], v[20:23]
	v_mfma_f32_16x16x32_bf16 v[16:19], v[164:167], v[200:203], v[16:19]
	v_mfma_f32_16x16x32_bf16 v[12:15], v[172:175], v[192:195], v[12:15]
	v_mfma_f32_16x16x32_bf16 v[8:11], v[172:175], v[200:203], v[8:11]
	v_mfma_f32_16x16x32_bf16 v[4:7], v[184:187], v[192:195], v[4:7]
	v_mfma_f32_16x16x32_bf16 v[0:3], v[184:187], v[200:203], v[0:3]
	v_mfma_f32_16x16x32_bf16 v[28:31], v[160:163], v[196:199], v[28:31]
	v_mfma_f32_16x16x32_bf16 v[24:27], v[160:163], v[204:207], v[24:27]
	v_mfma_f32_16x16x32_bf16 v[20:23], v[168:171], v[196:199], v[20:23]
	v_mfma_f32_16x16x32_bf16 v[16:19], v[168:171], v[204:207], v[16:19]
	v_mfma_f32_16x16x32_bf16 v[12:15], v[180:183], v[196:199], v[12:15]
	v_mfma_f32_16x16x32_bf16 v[8:11], v[180:183], v[204:207], v[8:11]
	v_mfma_f32_16x16x32_bf16 v[4:7], v[188:191], v[196:199], v[4:7]
	v_mfma_f32_16x16x32_bf16 v[0:3], v[188:191], v[204:207], v[0:3]
	s_barrier
; #define STAGE(P, BASE, br, kt) do { const char* _g = (const char*)((BASE) + (size_t)(br) * K + (size_t)(kt) * G_BK); \
;     _Pragma("unroll") for (int _i = 0; _i < 2; ++_i) { \
;       __builtin_amdgcn_global_load_lds((const unsigned*)(_g + (size_t)_i * 128 * K + sg_off), (unsigned*)((char*)(P) + wid * 1024 + _i * 8192), 16, 0, 0); } } while (0)
; #define LDA(dst, b, h) _Pragma("unroll") for (int m = 0; m < 4; ++m) _Pragma("unroll") for (int k = 0; k < 2; ++k) \
;     dst[m][k] = *reinterpret_cast<const bf16x8*>((const char*)shm + aoff + (((b) * 2 + (h)) * 16384 + m * 2048 + k * 1024))
; #define LDB(dst, b, h) _Pragma("unroll") for (int n = 0; n < 2; ++n) _Pragma("unroll") for (int k = 0; k < 2; ++k) \
;     dst[n][k] = *reinterpret_cast<const bf16x8*>((const char*)shm + boff + (((b) * 2 + (h)) * 16384 + n * 2048 + k * 1024))
; #define WAIT_V(n) asm volatile("s_waitcnt vmcnt(" #n ")" ::: "memory")
; #define WAIT_L(n) asm volatile("s_waitcnt lgkmcnt(" #n ")" ::: "memory")
; #define BAR __builtin_amdgcn_s_barrier()
; #define SCHED __builtin_amdgcn_sched_barrier(0)
; template <class Epi>
; __device__ __forceinline__ void gemm_phase(const bfr* __restrict__ A, int lda, const bfr* __restrict__ Bt, int K,
;                                            int nM, int nN, const Epi& epi, bfr* shm, int wv, int nMfull, int ksplit) {
;     ...
;     for (int t = 0; t < nt - 2; t += 2) {
;       LDB(B0, 0, 0); SCHED; LDA(At, 0, 0); STAGE(SA(1, 1), Ak, brow + G_HALF, t + 1);
;       WAIT_L(8); BAR; WAIT_L(0); MMA(0, 0, At, B0); BAR; SCHED;
;       LDB(B1, 0, 1); STAGE(SB(0, 0), Bk, bcol, t + 2);
;       BAR; WAIT_L(0); MMA(0, 1, At, B1); BAR;
;       LDA(At, 0, 1); STAGE(SA(0, 0), Ak, brow, t + 2);
;       BAR; WAIT_L(0); MMA(1, 0, At, B0); BAR; SCHED;
;       STAGE(SB(0, 1), Bk, bcol + G_HALF, t + 2);
;       WAIT_V(6); BAR; MMA(1, 1, At, B1); BAR;
;       LDB(B0, 1, 0); SCHED; LDA(At, 1, 0); STAGE(SA(0, 1), Ak, brow + G_HALF, t + 2);
;       WAIT_L(8); BAR; WAIT_L(0); MMA(0, 0, At, B0); BAR; SCHED;
;       LDB(B1, 1, 1); STAGE(SB(1, 0), Bk, bcol, t + 3);
;       BAR; WAIT_L(0); MMA(0, 1, At, B1); BAR;
;       LDA(At, 1, 1); STAGE(SA(1, 0), Ak, brow, t + 3);
;       BAR; WAIT_L(0); MMA(1, 0, At, B0); BAR; SCHED;
;       STAGE(SB(1, 1), Bk, bcol + G_HALF, t + 3);
;       WAIT_V(6); BAR; MMA(1, 1, At, B1); BAR;
;     }
	ds_read_b128 v[140:143], v178 offset:32768
	ds_read_b128 v[144:147], v178 offset:33792
	ds_read_b128 v[148:151], v178 offset:34816
	ds_read_b128 v[152:155], v178 offset:35840
	ds_read_b128 v[156:159], v129 offset:32768
	ds_read_b128 v[160:163], v129 offset:33792
	ds_read_b128 v[164:167], v129 offset:34816
	ds_read_b128 v[168:171], v129 offset:35840
	ds_read_b128 v[172:175], v129 offset:36864
	ds_read_b128 v[180:183], v129 offset:37888
	ds_read_b128 v[184:187], v129 offset:38912
	ds_read_b128 v[188:191], v129 offset:39936
	ds_read_b128 v[192:195], v178 offset:49152
	ds_read_b128 v[196:199], v178 offset:50176
	ds_read_b128 v[200:203], v178 offset:51200
	ds_read_b128 v[204:207], v178 offset:52224
	s_mov_b32 m0, s94
	v_lshl_add_u64 v[216:217], v[176:177], 0, s[40:41]
	global_load_lds_dwordx4 v[216:217], off
	s_mov_b32 m0, s95
	v_lshl_add_u64 v[212:213], v[176:177], 0, s[42:43]
	global_load_lds_dwordx4 v[212:213], off
	s_waitcnt lgkmcnt(0)
	s_barrier
	v_mfma_f32_16x16x32_bf16 v[124:127], v[156:159], v[140:143], v[124:127]
	v_mfma_f32_16x16x32_bf16 v[120:123], v[156:159], v[148:151], v[120:123]
	v_mfma_f32_16x16x32_bf16 v[116:119], v[164:167], v[140:143], v[116:119]
	v_mfma_f32_16x16x32_bf16 v[112:115], v[164:167], v[148:151], v[112:115]
	v_mfma_f32_16x16x32_bf16 v[108:111], v[172:175], v[140:143], v[108:111]
	v_mfma_f32_16x16x32_bf16 v[104:107], v[172:175], v[148:151], v[104:107]
	v_mfma_f32_16x16x32_bf16 v[100:103], v[184:187], v[140:143], v[100:103]
	v_mfma_f32_16x16x32_bf16 v[96:99], v[184:187], v[148:151], v[96:99]
	v_mfma_f32_16x16x32_bf16 v[124:127], v[160:163], v[144:147], v[124:127]
	v_mfma_f32_16x16x32_bf16 v[120:123], v[160:163], v[152:155], v[120:123]
	v_mfma_f32_16x16x32_bf16 v[116:119], v[168:171], v[144:147], v[116:119]
	v_mfma_f32_16x16x32_bf16 v[112:115], v[168:171], v[152:155], v[112:115]
	v_mfma_f32_16x16x32_bf16 v[108:111], v[180:183], v[144:147], v[108:111]
	v_mfma_f32_16x16x32_bf16 v[104:107], v[180:183], v[152:155], v[104:107]
	v_mfma_f32_16x16x32_bf16 v[100:103], v[188:191], v[144:147], v[100:103]
	v_mfma_f32_16x16x32_bf16 v[96:99], v[188:191], v[152:155], v[96:99]
	v_mfma_f32_16x16x32_bf16 v[92:95], v[156:159], v[192:195], v[92:95]
	v_mfma_f32_16x16x32_bf16 v[88:91], v[156:159], v[200:203], v[88:91]
	v_mfma_f32_16x16x32_bf16 v[84:87], v[164:167], v[192:195], v[84:87]
	v_mfma_f32_16x16x32_bf16 v[80:83], v[164:167], v[200:203], v[80:83]
	v_mfma_f32_16x16x32_bf16 v[76:79], v[172:175], v[192:195], v[76:79]
	v_mfma_f32_16x16x32_bf16 v[72:75], v[172:175], v[200:203], v[72:75]
	v_mfma_f32_16x16x32_bf16 v[68:71], v[184:187], v[192:195], v[68:71]
	v_mfma_f32_16x16x32_bf16 v[64:67], v[184:187], v[200:203], v[64:67]
	v_mfma_f32_16x16x32_bf16 v[92:95], v[160:163], v[196:199], v[92:95]
	v_mfma_f32_16x16x32_bf16 v[88:91], v[160:163], v[204:207], v[88:91]
	v_mfma_f32_16x16x32_bf16 v[84:87], v[168:171], v[196:199], v[84:87]
	v_mfma_f32_16x16x32_bf16 v[80:83], v[168:171], v[204:207], v[80:83]
	v_mfma_f32_16x16x32_bf16 v[76:79], v[180:183], v[196:199], v[76:79]
	v_mfma_f32_16x16x32_bf16 v[72:75], v[180:183], v[204:207], v[72:75]
	v_mfma_f32_16x16x32_bf16 v[68:71], v[188:191], v[196:199], v[68:71]
	v_mfma_f32_16x16x32_bf16 v[64:67], v[188:191], v[204:207], v[64:67]
	s_barrier
	ds_read_b128 v[156:159], v129 offset:49152
	ds_read_b128 v[160:163], v129 offset:50176
	ds_read_b128 v[164:167], v129 offset:51200
	ds_read_b128 v[168:171], v129 offset:52224
	ds_read_b128 v[172:175], v129 offset:53248
	ds_read_b128 v[180:183], v129 offset:54272
	ds_read_b128 v[184:187], v129 offset:55296
	ds_read_b128 v[188:191], v129 offset:56320
	s_mov_b32 m0, s8
	v_lshl_add_u64 v[214:215], v[208:209], 0, s[46:47]
	global_load_lds_dwordx4 v[214:215], off
	s_mov_b32 m0, s9
	v_lshl_add_u64 v[216:217], v[208:209], 0, s[48:49]
	global_load_lds_dwordx4 v[216:217], off
	s_mov_b32 m0, s50
	v_lshl_add_u64 v[212:213], v[176:177], 0, s[46:47]
	global_load_lds_dwordx4 v[212:213], off
	s_mov_b32 m0, s51
	v_lshl_add_u64 v[214:215], v[176:177], 0, s[48:49]
	global_load_lds_dwordx4 v[214:215], off
	s_mov_b32 m0, s24
	s_mov_b64 s[54:55], 0xb0180
	v_lshl_add_u64 v[216:217], v[208:209], 0, s[54:55]
	global_load_lds_dwordx4 v[216:217], off
	s_mov_b32 m0, s25
	s_mov_b64 s[54:55], 0x108180
	v_lshl_add_u64 v[212:213], v[208:209], 0, s[54:55]
	global_load_lds_dwordx4 v[212:213], off
	s_waitcnt vmcnt(6)
	s_waitcnt lgkmcnt(0)
	s_barrier
	v_mfma_f32_16x16x32_bf16 v[60:63], v[156:159], v[140:143], v[60:63]
	v_mfma_f32_16x16x32_bf16 v[56:59], v[156:159], v[148:151], v[56:59]
	v_mfma_f32_16x16x32_bf16 v[52:55], v[164:167], v[140:143], v[52:55]
	v_mfma_f32_16x16x32_bf16 v[48:51], v[164:167], v[148:151], v[48:51]
	v_mfma_f32_16x16x32_bf16 v[44:47], v[172:175], v[140:143], v[44:47]
	v_mfma_f32_16x16x32_bf16 v[40:43], v[172:175], v[148:151], v[40:43]
	v_mfma_f32_16x16x32_bf16 v[36:39], v[184:187], v[140:143], v[36:39]
	v_mfma_f32_16x16x32_bf16 v[32:35], v[184:187], v[148:151], v[32:35]
	v_mfma_f32_16x16x32_bf16 v[60:63], v[160:163], v[144:147], v[60:63]
	v_mfma_f32_16x16x32_bf16 v[56:59], v[160:163], v[152:155], v[56:59]
	v_mfma_f32_16x16x32_bf16 v[52:55], v[168:171], v[144:147], v[52:55]
	v_mfma_f32_16x16x32_bf16 v[48:51], v[168:171], v[152:155], v[48:51]
	v_mfma_f32_16x16x32_bf16 v[44:47], v[180:183], v[144:147], v[44:47]
	v_mfma_f32_16x16x32_bf16 v[40:43], v[180:183], v[152:155], v[40:43]
	v_mfma_f32_16x16x32_bf16 v[36:39], v[188:191], v[144:147], v[36:39]
	v_mfma_f32_16x16x32_bf16 v[32:35], v[188:191], v[152:155], v[32:35]
	v_mfma_f32_16x16x32_bf16 v[28:31], v[156:159], v[192:195], v[28:31]
	v_mfma_f32_16x16x32_bf16 v[24:27], v[156:159], v[200:203], v[24:27]
	v_mfma_f32_16x16x32_bf16 v[20:23], v[164:167], v[192:195], v[20:23]
	v_mfma_f32_16x16x32_bf16 v[16:19], v[164:167], v[200:203], v[16:19]
	v_mfma_f32_16x16x32_bf16 v[12:15], v[172:175], v[192:195], v[12:15]
	v_mfma_f32_16x16x32_bf16 v[8:11], v[172:175], v[200:203], v[8:11]
	v_mfma_f32_16x16x32_bf16 v[4:7], v[184:187], v[192:195], v[4:7]
	v_mfma_f32_16x16x32_bf16 v[0:3], v[184:187], v[200:203], v[0:3]
	v_mfma_f32_16x16x32_bf16 v[28:31], v[160:163], v[196:199], v[28:31]
	v_mfma_f32_16x16x32_bf16 v[24:27], v[160:163], v[204:207], v[24:27]
	v_mfma_f32_16x16x32_bf16 v[20:23], v[168:171], v[196:199], v[20:23]
	v_mfma_f32_16x16x32_bf16 v[16:19], v[168:171], v[204:207], v[16:19]
	v_mfma_f32_16x16x32_bf16 v[12:15], v[180:183], v[196:199], v[12:15]
	v_mfma_f32_16x16x32_bf16 v[8:11], v[180:183], v[204:207], v[8:11]
	v_mfma_f32_16x16x32_bf16 v[4:7], v[188:191], v[196:199], v[4:7]
	v_mfma_f32_16x16x32_bf16 v[0:3], v[188:191], v[204:207], v[0:3]
	s_add_i32 s27, s27, 2
	s_add_u32 s38, s38, 0x100
	s_addc_u32 s39, s39, 0
	s_add_u32 s44, s44, 0x100
	s_addc_u32 s45, s45, 0
	s_cmp_ge_i32 s27, s6
	s_barrier
	s_cbranch_scc0 .LBB0_242

; #define STAGE(P, BASE, br, kt) do { const char* _g = (const char*)((BASE) + (size_t)(br) * K + (size_t)(kt) * G_BK); \
;     _Pragma("unroll") for (int _i = 0; _i < 2; ++_i) { \
;       __builtin_amdgcn_global_load_lds((const unsigned*)(_g + (size_t)_i * 128 * K + sg_off), (unsigned*)((char*)(P) + wid * 1024 + _i * 8192), 16, 0, 0); } } while (0)
; #define LDA(dst, b, h) _Pragma("unroll") for (int m = 0; m < 4; ++m) _Pragma("unroll") for (int k = 0; k < 2; ++k) \
;     dst[m][k] = *reinterpret_cast<const bf16x8*>((const char*)shm + aoff + (((b) * 2 + (h)) * 16384 + m * 2048 + k * 1024))
; #define LDB(dst, b, h) _Pragma("unroll") for (int n = 0; n < 2; ++n) _Pragma("unroll") for (int k = 0; k < 2; ++k) \
;     dst[n][k] = *reinterpret_cast<const bf16x8*>((const char*)shm + boff + (((b) * 2 + (h)) * 16384 + n * 2048 + k * 1024))
; #define WAIT_V(n) asm volatile("s_waitcnt vmcnt(" #n ")" ::: "memory")
; #define WAIT_L(n) asm volatile("s_waitcnt lgkmcnt(" #n ")" ::: "memory")
; #define BAR __builtin_amdgcn_s_barrier()
; #define SCHED __builtin_amdgcn_sched_barrier(0)
; template <class Epi>
; __device__ __forceinline__ void gemm_phase(const bfr* __restrict__ A, int lda, const bfr* __restrict__ Bt, int K,
;                                            int nM, int nN, const Epi& epi, bfr* shm, int wv, int nMfull, int ksplit) {
;     ...
;     for (int t = 0; t < nt - 2; t += 2) {
;       LDB(B0, 0, 0); SCHED; LDA(At, 0, 0); STAGE(SA(1, 1), Ak, brow + G_HALF, t + 1);
;       WAIT_L(8); BAR; WAIT_L(0); MMA(0, 0, At, B0); BAR; SCHED;
;       LDB(B1, 0, 1); STAGE(SB(0, 0), Bk, bcol, t + 2);
;       BAR; WAIT_L(0); MMA(0, 1, At, B1); BAR;
;       LDA(At, 0, 1); STAGE(SA(0, 0), Ak, brow, t + 2);
;       BAR; WAIT_L(0); MMA(1, 0, At, B0); BAR; SCHED;
;       STAGE(SB(0, 1), Bk, bcol + G_HALF, t + 2);
;       WAIT_V(6); BAR; MMA(1, 1, At, B1); BAR;
;       LDB(B0, 1, 0); SCHED; LDA(At, 1, 0); STAGE(SA(0, 1), Ak, brow + G_HALF, t + 2);
;       WAIT_L(8); BAR; WAIT_L(0); MMA(0, 0, At, B0); BAR; SCHED;
;       LDB(B1, 1, 1); STAGE(SB(1, 0), Bk, bcol, t + 3);
;       BAR; WAIT_L(0); MMA(0, 1, At, B1); BAR;
;       LDA(At, 1, 1); STAGE(SA(1, 0), Ak, brow, t + 3);
;       BAR; WAIT_L(0); MMA(1, 0, At, B0); BAR; SCHED;
;       STAGE(SB(1, 1), Bk, bcol + G_HALF, t + 3);
;       WAIT_V(6); BAR; MMA(1, 1, At, B1); BAR;
;     }
.LBB0_396:
	ds_read_b128 v[128:131], v181
	ds_read_b128 v[136:139], v181 offset:1024
	ds_read_b128 v[142:145], v181 offset:2048
	ds_read_b128 v[146:149], v181 offset:3072
	ds_read_b128 v[150:153], v179
	ds_read_b128 v[154:157], v179 offset:1024
	ds_read_b128 v[158:161], v179 offset:2048
	ds_read_b128 v[162:165], v179 offset:3072
	ds_read_b128 v[166:169], v179 offset:4096
	ds_read_b128 v[182:185], v179 offset:5120
	ds_read_b128 v[186:189], v179 offset:6144
	ds_read_b128 v[190:193], v179 offset:7168
	ds_read_b128 v[194:197], v181 offset:16384
	ds_read_b128 v[198:201], v181 offset:17408
	ds_read_b128 v[202:205], v181 offset:18432
	ds_read_b128 v[206:209], v181 offset:19456
	v_lshl_add_u64 v[132:133], s[4:5], 0, v[140:141]
	v_lshl_add_u64 v[170:171], s[2:3], 0, v[140:141]
	s_mov_b32 m0, s58
	s_mov_b64 s[12:13], 0x40080
	v_lshl_add_u64 v[210:211], v[132:133], 0, s[12:13]
	global_load_lds_dwordx4 v[210:211], off
	s_mov_b32 m0, s59
	s_mov_b64 s[12:13], 0x60080
	v_lshl_add_u64 v[212:213], v[132:133], 0, s[12:13]
	global_load_lds_dwordx4 v[212:213], off
	s_waitcnt lgkmcnt(0)
	s_barrier
	v_mfma_f32_16x16x32_bf16 v[124:127], v[150:153], v[128:131], v[124:127]
	v_mfma_f32_16x16x32_bf16 v[120:123], v[150:153], v[142:145], v[120:123]
	v_mfma_f32_16x16x32_bf16 v[116:119], v[158:161], v[128:131], v[116:119]
	v_mfma_f32_16x16x32_bf16 v[112:115], v[158:161], v[142:145], v[112:115]
	v_mfma_f32_16x16x32_bf16 v[108:111], v[166:169], v[128:131], v[108:111]
	v_mfma_f32_16x16x32_bf16 v[104:107], v[166:169], v[142:145], v[104:107]
	v_mfma_f32_16x16x32_bf16 v[100:103], v[186:189], v[128:131], v[100:103]
	v_mfma_f32_16x16x32_bf16 v[96:99], v[186:189], v[142:145], v[96:99]
	v_mfma_f32_16x16x32_bf16 v[124:127], v[154:157], v[136:139], v[124:127]
	v_mfma_f32_16x16x32_bf16 v[120:123], v[154:157], v[146:149], v[120:123]
	v_mfma_f32_16x16x32_bf16 v[116:119], v[162:165], v[136:139], v[116:119]
	v_mfma_f32_16x16x32_bf16 v[112:115], v[162:165], v[146:149], v[112:115]
	v_mfma_f32_16x16x32_bf16 v[108:111], v[182:185], v[136:139], v[108:111]
	v_mfma_f32_16x16x32_bf16 v[104:107], v[182:185], v[146:149], v[104:107]
	v_mfma_f32_16x16x32_bf16 v[100:103], v[190:193], v[136:139], v[100:103]
	v_mfma_f32_16x16x32_bf16 v[96:99], v[190:193], v[146:149], v[96:99]
	v_mfma_f32_16x16x32_bf16 v[92:95], v[150:153], v[194:197], v[92:95]
	v_mfma_f32_16x16x32_bf16 v[88:91], v[150:153], v[202:205], v[88:91]
	v_mfma_f32_16x16x32_bf16 v[84:87], v[158:161], v[194:197], v[84:87]
	v_mfma_f32_16x16x32_bf16 v[80:83], v[158:161], v[202:205], v[80:83]
	v_mfma_f32_16x16x32_bf16 v[76:79], v[166:169], v[194:197], v[76:79]
	v_mfma_f32_16x16x32_bf16 v[72:75], v[166:169], v[202:205], v[72:75]
	v_mfma_f32_16x16x32_bf16 v[68:71], v[186:189], v[194:197], v[68:71]
	v_mfma_f32_16x16x32_bf16 v[64:67], v[186:189], v[202:205], v[64:67]
	v_mfma_f32_16x16x32_bf16 v[92:95], v[154:157], v[198:201], v[92:95]
	v_mfma_f32_16x16x32_bf16 v[88:91], v[154:157], v[206:209], v[88:91]
	v_mfma_f32_16x16x32_bf16 v[84:87], v[162:165], v[198:201], v[84:87]
	v_mfma_f32_16x16x32_bf16 v[80:83], v[162:165], v[206:209], v[80:83]
	v_mfma_f32_16x16x32_bf16 v[76:79], v[182:185], v[198:201], v[76:79]
	v_mfma_f32_16x16x32_bf16 v[72:75], v[182:185], v[206:209], v[72:75]
	v_mfma_f32_16x16x32_bf16 v[68:71], v[190:193], v[198:201], v[68:71]
	v_mfma_f32_16x16x32_bf16 v[64:67], v[190:193], v[206:209], v[64:67]
	s_barrier
	ds_read_b128 v[150:153], v179 offset:16384
	ds_read_b128 v[154:157], v179 offset:17408
	ds_read_b128 v[158:161], v179 offset:18432
	ds_read_b128 v[162:165], v179 offset:19456
	ds_read_b128 v[166:169], v179 offset:20480
	ds_read_b128 v[182:185], v179 offset:21504
	ds_read_b128 v[186:189], v179 offset:22528
	ds_read_b128 v[190:193], v179 offset:23552
	s_mov_b32 m0, s97
	v_lshl_add_u64 v[214:215], v[170:171], 0, s[14:15]
	global_load_lds_dwordx4 v[214:215], off
	s_mov_b32 m0, s51
	v_lshl_add_u64 v[210:211], v[170:171], 0, s[16:17]
	global_load_lds_dwordx4 v[210:211], off
	s_mov_b32 m0, s56
	v_lshl_add_u64 v[212:213], v[132:133], 0, s[14:15]
	global_load_lds_dwordx4 v[212:213], off
	s_mov_b32 m0, s57
	v_lshl_add_u64 v[214:215], v[132:133], 0, s[16:17]
	global_load_lds_dwordx4 v[214:215], off
	s_mov_b32 m0, s33
	v_lshl_add_u64 v[210:211], v[170:171], 0, s[18:19]
	global_load_lds_dwordx4 v[210:211], off
	s_mov_b32 m0, s22
	v_lshl_add_u64 v[212:213], v[170:171], 0, s[20:21]
	global_load_lds_dwordx4 v[212:213], off
	s_waitcnt vmcnt(6)
	s_waitcnt lgkmcnt(0)
	s_barrier
	v_mfma_f32_16x16x32_bf16 v[60:63], v[150:153], v[128:131], v[60:63]
	v_mfma_f32_16x16x32_bf16 v[56:59], v[150:153], v[142:145], v[56:59]
	v_mfma_f32_16x16x32_bf16 v[52:55], v[158:161], v[128:131], v[52:55]
	v_mfma_f32_16x16x32_bf16 v[48:51], v[158:161], v[142:145], v[48:51]
	v_mfma_f32_16x16x32_bf16 v[44:47], v[166:169], v[128:131], v[44:47]
	v_mfma_f32_16x16x32_bf16 v[40:43], v[166:169], v[142:145], v[40:43]
	v_mfma_f32_16x16x32_bf16 v[36:39], v[186:189], v[128:131], v[36:39]
	v_mfma_f32_16x16x32_bf16 v[32:35], v[186:189], v[142:145], v[32:35]
	v_mfma_f32_16x16x32_bf16 v[60:63], v[154:157], v[136:139], v[60:63]
	v_mfma_f32_16x16x32_bf16 v[56:59], v[154:157], v[146:149], v[56:59]
	v_mfma_f32_16x16x32_bf16 v[52:55], v[162:165], v[136:139], v[52:55]
	v_mfma_f32_16x16x32_bf16 v[48:51], v[162:165], v[146:149], v[48:51]
	v_mfma_f32_16x16x32_bf16 v[44:47], v[182:185], v[136:139], v[44:47]
	v_mfma_f32_16x16x32_bf16 v[40:43], v[182:185], v[146:149], v[40:43]
	v_mfma_f32_16x16x32_bf16 v[36:39], v[190:193], v[136:139], v[36:39]
	v_mfma_f32_16x16x32_bf16 v[32:35], v[190:193], v[146:149], v[32:35]
	v_mfma_f32_16x16x32_bf16 v[28:31], v[150:153], v[194:197], v[28:31]
	v_mfma_f32_16x16x32_bf16 v[24:27], v[150:153], v[202:205], v[24:27]
	v_mfma_f32_16x16x32_bf16 v[20:23], v[158:161], v[194:197], v[20:23]
	v_mfma_f32_16x16x32_bf16 v[16:19], v[158:161], v[202:205], v[16:19]
	v_mfma_f32_16x16x32_bf16 v[12:15], v[166:169], v[194:197], v[12:15]
	v_mfma_f32_16x16x32_bf16 v[8:11], v[166:169], v[202:205], v[8:11]
	v_mfma_f32_16x16x32_bf16 v[4:7], v[186:189], v[194:197], v[4:7]
	v_mfma_f32_16x16x32_bf16 v[0:3], v[186:189], v[202:205], v[0:3]
	v_mfma_f32_16x16x32_bf16 v[28:31], v[154:157], v[198:201], v[28:31]
	v_mfma_f32_16x16x32_bf16 v[24:27], v[154:157], v[206:209], v[24:27]
	v_mfma_f32_16x16x32_bf16 v[20:23], v[162:165], v[198:201], v[20:23]
	v_mfma_f32_16x16x32_bf16 v[16:19], v[162:165], v[206:209], v[16:19]
	v_mfma_f32_16x16x32_bf16 v[12:15], v[182:185], v[198:201], v[12:15]
	v_mfma_f32_16x16x32_bf16 v[8:11], v[182:185], v[206:209], v[8:11]
	v_mfma_f32_16x16x32_bf16 v[4:7], v[190:193], v[198:201], v[4:7]
	v_mfma_f32_16x16x32_bf16 v[0:3], v[190:193], v[206:209], v[0:3]
	s_barrier
; #define STAGE(P, BASE, br, kt) do { const char* _g = (const char*)((BASE) + (size_t)(br) * K + (size_t)(kt) * G_BK); \
;     _Pragma("unroll") for (int _i = 0; _i < 2; ++_i) { \
;       __builtin_amdgcn_global_load_lds((const unsigned*)(_g + (size_t)_i * 128 * K + sg_off), (unsigned*)((char*)(P) + wid * 1024 + _i * 8192), 16, 0, 0); } } while (0)
; #define LDA(dst, b, h) _Pragma("unroll") for (int m = 0; m < 4; ++m) _Pragma("unroll") for (int k = 0; k < 2; ++k) \
;     dst[m][k] = *reinterpret_cast<const bf16x8*>((const char*)shm + aoff + (((b) * 2 + (h)) * 16384 + m * 2048 + k * 1024))
; #define LDB(dst, b, h) _Pragma("unroll") for (int n = 0; n < 2; ++n) _Pragma("unroll") for (int k = 0; k < 2; ++k) \
;     dst[n][k] = *reinterpret_cast<const bf16x8*>((const char*)shm + boff + (((b) * 2 + (h)) * 16384 + n * 2048 + k * 1024))
; #define WAIT_V(n) asm volatile("s_waitcnt vmcnt(" #n ")" ::: "memory")
; #define WAIT_L(n) asm volatile("s_waitcnt lgkmcnt(" #n ")" ::: "memory")
; #define BAR __builtin_amdgcn_s_barrier()
; #define SCHED __builtin_amdgcn_sched_barrier(0)
; template <class Epi>
; __device__ __forceinline__ void gemm_phase(const bfr* __restrict__ A, int lda, const bfr* __restrict__ Bt, int K,
;                                            int nM, int nN, const Epi& epi, bfr* shm, int wv, int nMfull, int ksplit) {
;     ...
;     for (int t = 0; t < nt - 2; t += 2) {
;       LDB(B0, 0, 0); SCHED; LDA(At, 0, 0); STAGE(SA(1, 1), Ak, brow + G_HALF, t + 1);
;       WAIT_L(8); BAR; WAIT_L(0); MMA(0, 0, At, B0); BAR; SCHED;
;       LDB(B1, 0, 1); STAGE(SB(0, 0), Bk, bcol, t + 2);
;       BAR; WAIT_L(0); MMA(0, 1, At, B1); BAR;
;       LDA(At, 0, 1); STAGE(SA(0, 0), Ak, brow, t + 2);
;       BAR; WAIT_L(0); MMA(1, 0, At, B0); BAR; SCHED;
;       STAGE(SB(0, 1), Bk, bcol + G_HALF, t + 2);
;       WAIT_V(6); BAR; MMA(1, 1, At, B1); BAR;
;       LDB(B0, 1, 0); SCHED; LDA(At, 1, 0); STAGE(SA(0, 1), Ak, brow + G_HALF, t + 2);
;       WAIT_L(8); BAR; WAIT_L(0); MMA(0, 0, At, B0); BAR; SCHED;
;       LDB(B1, 1, 1); STAGE(SB(1, 0), Bk, bcol, t + 3);
;       BAR; WAIT_L(0); MMA(0, 1, At, B1); BAR;
;       LDA(At, 1, 1); STAGE(SA(1, 0), Ak, brow, t + 3);
;       BAR; WAIT_L(0); MMA(1, 0, At, B0); BAR; SCHED;
;       STAGE(SB(1, 1), Bk, bcol + G_HALF, t + 3);
;       WAIT_V(6); BAR; MMA(1, 1, At, B1); BAR;
;     }
	ds_read_b128 v[128:131], v181 offset:32768
	ds_read_b128 v[136:139], v181 offset:33792
	ds_read_b128 v[142:145], v181 offset:34816
	ds_read_b128 v[146:149], v181 offset:35840
	ds_read_b128 v[150:153], v179 offset:32768
	ds_read_b128 v[154:157], v179 offset:33792
	ds_read_b128 v[158:161], v179 offset:34816
	ds_read_b128 v[162:165], v179 offset:35840
	ds_read_b128 v[166:169], v179 offset:36864
	ds_read_b128 v[182:185], v179 offset:37888
	ds_read_b128 v[186:189], v179 offset:38912
	ds_read_b128 v[190:193], v179 offset:39936
	ds_read_b128 v[194:197], v181 offset:49152
	ds_read_b128 v[198:201], v181 offset:50176
	ds_read_b128 v[202:205], v181 offset:51200
	ds_read_b128 v[206:209], v181 offset:52224
	s_mov_b32 m0, s23
	v_lshl_add_u64 v[214:215], v[132:133], 0, s[18:19]
	global_load_lds_dwordx4 v[214:215], off
	s_mov_b32 m0, s24
	v_lshl_add_u64 v[210:211], v[132:133], 0, s[20:21]
	global_load_lds_dwordx4 v[210:211], off
	s_waitcnt lgkmcnt(0)
	s_barrier
	v_mfma_f32_16x16x32_bf16 v[124:127], v[150:153], v[128:131], v[124:127]
	v_mfma_f32_16x16x32_bf16 v[120:123], v[150:153], v[142:145], v[120:123]
	v_mfma_f32_16x16x32_bf16 v[116:119], v[158:161], v[128:131], v[116:119]
	v_mfma_f32_16x16x32_bf16 v[112:115], v[158:161], v[142:145], v[112:115]
	v_mfma_f32_16x16x32_bf16 v[108:111], v[166:169], v[128:131], v[108:111]
	v_mfma_f32_16x16x32_bf16 v[104:107], v[166:169], v[142:145], v[104:107]
	v_mfma_f32_16x16x32_bf16 v[100:103], v[186:189], v[128:131], v[100:103]
	v_mfma_f32_16x16x32_bf16 v[96:99], v[186:189], v[142:145], v[96:99]
	v_mfma_f32_16x16x32_bf16 v[124:127], v[154:157], v[136:139], v[124:127]
	v_mfma_f32_16x16x32_bf16 v[120:123], v[154:157], v[146:149], v[120:123]
	v_mfma_f32_16x16x32_bf16 v[116:119], v[162:165], v[136:139], v[116:119]
	v_mfma_f32_16x16x32_bf16 v[112:115], v[162:165], v[146:149], v[112:115]
	v_mfma_f32_16x16x32_bf16 v[108:111], v[182:185], v[136:139], v[108:111]
	v_mfma_f32_16x16x32_bf16 v[104:107], v[182:185], v[146:149], v[104:107]
	v_mfma_f32_16x16x32_bf16 v[100:103], v[190:193], v[136:139], v[100:103]
	v_mfma_f32_16x16x32_bf16 v[96:99], v[190:193], v[146:149], v[96:99]
	v_mfma_f32_16x16x32_bf16 v[92:95], v[150:153], v[194:197], v[92:95]
	v_mfma_f32_16x16x32_bf16 v[88:91], v[150:153], v[202:205], v[88:91]
	v_mfma_f32_16x16x32_bf16 v[84:87], v[158:161], v[194:197], v[84:87]
	v_mfma_f32_16x16x32_bf16 v[80:83], v[158:161], v[202:205], v[80:83]
	v_mfma_f32_16x16x32_bf16 v[76:79], v[166:169], v[194:197], v[76:79]
	v_mfma_f32_16x16x32_bf16 v[72:75], v[166:169], v[202:205], v[72:75]
	v_mfma_f32_16x16x32_bf16 v[68:71], v[186:189], v[194:197], v[68:71]
	v_mfma_f32_16x16x32_bf16 v[64:67], v[186:189], v[202:205], v[64:67]
	v_mfma_f32_16x16x32_bf16 v[92:95], v[154:157], v[198:201], v[92:95]
	v_mfma_f32_16x16x32_bf16 v[88:91], v[154:157], v[206:209], v[88:91]
	v_mfma_f32_16x16x32_bf16 v[84:87], v[162:165], v[198:201], v[84:87]
	v_mfma_f32_16x16x32_bf16 v[80:83], v[162:165], v[206:209], v[80:83]
	v_mfma_f32_16x16x32_bf16 v[76:79], v[182:185], v[198:201], v[76:79]
	v_mfma_f32_16x16x32_bf16 v[72:75], v[182:185], v[206:209], v[72:75]
	v_mfma_f32_16x16x32_bf16 v[68:71], v[190:193], v[198:201], v[68:71]
	v_mfma_f32_16x16x32_bf16 v[64:67], v[190:193], v[206:209], v[64:67]
	s_barrier
	ds_read_b128 v[150:153], v179 offset:49152
	ds_read_b128 v[154:157], v179 offset:50176
	ds_read_b128 v[158:161], v179 offset:51200
	ds_read_b128 v[162:165], v179 offset:52224
	ds_read_b128 v[166:169], v179 offset:53248
	ds_read_b128 v[182:185], v179 offset:54272
	ds_read_b128 v[186:189], v179 offset:55296
	ds_read_b128 v[190:193], v179 offset:56320
	s_mov_b32 m0, s25
	v_lshl_add_u64 v[212:213], v[170:171], 0, s[30:31]
	global_load_lds_dwordx4 v[212:213], off
	s_mov_b32 m0, s26
	v_lshl_add_u64 v[214:215], v[170:171], 0, s[40:41]
	global_load_lds_dwordx4 v[214:215], off
	s_mov_b32 m0, s27
	v_lshl_add_u64 v[210:211], v[132:133], 0, s[30:31]
	global_load_lds_dwordx4 v[210:211], off
	s_mov_b32 m0, s28
	v_lshl_add_u64 v[212:213], v[132:133], 0, s[40:41]
	global_load_lds_dwordx4 v[212:213], off
	s_mov_b32 m0, s29
	s_mov_b64 s[12:13], 0x40180
	v_lshl_add_u64 v[214:215], v[170:171], 0, s[12:13]
	global_load_lds_dwordx4 v[214:215], off
	s_mov_b32 m0, s9
	s_mov_b64 s[12:13], 0x60180
	v_lshl_add_u64 v[210:211], v[170:171], 0, s[12:13]
	global_load_lds_dwordx4 v[210:211], off
	s_waitcnt vmcnt(6)
	s_waitcnt lgkmcnt(0)
	s_barrier
	v_mfma_f32_16x16x32_bf16 v[60:63], v[150:153], v[128:131], v[60:63]
	v_mfma_f32_16x16x32_bf16 v[56:59], v[150:153], v[142:145], v[56:59]
	v_mfma_f32_16x16x32_bf16 v[52:55], v[158:161], v[128:131], v[52:55]
	v_mfma_f32_16x16x32_bf16 v[48:51], v[158:161], v[142:145], v[48:51]
	v_mfma_f32_16x16x32_bf16 v[44:47], v[166:169], v[128:131], v[44:47]
	v_mfma_f32_16x16x32_bf16 v[40:43], v[166:169], v[142:145], v[40:43]
	v_mfma_f32_16x16x32_bf16 v[36:39], v[186:189], v[128:131], v[36:39]
	v_mfma_f32_16x16x32_bf16 v[32:35], v[186:189], v[142:145], v[32:35]
	v_mfma_f32_16x16x32_bf16 v[60:63], v[154:157], v[136:139], v[60:63]
	v_mfma_f32_16x16x32_bf16 v[56:59], v[154:157], v[146:149], v[56:59]
	v_mfma_f32_16x16x32_bf16 v[52:55], v[162:165], v[136:139], v[52:55]
	v_mfma_f32_16x16x32_bf16 v[48:51], v[162:165], v[146:149], v[48:51]
	v_mfma_f32_16x16x32_bf16 v[44:47], v[182:185], v[136:139], v[44:47]
	v_mfma_f32_16x16x32_bf16 v[40:43], v[182:185], v[146:149], v[40:43]
	v_mfma_f32_16x16x32_bf16 v[36:39], v[190:193], v[136:139], v[36:39]
	v_mfma_f32_16x16x32_bf16 v[32:35], v[190:193], v[146:149], v[32:35]
	v_mfma_f32_16x16x32_bf16 v[28:31], v[150:153], v[194:197], v[28:31]
	v_mfma_f32_16x16x32_bf16 v[24:27], v[150:153], v[202:205], v[24:27]
	v_mfma_f32_16x16x32_bf16 v[20:23], v[158:161], v[194:197], v[20:23]
	v_mfma_f32_16x16x32_bf16 v[16:19], v[158:161], v[202:205], v[16:19]
	v_mfma_f32_16x16x32_bf16 v[12:15], v[166:169], v[194:197], v[12:15]
	v_mfma_f32_16x16x32_bf16 v[8:11], v[166:169], v[202:205], v[8:11]
	v_mfma_f32_16x16x32_bf16 v[4:7], v[186:189], v[194:197], v[4:7]
	v_mfma_f32_16x16x32_bf16 v[0:3], v[186:189], v[202:205], v[0:3]
	v_mfma_f32_16x16x32_bf16 v[28:31], v[154:157], v[198:201], v[28:31]
	v_mfma_f32_16x16x32_bf16 v[24:27], v[154:157], v[206:209], v[24:27]
	v_mfma_f32_16x16x32_bf16 v[20:23], v[162:165], v[198:201], v[20:23]
	v_mfma_f32_16x16x32_bf16 v[16:19], v[162:165], v[206:209], v[16:19]
	v_mfma_f32_16x16x32_bf16 v[12:15], v[182:185], v[198:201], v[12:15]
	v_mfma_f32_16x16x32_bf16 v[8:11], v[182:185], v[206:209], v[8:11]
	v_mfma_f32_16x16x32_bf16 v[4:7], v[190:193], v[198:201], v[4:7]
	v_mfma_f32_16x16x32_bf16 v[0:3], v[190:193], v[206:209], v[0:3]
	s_add_i32 s6, s6, 2
	s_add_u32 s2, s2, 0x100
	s_addc_u32 s3, s3, 0
	s_add_u32 s4, s4, 0x100
	s_addc_u32 s5, s5, 0
	s_cmp_ge_i32 s6, s1
	s_barrier
	s_cbranch_scc0 .LBB0_396
	v_readlane_b32 s60, v255, 41

; #define STAGE(P, BASE, br, kt) do { const char* _g = (const char*)((BASE) + (size_t)(br) * K + (size_t)(kt) * G_BK); \
;     _Pragma("unroll") for (int _i = 0; _i < 2; ++_i) { \
;       __builtin_amdgcn_global_load_lds((const unsigned*)(_g + (size_t)_i * 128 * K + sg_off), (unsigned*)((char*)(P) + wid * 1024 + _i * 8192), 16, 0, 0); } } while (0)
; #define LDA(dst, b, h) _Pragma("unroll") for (int m = 0; m < 4; ++m) _Pragma("unroll") for (int k = 0; k < 2; ++k) \
;     dst[m][k] = *reinterpret_cast<const bf16x8*>((const char*)shm + aoff + (((b) * 2 + (h)) * 16384 + m * 2048 + k * 1024))
; #define LDB(dst, b, h) _Pragma("unroll") for (int n = 0; n < 2; ++n) _Pragma("unroll") for (int k = 0; k < 2; ++k) \
;     dst[n][k] = *reinterpret_cast<const bf16x8*>((const char*)shm + boff + (((b) * 2 + (h)) * 16384 + n * 2048 + k * 1024))
; #define WAIT_V(n) asm volatile("s_waitcnt vmcnt(" #n ")" ::: "memory")
; #define WAIT_L(n) asm volatile("s_waitcnt lgkmcnt(" #n ")" ::: "memory")
; #define BAR __builtin_amdgcn_s_barrier()
; #define SCHED __builtin_amdgcn_sched_barrier(0)
; template <class Epi>
; __device__ __forceinline__ void gemm_phase(const bfr* __restrict__ A, int lda, const bfr* __restrict__ Bt, int K,
;                                            int nM, int nN, const Epi& epi, bfr* shm, int wv, int nMfull, int ksplit) {
;     ...
;     for (int t = 0; t < nt - 2; t += 2) {
;       LDB(B0, 0, 0); SCHED; LDA(At, 0, 0); STAGE(SA(1, 1), Ak, brow + G_HALF, t + 1);
;       WAIT_L(8); BAR; WAIT_L(0); MMA(0, 0, At, B0); BAR; SCHED;
;       LDB(B1, 0, 1); STAGE(SB(0, 0), Bk, bcol, t + 2);
;       BAR; WAIT_L(0); MMA(0, 1, At, B1); BAR;
;       LDA(At, 0, 1); STAGE(SA(0, 0), Ak, brow, t + 2);
;       BAR; WAIT_L(0); MMA(1, 0, At, B0); BAR; SCHED;
;       STAGE(SB(0, 1), Bk, bcol + G_HALF, t + 2);
;       WAIT_V(6); BAR; MMA(1, 1, At, B1); BAR;
;       LDB(B0, 1, 0); SCHED; LDA(At, 1, 0); STAGE(SA(0, 1), Ak, brow + G_HALF, t + 2);
;       WAIT_L(8); BAR; WAIT_L(0); MMA(0, 0, At, B0); BAR; SCHED;
;       LDB(B1, 1, 1); STAGE(SB(1, 0), Bk, bcol, t + 3);
;       BAR; WAIT_L(0); MMA(0, 1, At, B1); BAR;
;       LDA(At, 1, 1); STAGE(SA(1, 0), Ak, brow, t + 3);
;       BAR; WAIT_L(0); MMA(1, 0, At, B0); BAR; SCHED;
;       STAGE(SB(1, 1), Bk, bcol + G_HALF, t + 3);
;       WAIT_V(6); BAR; MMA(1, 1, At, B1); BAR;
;     }
.LBB0_523:
	ds_read_b128 v[138:141], v179
	ds_read_b128 v[142:145], v179 offset:1024
	ds_read_b128 v[146:149], v179 offset:2048
	ds_read_b128 v[150:153], v179 offset:3072
	ds_read_b128 v[154:157], v178
	ds_read_b128 v[158:161], v178 offset:1024
	ds_read_b128 v[162:165], v178 offset:2048
	ds_read_b128 v[166:169], v178 offset:3072
	ds_read_b128 v[170:173], v178 offset:4096
	ds_read_b128 v[174:177], v178 offset:5120
	ds_read_b128 v[184:187], v178 offset:6144
	ds_read_b128 v[188:191], v178 offset:7168
	ds_read_b128 v[192:195], v179 offset:16384
	ds_read_b128 v[196:199], v179 offset:17408
	ds_read_b128 v[200:203], v179 offset:18432
	ds_read_b128 v[204:207], v179 offset:19456
	v_lshl_add_u64 v[208:209], s[44:45], 0, v[136:137]
	v_lshl_add_u64 v[210:211], s[42:43], 0, v[136:137]
	s_mov_b32 m0, s92
	s_mov_b64 s[52:53], 0x40080
	v_lshl_add_u64 v[214:215], v[208:209], 0, s[52:53]
	global_load_lds_dwordx4 v[214:215], off
	s_mov_b32 m0, s93
	s_mov_b64 s[52:53], 0x60080
	v_lshl_add_u64 v[216:217], v[208:209], 0, s[52:53]
	global_load_lds_dwordx4 v[216:217], off
	s_waitcnt lgkmcnt(0)
	s_barrier
	v_mfma_f32_16x16x32_bf16 v[124:127], v[154:157], v[138:141], v[124:127]
	v_mfma_f32_16x16x32_bf16 v[120:123], v[154:157], v[146:149], v[120:123]
	v_mfma_f32_16x16x32_bf16 v[116:119], v[162:165], v[138:141], v[116:119]
	v_mfma_f32_16x16x32_bf16 v[112:115], v[162:165], v[146:149], v[112:115]
	v_mfma_f32_16x16x32_bf16 v[108:111], v[170:173], v[138:141], v[108:111]
	v_mfma_f32_16x16x32_bf16 v[104:107], v[170:173], v[146:149], v[104:107]
	v_mfma_f32_16x16x32_bf16 v[100:103], v[184:187], v[138:141], v[100:103]
	v_mfma_f32_16x16x32_bf16 v[96:99], v[184:187], v[146:149], v[96:99]
	v_mfma_f32_16x16x32_bf16 v[124:127], v[158:161], v[142:145], v[124:127]
	v_mfma_f32_16x16x32_bf16 v[120:123], v[158:161], v[150:153], v[120:123]
	v_mfma_f32_16x16x32_bf16 v[116:119], v[166:169], v[142:145], v[116:119]
	v_mfma_f32_16x16x32_bf16 v[112:115], v[166:169], v[150:153], v[112:115]
	v_mfma_f32_16x16x32_bf16 v[108:111], v[174:177], v[142:145], v[108:111]
	v_mfma_f32_16x16x32_bf16 v[104:107], v[174:177], v[150:153], v[104:107]
	v_mfma_f32_16x16x32_bf16 v[100:103], v[188:191], v[142:145], v[100:103]
	v_mfma_f32_16x16x32_bf16 v[96:99], v[188:191], v[150:153], v[96:99]
	v_mfma_f32_16x16x32_bf16 v[92:95], v[154:157], v[192:195], v[92:95]
	v_mfma_f32_16x16x32_bf16 v[88:91], v[154:157], v[200:203], v[88:91]
	v_mfma_f32_16x16x32_bf16 v[84:87], v[162:165], v[192:195], v[84:87]
	v_mfma_f32_16x16x32_bf16 v[80:83], v[162:165], v[200:203], v[80:83]
	v_mfma_f32_16x16x32_bf16 v[76:79], v[170:173], v[192:195], v[76:79]
	v_mfma_f32_16x16x32_bf16 v[72:75], v[170:173], v[200:203], v[72:75]
	v_mfma_f32_16x16x32_bf16 v[68:71], v[184:187], v[192:195], v[68:71]
	v_mfma_f32_16x16x32_bf16 v[64:67], v[184:187], v[200:203], v[64:67]
	v_mfma_f32_16x16x32_bf16 v[92:95], v[158:161], v[196:199], v[92:95]
	v_mfma_f32_16x16x32_bf16 v[88:91], v[158:161], v[204:207], v[88:91]
	v_mfma_f32_16x16x32_bf16 v[84:87], v[166:169], v[196:199], v[84:87]
	v_mfma_f32_16x16x32_bf16 v[80:83], v[166:169], v[204:207], v[80:83]
	v_mfma_f32_16x16x32_bf16 v[76:79], v[174:177], v[196:199], v[76:79]
	v_mfma_f32_16x16x32_bf16 v[72:75], v[174:177], v[204:207], v[72:75]
	v_mfma_f32_16x16x32_bf16 v[68:71], v[188:191], v[196:199], v[68:71]
	v_mfma_f32_16x16x32_bf16 v[64:67], v[188:191], v[204:207], v[64:67]
	s_barrier
	ds_read_b128 v[154:157], v178 offset:16384
	ds_read_b128 v[158:161], v178 offset:17408
	ds_read_b128 v[162:165], v178 offset:18432
	ds_read_b128 v[166:169], v178 offset:19456
	ds_read_b128 v[170:173], v178 offset:20480
	ds_read_b128 v[174:177], v178 offset:21504
	ds_read_b128 v[184:187], v178 offset:22528
	ds_read_b128 v[188:191], v178 offset:23552
	s_mov_b32 m0, s94
	v_lshl_add_u64 v[218:219], v[210:211], 0, s[16:17]
	global_load_lds_dwordx4 v[218:219], off
	s_mov_b32 m0, s95
	v_lshl_add_u64 v[214:215], v[210:211], 0, s[18:19]
	global_load_lds_dwordx4 v[214:215], off
	s_mov_b32 m0, s91
	v_lshl_add_u64 v[216:217], v[208:209], 0, s[16:17]
	global_load_lds_dwordx4 v[216:217], off
	s_mov_b32 m0, s96
	v_lshl_add_u64 v[218:219], v[208:209], 0, s[18:19]
	global_load_lds_dwordx4 v[218:219], off
	s_mov_b32 m0, s97
	v_lshl_add_u64 v[214:215], v[210:211], 0, s[20:21]
	global_load_lds_dwordx4 v[214:215], off
	s_mov_b32 m0, s34
	v_lshl_add_u64 v[216:217], v[210:211], 0, s[22:23]
	global_load_lds_dwordx4 v[216:217], off
	s_waitcnt vmcnt(6)
	s_waitcnt lgkmcnt(0)
	s_barrier
	v_mfma_f32_16x16x32_bf16 v[60:63], v[154:157], v[138:141], v[60:63]
	v_mfma_f32_16x16x32_bf16 v[56:59], v[154:157], v[146:149], v[56:59]
	v_mfma_f32_16x16x32_bf16 v[52:55], v[162:165], v[138:141], v[52:55]
	v_mfma_f32_16x16x32_bf16 v[48:51], v[162:165], v[146:149], v[48:51]
	v_mfma_f32_16x16x32_bf16 v[44:47], v[170:173], v[138:141], v[44:47]
	v_mfma_f32_16x16x32_bf16 v[40:43], v[170:173], v[146:149], v[40:43]
	v_mfma_f32_16x16x32_bf16 v[36:39], v[184:187], v[138:141], v[36:39]
	v_mfma_f32_16x16x32_bf16 v[32:35], v[184:187], v[146:149], v[32:35]
	v_mfma_f32_16x16x32_bf16 v[60:63], v[158:161], v[142:145], v[60:63]
	v_mfma_f32_16x16x32_bf16 v[56:59], v[158:161], v[150:153], v[56:59]
	v_mfma_f32_16x16x32_bf16 v[52:55], v[166:169], v[142:145], v[52:55]
	v_mfma_f32_16x16x32_bf16 v[48:51], v[166:169], v[150:153], v[48:51]
	v_mfma_f32_16x16x32_bf16 v[44:47], v[174:177], v[142:145], v[44:47]
	v_mfma_f32_16x16x32_bf16 v[40:43], v[174:177], v[150:153], v[40:43]
	v_mfma_f32_16x16x32_bf16 v[36:39], v[188:191], v[142:145], v[36:39]
	v_mfma_f32_16x16x32_bf16 v[32:35], v[188:191], v[150:153], v[32:35]
	v_mfma_f32_16x16x32_bf16 v[28:31], v[154:157], v[192:195], v[28:31]
	v_mfma_f32_16x16x32_bf16 v[24:27], v[154:157], v[200:203], v[24:27]
	v_mfma_f32_16x16x32_bf16 v[20:23], v[162:165], v[192:195], v[20:23]
	v_mfma_f32_16x16x32_bf16 v[16:19], v[162:165], v[200:203], v[16:19]
	v_mfma_f32_16x16x32_bf16 v[12:15], v[170:173], v[192:195], v[12:15]
	v_mfma_f32_16x16x32_bf16 v[8:11], v[170:173], v[200:203], v[8:11]
	v_mfma_f32_16x16x32_bf16 v[4:7], v[184:187], v[192:195], v[4:7]
	v_mfma_f32_16x16x32_bf16 v[0:3], v[184:187], v[200:203], v[0:3]
	v_mfma_f32_16x16x32_bf16 v[28:31], v[158:161], v[196:199], v[28:31]
	v_mfma_f32_16x16x32_bf16 v[24:27], v[158:161], v[204:207], v[24:27]
	v_mfma_f32_16x16x32_bf16 v[20:23], v[166:169], v[196:199], v[20:23]
	v_mfma_f32_16x16x32_bf16 v[16:19], v[166:169], v[204:207], v[16:19]
	v_mfma_f32_16x16x32_bf16 v[12:15], v[174:177], v[196:199], v[12:15]
	v_mfma_f32_16x16x32_bf16 v[8:11], v[174:177], v[204:207], v[8:11]
	v_mfma_f32_16x16x32_bf16 v[4:7], v[188:191], v[196:199], v[4:7]
	v_mfma_f32_16x16x32_bf16 v[0:3], v[188:191], v[204:207], v[0:3]
	s_barrier
; #define STAGE(P, BASE, br, kt) do { const char* _g = (const char*)((BASE) + (size_t)(br) * K + (size_t)(kt) * G_BK); \
;     _Pragma("unroll") for (int _i = 0; _i < 2; ++_i) { \
;       __builtin_amdgcn_global_load_lds((const unsigned*)(_g + (size_t)_i * 128 * K + sg_off), (unsigned*)((char*)(P) + wid * 1024 + _i * 8192), 16, 0, 0); } } while (0)
; #define LDA(dst, b, h) _Pragma("unroll") for (int m = 0; m < 4; ++m) _Pragma("unroll") for (int k = 0; k < 2; ++k) \
;     dst[m][k] = *reinterpret_cast<const bf16x8*>((const char*)shm + aoff + (((b) * 2 + (h)) * 16384 + m * 2048 + k * 1024))
; #define LDB(dst, b, h) _Pragma("unroll") for (int n = 0; n < 2; ++n) _Pragma("unroll") for (int k = 0; k < 2; ++k) \
;     dst[n][k] = *reinterpret_cast<const bf16x8*>((const char*)shm + boff + (((b) * 2 + (h)) * 16384 + n * 2048 + k * 1024))
; #define WAIT_V(n) asm volatile("s_waitcnt vmcnt(" #n ")" ::: "memory")
; #define WAIT_L(n) asm volatile("s_waitcnt lgkmcnt(" #n ")" ::: "memory")
; #define BAR __builtin_amdgcn_s_barrier()
; #define SCHED __builtin_amdgcn_sched_barrier(0)
; template <class Epi>
; __device__ __forceinline__ void gemm_phase(const bfr* __restrict__ A, int lda, const bfr* __restrict__ Bt, int K,
;                                            int nM, int nN, const Epi& epi, bfr* shm, int wv, int nMfull, int ksplit) {
;     ...
;     for (int t = 0; t < nt - 2; t += 2) {
;       LDB(B0, 0, 0); SCHED; LDA(At, 0, 0); STAGE(SA(1, 1), Ak, brow + G_HALF, t + 1);
;       WAIT_L(8); BAR; WAIT_L(0); MMA(0, 0, At, B0); BAR; SCHED;
;       LDB(B1, 0, 1); STAGE(SB(0, 0), Bk, bcol, t + 2);
;       BAR; WAIT_L(0); MMA(0, 1, At, B1); BAR;
;       LDA(At, 0, 1); STAGE(SA(0, 0), Ak, brow, t + 2);
;       BAR; WAIT_L(0); MMA(1, 0, At, B0); BAR; SCHED;
;       STAGE(SB(0, 1), Bk, bcol + G_HALF, t + 2);
;       WAIT_V(6); BAR; MMA(1, 1, At, B1); BAR;
;       LDB(B0, 1, 0); SCHED; LDA(At, 1, 0); STAGE(SA(0, 1), Ak, brow + G_HALF, t + 2);
;       WAIT_L(8); BAR; WAIT_L(0); MMA(0, 0, At, B0); BAR; SCHED;
;       LDB(B1, 1, 1); STAGE(SB(1, 0), Bk, bcol, t + 3);
;       BAR; WAIT_L(0); MMA(0, 1, At, B1); BAR;
;       LDA(At, 1, 1); STAGE(SA(1, 0), Ak, brow, t + 3);
;       BAR; WAIT_L(0); MMA(1, 0, At, B0); BAR; SCHED;
;       STAGE(SB(1, 1), Bk, bcol + G_HALF, t + 3);
;       WAIT_V(6); BAR; MMA(1, 1, At, B1); BAR;
;     }
	ds_read_b128 v[138:141], v179 offset:32768
	ds_read_b128 v[142:145], v179 offset:33792
	ds_read_b128 v[146:149], v179 offset:34816
	ds_read_b128 v[150:153], v179 offset:35840
	ds_read_b128 v[154:157], v178 offset:32768
	ds_read_b128 v[158:161], v178 offset:33792
	ds_read_b128 v[162:165], v178 offset:34816
	ds_read_b128 v[166:169], v178 offset:35840
	ds_read_b128 v[170:173], v178 offset:36864
	ds_read_b128 v[174:177], v178 offset:37888
	ds_read_b128 v[184:187], v178 offset:38912
	ds_read_b128 v[188:191], v178 offset:39936
	ds_read_b128 v[192:195], v179 offset:49152
	ds_read_b128 v[196:199], v179 offset:50176
	ds_read_b128 v[200:203], v179 offset:51200
	ds_read_b128 v[204:207], v179 offset:52224
	s_mov_b32 m0, s35
	v_lshl_add_u64 v[218:219], v[208:209], 0, s[20:21]
	global_load_lds_dwordx4 v[218:219], off
	s_mov_b32 m0, s36
	v_lshl_add_u64 v[214:215], v[208:209], 0, s[22:23]
	global_load_lds_dwordx4 v[214:215], off
	s_waitcnt lgkmcnt(0)
	s_barrier
	v_mfma_f32_16x16x32_bf16 v[124:127], v[154:157], v[138:141], v[124:127]
	v_mfma_f32_16x16x32_bf16 v[120:123], v[154:157], v[146:149], v[120:123]
	v_mfma_f32_16x16x32_bf16 v[116:119], v[162:165], v[138:141], v[116:119]
	v_mfma_f32_16x16x32_bf16 v[112:115], v[162:165], v[146:149], v[112:115]
	v_mfma_f32_16x16x32_bf16 v[108:111], v[170:173], v[138:141], v[108:111]
	v_mfma_f32_16x16x32_bf16 v[104:107], v[170:173], v[146:149], v[104:107]
	v_mfma_f32_16x16x32_bf16 v[100:103], v[184:187], v[138:141], v[100:103]
	v_mfma_f32_16x16x32_bf16 v[96:99], v[184:187], v[146:149], v[96:99]
	v_mfma_f32_16x16x32_bf16 v[124:127], v[158:161], v[142:145], v[124:127]
	v_mfma_f32_16x16x32_bf16 v[120:123], v[158:161], v[150:153], v[120:123]
	v_mfma_f32_16x16x32_bf16 v[116:119], v[166:169], v[142:145], v[116:119]
	v_mfma_f32_16x16x32_bf16 v[112:115], v[166:169], v[150:153], v[112:115]
	v_mfma_f32_16x16x32_bf16 v[108:111], v[174:177], v[142:145], v[108:111]
	v_mfma_f32_16x16x32_bf16 v[104:107], v[174:177], v[150:153], v[104:107]
	v_mfma_f32_16x16x32_bf16 v[100:103], v[188:191], v[142:145], v[100:103]
	v_mfma_f32_16x16x32_bf16 v[96:99], v[188:191], v[150:153], v[96:99]
	v_mfma_f32_16x16x32_bf16 v[92:95], v[154:157], v[192:195], v[92:95]
	v_mfma_f32_16x16x32_bf16 v[88:91], v[154:157], v[200:203], v[88:91]
	v_mfma_f32_16x16x32_bf16 v[84:87], v[162:165], v[192:195], v[84:87]
	v_mfma_f32_16x16x32_bf16 v[80:83], v[162:165], v[200:203], v[80:83]
	v_mfma_f32_16x16x32_bf16 v[76:79], v[170:173], v[192:195], v[76:79]
	v_mfma_f32_16x16x32_bf16 v[72:75], v[170:173], v[200:203], v[72:75]
	v_mfma_f32_16x16x32_bf16 v[68:71], v[184:187], v[192:195], v[68:71]
	v_mfma_f32_16x16x32_bf16 v[64:67], v[184:187], v[200:203], v[64:67]
	v_mfma_f32_16x16x32_bf16 v[92:95], v[158:161], v[196:199], v[92:95]
	v_mfma_f32_16x16x32_bf16 v[88:91], v[158:161], v[204:207], v[88:91]
	v_mfma_f32_16x16x32_bf16 v[84:87], v[166:169], v[196:199], v[84:87]
	v_mfma_f32_16x16x32_bf16 v[80:83], v[166:169], v[204:207], v[80:83]
	v_mfma_f32_16x16x32_bf16 v[76:79], v[174:177], v[196:199], v[76:79]
	v_mfma_f32_16x16x32_bf16 v[72:75], v[174:177], v[204:207], v[72:75]
	v_mfma_f32_16x16x32_bf16 v[68:71], v[188:191], v[196:199], v[68:71]
	v_mfma_f32_16x16x32_bf16 v[64:67], v[188:191], v[204:207], v[64:67]
	s_barrier
	ds_read_b128 v[154:157], v178 offset:49152
	ds_read_b128 v[158:161], v178 offset:50176
	ds_read_b128 v[162:165], v178 offset:51200
	ds_read_b128 v[166:169], v178 offset:52224
	ds_read_b128 v[170:173], v178 offset:53248
	ds_read_b128 v[174:177], v178 offset:54272
	ds_read_b128 v[184:187], v178 offset:55296
	ds_read_b128 v[188:191], v178 offset:56320
	s_mov_b32 m0, s37
	v_lshl_add_u64 v[216:217], v[210:211], 0, s[24:25]
	global_load_lds_dwordx4 v[216:217], off
	s_mov_b32 m0, s12
	v_lshl_add_u64 v[218:219], v[210:211], 0, s[26:27]
	global_load_lds_dwordx4 v[218:219], off
	s_mov_b32 m0, s13
	v_lshl_add_u64 v[214:215], v[208:209], 0, s[24:25]
	global_load_lds_dwordx4 v[214:215], off
	s_mov_b32 m0, s28
	v_lshl_add_u64 v[216:217], v[208:209], 0, s[26:27]
	global_load_lds_dwordx4 v[216:217], off
	s_mov_b32 m0, s29
	s_mov_b64 s[52:53], 0x40180
	v_lshl_add_u64 v[218:219], v[210:211], 0, s[52:53]
	global_load_lds_dwordx4 v[218:219], off
	s_mov_b32 m0, s30
	s_mov_b64 s[52:53], 0x60180
	v_lshl_add_u64 v[214:215], v[210:211], 0, s[52:53]
	global_load_lds_dwordx4 v[214:215], off
	s_waitcnt vmcnt(6)
	s_waitcnt lgkmcnt(0)
	s_barrier
	v_mfma_f32_16x16x32_bf16 v[60:63], v[154:157], v[138:141], v[60:63]
	v_mfma_f32_16x16x32_bf16 v[56:59], v[154:157], v[146:149], v[56:59]
	v_mfma_f32_16x16x32_bf16 v[52:55], v[162:165], v[138:141], v[52:55]
	v_mfma_f32_16x16x32_bf16 v[48:51], v[162:165], v[146:149], v[48:51]
	v_mfma_f32_16x16x32_bf16 v[44:47], v[170:173], v[138:141], v[44:47]
	v_mfma_f32_16x16x32_bf16 v[40:43], v[170:173], v[146:149], v[40:43]
	v_mfma_f32_16x16x32_bf16 v[36:39], v[184:187], v[138:141], v[36:39]
	v_mfma_f32_16x16x32_bf16 v[32:35], v[184:187], v[146:149], v[32:35]
	v_mfma_f32_16x16x32_bf16 v[60:63], v[158:161], v[142:145], v[60:63]
	v_mfma_f32_16x16x32_bf16 v[56:59], v[158:161], v[150:153], v[56:59]
	v_mfma_f32_16x16x32_bf16 v[52:55], v[166:169], v[142:145], v[52:55]
	v_mfma_f32_16x16x32_bf16 v[48:51], v[166:169], v[150:153], v[48:51]
	v_mfma_f32_16x16x32_bf16 v[44:47], v[174:177], v[142:145], v[44:47]
	v_mfma_f32_16x16x32_bf16 v[40:43], v[174:177], v[150:153], v[40:43]
	v_mfma_f32_16x16x32_bf16 v[36:39], v[188:191], v[142:145], v[36:39]
	v_mfma_f32_16x16x32_bf16 v[32:35], v[188:191], v[150:153], v[32:35]
	v_mfma_f32_16x16x32_bf16 v[28:31], v[154:157], v[192:195], v[28:31]
	v_mfma_f32_16x16x32_bf16 v[24:27], v[154:157], v[200:203], v[24:27]
	v_mfma_f32_16x16x32_bf16 v[20:23], v[162:165], v[192:195], v[20:23]
	v_mfma_f32_16x16x32_bf16 v[16:19], v[162:165], v[200:203], v[16:19]
	v_mfma_f32_16x16x32_bf16 v[12:15], v[170:173], v[192:195], v[12:15]
	v_mfma_f32_16x16x32_bf16 v[8:11], v[170:173], v[200:203], v[8:11]
	v_mfma_f32_16x16x32_bf16 v[4:7], v[184:187], v[192:195], v[4:7]
	v_mfma_f32_16x16x32_bf16 v[0:3], v[184:187], v[200:203], v[0:3]
	v_mfma_f32_16x16x32_bf16 v[28:31], v[158:161], v[196:199], v[28:31]
	v_mfma_f32_16x16x32_bf16 v[24:27], v[158:161], v[204:207], v[24:27]
	v_mfma_f32_16x16x32_bf16 v[20:23], v[166:169], v[196:199], v[20:23]
	v_mfma_f32_16x16x32_bf16 v[16:19], v[166:169], v[204:207], v[16:19]
	v_mfma_f32_16x16x32_bf16 v[12:15], v[174:177], v[196:199], v[12:15]
	v_mfma_f32_16x16x32_bf16 v[8:11], v[174:177], v[204:207], v[8:11]
	v_mfma_f32_16x16x32_bf16 v[4:7], v[188:191], v[196:199], v[4:7]
	v_mfma_f32_16x16x32_bf16 v[0:3], v[188:191], v[204:207], v[0:3]
	s_add_i32 s41, s41, 2
	s_add_u32 s42, s42, 0x100
	s_addc_u32 s43, s43, 0
	s_add_u32 s44, s44, 0x100
	s_addc_u32 s45, s45, 0
	s_cmp_ge_i32 s41, s46
	s_barrier
	s_cbranch_scc0 .LBB0_523

; #define STAGE(P, BASE, br, kt) do { const char* _g = (const char*)((BASE) + (size_t)(br) * K + (size_t)(kt) * G_BK); \
;     _Pragma("unroll") for (int _i = 0; _i < 2; ++_i) { \
;       __builtin_amdgcn_global_load_lds((const unsigned*)(_g + (size_t)_i * 128 * K + sg_off), (unsigned*)((char*)(P) + wid * 1024 + _i * 8192), 16, 0, 0); } } while (0)
; #define LDA(dst, b, h) _Pragma("unroll") for (int m = 0; m < 4; ++m) _Pragma("unroll") for (int k = 0; k < 2; ++k) \
;     dst[m][k] = *reinterpret_cast<const bf16x8*>((const char*)shm + aoff + (((b) * 2 + (h)) * 16384 + m * 2048 + k * 1024))
; #define LDB(dst, b, h) _Pragma("unroll") for (int n = 0; n < 2; ++n) _Pragma("unroll") for (int k = 0; k < 2; ++k) \
;     dst[n][k] = *reinterpret_cast<const bf16x8*>((const char*)shm + boff + (((b) * 2 + (h)) * 16384 + n * 2048 + k * 1024))
; #define WAIT_V(n) asm volatile("s_waitcnt vmcnt(" #n ")" ::: "memory")
; #define WAIT_L(n) asm volatile("s_waitcnt lgkmcnt(" #n ")" ::: "memory")
; #define BAR __builtin_amdgcn_s_barrier()
; #define SCHED __builtin_amdgcn_sched_barrier(0)
; template <class Epi>
; __device__ __forceinline__ void gemm_phase(const bfr* __restrict__ A, int lda, const bfr* __restrict__ Bt, int K,
;                                            int nM, int nN, const Epi& epi, bfr* shm, int wv, int nMfull, int ksplit) {
;     ...
;     for (int t = 0; t < nt - 2; t += 2) {
;       LDB(B0, 0, 0); SCHED; LDA(At, 0, 0); STAGE(SA(1, 1), Ak, brow + G_HALF, t + 1);
;       WAIT_L(8); BAR; WAIT_L(0); MMA(0, 0, At, B0); BAR; SCHED;
;       LDB(B1, 0, 1); STAGE(SB(0, 0), Bk, bcol, t + 2);
;       BAR; WAIT_L(0); MMA(0, 1, At, B1); BAR;
;       LDA(At, 0, 1); STAGE(SA(0, 0), Ak, brow, t + 2);
;       BAR; WAIT_L(0); MMA(1, 0, At, B0); BAR; SCHED;
;       STAGE(SB(0, 1), Bk, bcol + G_HALF, t + 2);
;       WAIT_V(6); BAR; MMA(1, 1, At, B1); BAR;
;       LDB(B0, 1, 0); SCHED; LDA(At, 1, 0); STAGE(SA(0, 1), Ak, brow + G_HALF, t + 2);
;       WAIT_L(8); BAR; WAIT_L(0); MMA(0, 0, At, B0); BAR; SCHED;
;       LDB(B1, 1, 1); STAGE(SB(1, 0), Bk, bcol, t + 3);
;       BAR; WAIT_L(0); MMA(0, 1, At, B1); BAR;
;       LDA(At, 1, 1); STAGE(SA(1, 0), Ak, brow, t + 3);
;       BAR; WAIT_L(0); MMA(1, 0, At, B0); BAR; SCHED;
;       STAGE(SB(1, 1), Bk, bcol + G_HALF, t + 3);
;       WAIT_V(6); BAR; MMA(1, 1, At, B1); BAR;
;     }
.LBB0_673:
	ds_read_b128 v[138:141], v169
	ds_read_b128 v[142:145], v169 offset:1024
	ds_read_b128 v[146:149], v169 offset:2048
	ds_read_b128 v[150:153], v169 offset:3072
	ds_read_b128 v[154:157], v129
	ds_read_b128 v[158:161], v129 offset:1024
	ds_read_b128 v[162:165], v129 offset:2048
	ds_read_b128 v[172:175], v129 offset:3072
	ds_read_b128 v[180:183], v129 offset:4096
	ds_read_b128 v[184:187], v129 offset:5120
	ds_read_b128 v[188:191], v129 offset:6144
	ds_read_b128 v[192:195], v129 offset:7168
	ds_read_b128 v[196:199], v169 offset:16384
	ds_read_b128 v[200:203], v169 offset:17408
	ds_read_b128 v[204:207], v169 offset:18432
	ds_read_b128 v[208:211], v169 offset:19456
	v_lshl_add_u64 v[166:167], s[24:25], 0, v[136:137]
	v_lshl_add_u64 v[176:177], s[6:7], 0, v[136:137]
	s_mov_b32 m0, s52
	s_mov_b64 s[26:27], 0x40080
	v_lshl_add_u64 v[214:215], v[166:167], 0, s[26:27]
	global_load_lds_dwordx4 v[214:215], off
	s_mov_b32 m0, s53
	s_mov_b64 s[26:27], 0x60080
	v_lshl_add_u64 v[216:217], v[166:167], 0, s[26:27]
	global_load_lds_dwordx4 v[216:217], off
	s_waitcnt lgkmcnt(0)
	s_barrier
	v_mfma_f32_16x16x32_bf16 v[124:127], v[154:157], v[138:141], v[124:127]
	v_mfma_f32_16x16x32_bf16 v[120:123], v[154:157], v[146:149], v[120:123]
	v_mfma_f32_16x16x32_bf16 v[116:119], v[162:165], v[138:141], v[116:119]
	v_mfma_f32_16x16x32_bf16 v[112:115], v[162:165], v[146:149], v[112:115]
	v_mfma_f32_16x16x32_bf16 v[108:111], v[180:183], v[138:141], v[108:111]
	v_mfma_f32_16x16x32_bf16 v[104:107], v[180:183], v[146:149], v[104:107]
	v_mfma_f32_16x16x32_bf16 v[100:103], v[188:191], v[138:141], v[100:103]
	v_mfma_f32_16x16x32_bf16 v[96:99], v[188:191], v[146:149], v[96:99]
	v_mfma_f32_16x16x32_bf16 v[124:127], v[158:161], v[142:145], v[124:127]
	v_mfma_f32_16x16x32_bf16 v[120:123], v[158:161], v[150:153], v[120:123]
	v_mfma_f32_16x16x32_bf16 v[116:119], v[172:175], v[142:145], v[116:119]
	v_mfma_f32_16x16x32_bf16 v[112:115], v[172:175], v[150:153], v[112:115]
	v_mfma_f32_16x16x32_bf16 v[108:111], v[184:187], v[142:145], v[108:111]
	v_mfma_f32_16x16x32_bf16 v[104:107], v[184:187], v[150:153], v[104:107]
	v_mfma_f32_16x16x32_bf16 v[100:103], v[192:195], v[142:145], v[100:103]
	v_mfma_f32_16x16x32_bf16 v[96:99], v[192:195], v[150:153], v[96:99]
	v_mfma_f32_16x16x32_bf16 v[92:95], v[154:157], v[196:199], v[92:95]
	v_mfma_f32_16x16x32_bf16 v[88:91], v[154:157], v[204:207], v[88:91]
	v_mfma_f32_16x16x32_bf16 v[84:87], v[162:165], v[196:199], v[84:87]
	v_mfma_f32_16x16x32_bf16 v[80:83], v[162:165], v[204:207], v[80:83]
	v_mfma_f32_16x16x32_bf16 v[76:79], v[180:183], v[196:199], v[76:79]
	v_mfma_f32_16x16x32_bf16 v[72:75], v[180:183], v[204:207], v[72:75]
	v_mfma_f32_16x16x32_bf16 v[68:71], v[188:191], v[196:199], v[68:71]
	v_mfma_f32_16x16x32_bf16 v[64:67], v[188:191], v[204:207], v[64:67]
	v_mfma_f32_16x16x32_bf16 v[92:95], v[158:161], v[200:203], v[92:95]
	v_mfma_f32_16x16x32_bf16 v[88:91], v[158:161], v[208:211], v[88:91]
	v_mfma_f32_16x16x32_bf16 v[84:87], v[172:175], v[200:203], v[84:87]
	v_mfma_f32_16x16x32_bf16 v[80:83], v[172:175], v[208:211], v[80:83]
	v_mfma_f32_16x16x32_bf16 v[76:79], v[184:187], v[200:203], v[76:79]
	v_mfma_f32_16x16x32_bf16 v[72:75], v[184:187], v[208:211], v[72:75]
	v_mfma_f32_16x16x32_bf16 v[68:71], v[192:195], v[200:203], v[68:71]
	v_mfma_f32_16x16x32_bf16 v[64:67], v[192:195], v[208:211], v[64:67]
	s_barrier
	ds_read_b128 v[154:157], v129 offset:16384
	ds_read_b128 v[158:161], v129 offset:17408
	ds_read_b128 v[162:165], v129 offset:18432
	ds_read_b128 v[172:175], v129 offset:19456
	ds_read_b128 v[180:183], v129 offset:20480
	ds_read_b128 v[184:187], v129 offset:21504
	ds_read_b128 v[188:191], v129 offset:22528
	ds_read_b128 v[192:195], v129 offset:23552
	s_mov_b32 m0, s39
	s_mov_b64 s[26:27], 0xb00100
	v_lshl_add_u64 v[218:219], v[176:177], 0, s[26:27]
	global_load_lds_dwordx4 v[218:219], off
	s_mov_b32 m0, s40
	s_mov_b64 s[26:27], 0xb20100
	v_lshl_add_u64 v[214:215], v[176:177], 0, s[26:27]
	global_load_lds_dwordx4 v[214:215], off
	s_mov_b32 m0, s38
	s_mov_b64 s[26:27], 0x100
	v_lshl_add_u64 v[216:217], v[166:167], 0, s[26:27]
	global_load_lds_dwordx4 v[216:217], off
	s_mov_b32 m0, s41
	s_mov_b64 s[26:27], 0x20100
	v_lshl_add_u64 v[218:219], v[166:167], 0, s[26:27]
	global_load_lds_dwordx4 v[218:219], off
	s_mov_b32 m0, s42
	s_mov_b64 s[26:27], 0xb40100
	v_lshl_add_u64 v[214:215], v[176:177], 0, s[26:27]
	global_load_lds_dwordx4 v[214:215], off
	s_mov_b32 m0, s43
	s_mov_b64 s[26:27], 0xb60100
	v_lshl_add_u64 v[216:217], v[176:177], 0, s[26:27]
	global_load_lds_dwordx4 v[216:217], off
	s_waitcnt vmcnt(6)
	s_waitcnt lgkmcnt(0)
	s_barrier
; #define STAGE(P, BASE, br, kt) do { const char* _g = (const char*)((BASE) + (size_t)(br) * K + (size_t)(kt) * G_BK); \
;     _Pragma("unroll") for (int _i = 0; _i < 2; ++_i) { \
;       __builtin_amdgcn_global_load_lds((const unsigned*)(_g + (size_t)_i * 128 * K + sg_off), (unsigned*)((char*)(P) + wid * 1024 + _i * 8192), 16, 0, 0); } } while (0)
; #define LDA(dst, b, h) _Pragma("unroll") for (int m = 0; m < 4; ++m) _Pragma("unroll") for (int k = 0; k < 2; ++k) \
;     dst[m][k] = *reinterpret_cast<const bf16x8*>((const char*)shm + aoff + (((b) * 2 + (h)) * 16384 + m * 2048 + k * 1024))
; #define LDB(dst, b, h) _Pragma("unroll") for (int n = 0; n < 2; ++n) _Pragma("unroll") for (int k = 0; k < 2; ++k) \
;     dst[n][k] = *reinterpret_cast<const bf16x8*>((const char*)shm + boff + (((b) * 2 + (h)) * 16384 + n * 2048 + k * 1024))
; #define WAIT_V(n) asm volatile("s_waitcnt vmcnt(" #n ")" ::: "memory")
; #define WAIT_L(n) asm volatile("s_waitcnt lgkmcnt(" #n ")" ::: "memory")
; #define BAR __builtin_amdgcn_s_barrier()
; #define SCHED __builtin_amdgcn_sched_barrier(0)
; template <class Epi>
; __device__ __forceinline__ void gemm_phase(const bfr* __restrict__ A, int lda, const bfr* __restrict__ Bt, int K,
;                                            int nM, int nN, const Epi& epi, bfr* shm, int wv, int nMfull, int ksplit) {
;     ...
;     for (int t = 0; t < nt - 2; t += 2) {
;       LDB(B0, 0, 0); SCHED; LDA(At, 0, 0); STAGE(SA(1, 1), Ak, brow + G_HALF, t + 1);
;       WAIT_L(8); BAR; WAIT_L(0); MMA(0, 0, At, B0); BAR; SCHED;
;       LDB(B1, 0, 1); STAGE(SB(0, 0), Bk, bcol, t + 2);
;       BAR; WAIT_L(0); MMA(0, 1, At, B1); BAR;
;       LDA(At, 0, 1); STAGE(SA(0, 0), Ak, brow, t + 2);
;       BAR; WAIT_L(0); MMA(1, 0, At, B0); BAR; SCHED;
;       STAGE(SB(0, 1), Bk, bcol + G_HALF, t + 2);
;       WAIT_V(6); BAR; MMA(1, 1, At, B1); BAR;
;       LDB(B0, 1, 0); SCHED; LDA(At, 1, 0); STAGE(SA(0, 1), Ak, brow + G_HALF, t + 2);
;       WAIT_L(8); BAR; WAIT_L(0); MMA(0, 0, At, B0); BAR; SCHED;
;       LDB(B1, 1, 1); STAGE(SB(1, 0), Bk, bcol, t + 3);
;       BAR; WAIT_L(0); MMA(0, 1, At, B1); BAR;
;       LDA(At, 1, 1); STAGE(SA(1, 0), Ak, brow, t + 3);
;       BAR; WAIT_L(0); MMA(1, 0, At, B0); BAR; SCHED;
;       STAGE(SB(1, 1), Bk, bcol + G_HALF, t + 3);
;       WAIT_V(6); BAR; MMA(1, 1, At, B1); BAR;
;     }
	v_mfma_f32_16x16x32_bf16 v[60:63], v[154:157], v[138:141], v[60:63]
	v_mfma_f32_16x16x32_bf16 v[56:59], v[154:157], v[146:149], v[56:59]
	v_mfma_f32_16x16x32_bf16 v[52:55], v[162:165], v[138:141], v[52:55]
	v_mfma_f32_16x16x32_bf16 v[48:51], v[162:165], v[146:149], v[48:51]
	v_mfma_f32_16x16x32_bf16 v[44:47], v[180:183], v[138:141], v[44:47]
	v_mfma_f32_16x16x32_bf16 v[40:43], v[180:183], v[146:149], v[40:43]
	v_mfma_f32_16x16x32_bf16 v[36:39], v[188:191], v[138:141], v[36:39]
	v_mfma_f32_16x16x32_bf16 v[32:35], v[188:191], v[146:149], v[32:35]
	v_mfma_f32_16x16x32_bf16 v[60:63], v[158:161], v[142:145], v[60:63]
	v_mfma_f32_16x16x32_bf16 v[56:59], v[158:161], v[150:153], v[56:59]
	v_mfma_f32_16x16x32_bf16 v[52:55], v[172:175], v[142:145], v[52:55]
	v_mfma_f32_16x16x32_bf16 v[48:51], v[172:175], v[150:153], v[48:51]
	v_mfma_f32_16x16x32_bf16 v[44:47], v[184:187], v[142:145], v[44:47]
	v_mfma_f32_16x16x32_bf16 v[40:43], v[184:187], v[150:153], v[40:43]
	v_mfma_f32_16x16x32_bf16 v[36:39], v[192:195], v[142:145], v[36:39]
	v_mfma_f32_16x16x32_bf16 v[32:35], v[192:195], v[150:153], v[32:35]
	v_mfma_f32_16x16x32_bf16 v[28:31], v[154:157], v[196:199], v[28:31]
	v_mfma_f32_16x16x32_bf16 v[24:27], v[154:157], v[204:207], v[24:27]
	v_mfma_f32_16x16x32_bf16 v[20:23], v[162:165], v[196:199], v[20:23]
	v_mfma_f32_16x16x32_bf16 v[16:19], v[162:165], v[204:207], v[16:19]
	v_mfma_f32_16x16x32_bf16 v[12:15], v[180:183], v[196:199], v[12:15]
	v_mfma_f32_16x16x32_bf16 v[8:11], v[180:183], v[204:207], v[8:11]
	v_mfma_f32_16x16x32_bf16 v[4:7], v[188:191], v[196:199], v[4:7]
	v_mfma_f32_16x16x32_bf16 v[0:3], v[188:191], v[204:207], v[0:3]
	v_mfma_f32_16x16x32_bf16 v[28:31], v[158:161], v[200:203], v[28:31]
	v_mfma_f32_16x16x32_bf16 v[24:27], v[158:161], v[208:211], v[24:27]
	v_mfma_f32_16x16x32_bf16 v[20:23], v[172:175], v[200:203], v[20:23]
	v_mfma_f32_16x16x32_bf16 v[16:19], v[172:175], v[208:211], v[16:19]
	v_mfma_f32_16x16x32_bf16 v[12:15], v[184:187], v[200:203], v[12:15]
	v_mfma_f32_16x16x32_bf16 v[8:11], v[184:187], v[208:211], v[8:11]
	v_mfma_f32_16x16x32_bf16 v[4:7], v[192:195], v[200:203], v[4:7]
	v_mfma_f32_16x16x32_bf16 v[0:3], v[192:195], v[208:211], v[0:3]
	s_barrier
	ds_read_b128 v[138:141], v169 offset:32768
	ds_read_b128 v[142:145], v169 offset:33792
	ds_read_b128 v[146:149], v169 offset:34816
	ds_read_b128 v[150:153], v169 offset:35840
	ds_read_b128 v[154:157], v129 offset:32768
	ds_read_b128 v[158:161], v129 offset:33792
	ds_read_b128 v[162:165], v129 offset:34816
	ds_read_b128 v[172:175], v129 offset:35840
	ds_read_b128 v[180:183], v129 offset:36864
	ds_read_b128 v[184:187], v129 offset:37888
	ds_read_b128 v[188:191], v129 offset:38912
	ds_read_b128 v[192:195], v129 offset:39936
	ds_read_b128 v[196:199], v169 offset:49152
	ds_read_b128 v[200:203], v169 offset:50176
	ds_read_b128 v[204:207], v169 offset:51200
	ds_read_b128 v[208:211], v169 offset:52224
	s_mov_b32 m0, s44
	s_mov_b64 s[26:27], 0x40100
	v_lshl_add_u64 v[218:219], v[166:167], 0, s[26:27]
	global_load_lds_dwordx4 v[218:219], off
	s_mov_b32 m0, s45
	s_mov_b64 s[26:27], 0x60100
	v_lshl_add_u64 v[214:215], v[166:167], 0, s[26:27]
	global_load_lds_dwordx4 v[214:215], off
	s_waitcnt lgkmcnt(0)
	s_barrier
	v_mfma_f32_16x16x32_bf16 v[124:127], v[154:157], v[138:141], v[124:127]
	v_mfma_f32_16x16x32_bf16 v[120:123], v[154:157], v[146:149], v[120:123]
	v_mfma_f32_16x16x32_bf16 v[116:119], v[162:165], v[138:141], v[116:119]
	v_mfma_f32_16x16x32_bf16 v[112:115], v[162:165], v[146:149], v[112:115]
	v_mfma_f32_16x16x32_bf16 v[108:111], v[180:183], v[138:141], v[108:111]
	v_mfma_f32_16x16x32_bf16 v[104:107], v[180:183], v[146:149], v[104:107]
	v_mfma_f32_16x16x32_bf16 v[100:103], v[188:191], v[138:141], v[100:103]
	v_mfma_f32_16x16x32_bf16 v[96:99], v[188:191], v[146:149], v[96:99]
	v_mfma_f32_16x16x32_bf16 v[124:127], v[158:161], v[142:145], v[124:127]
	v_mfma_f32_16x16x32_bf16 v[120:123], v[158:161], v[150:153], v[120:123]
	v_mfma_f32_16x16x32_bf16 v[116:119], v[172:175], v[142:145], v[116:119]
	v_mfma_f32_16x16x32_bf16 v[112:115], v[172:175], v[150:153], v[112:115]
	v_mfma_f32_16x16x32_bf16 v[108:111], v[184:187], v[142:145], v[108:111]
	v_mfma_f32_16x16x32_bf16 v[104:107], v[184:187], v[150:153], v[104:107]
	v_mfma_f32_16x16x32_bf16 v[100:103], v[192:195], v[142:145], v[100:103]
	v_mfma_f32_16x16x32_bf16 v[96:99], v[192:195], v[150:153], v[96:99]
	v_mfma_f32_16x16x32_bf16 v[92:95], v[154:157], v[196:199], v[92:95]
	v_mfma_f32_16x16x32_bf16 v[88:91], v[154:157], v[204:207], v[88:91]
	v_mfma_f32_16x16x32_bf16 v[84:87], v[162:165], v[196:199], v[84:87]
	v_mfma_f32_16x16x32_bf16 v[80:83], v[162:165], v[204:207], v[80:83]
	v_mfma_f32_16x16x32_bf16 v[76:79], v[180:183], v[196:199], v[76:79]
	v_mfma_f32_16x16x32_bf16 v[72:75], v[180:183], v[204:207], v[72:75]
	v_mfma_f32_16x16x32_bf16 v[68:71], v[188:191], v[196:199], v[68:71]
	v_mfma_f32_16x16x32_bf16 v[64:67], v[188:191], v[204:207], v[64:67]
	v_mfma_f32_16x16x32_bf16 v[92:95], v[158:161], v[200:203], v[92:95]
	v_mfma_f32_16x16x32_bf16 v[88:91], v[158:161], v[208:211], v[88:91]
	v_mfma_f32_16x16x32_bf16 v[84:87], v[172:175], v[200:203], v[84:87]
	v_mfma_f32_16x16x32_bf16 v[80:83], v[172:175], v[208:211], v[80:83]
	v_mfma_f32_16x16x32_bf16 v[76:79], v[184:187], v[200:203], v[76:79]
	v_mfma_f32_16x16x32_bf16 v[72:75], v[184:187], v[208:211], v[72:75]
	v_mfma_f32_16x16x32_bf16 v[68:71], v[192:195], v[200:203], v[68:71]
	v_mfma_f32_16x16x32_bf16 v[64:67], v[192:195], v[208:211], v[64:67]
	s_barrier
; #define STAGE(P, BASE, br, kt) do { const char* _g = (const char*)((BASE) + (size_t)(br) * K + (size_t)(kt) * G_BK); \
;     _Pragma("unroll") for (int _i = 0; _i < 2; ++_i) { \
;       __builtin_amdgcn_global_load_lds((const unsigned*)(_g + (size_t)_i * 128 * K + sg_off), (unsigned*)((char*)(P) + wid * 1024 + _i * 8192), 16, 0, 0); } } while (0)
; #define LDA(dst, b, h) _Pragma("unroll") for (int m = 0; m < 4; ++m) _Pragma("unroll") for (int k = 0; k < 2; ++k) \
;     dst[m][k] = *reinterpret_cast<const bf16x8*>((const char*)shm + aoff + (((b) * 2 + (h)) * 16384 + m * 2048 + k * 1024))
; #define LDB(dst, b, h) _Pragma("unroll") for (int n = 0; n < 2; ++n) _Pragma("unroll") for (int k = 0; k < 2; ++k) \
;     dst[n][k] = *reinterpret_cast<const bf16x8*>((const char*)shm + boff + (((b) * 2 + (h)) * 16384 + n * 2048 + k * 1024))
; #define WAIT_V(n) asm volatile("s_waitcnt vmcnt(" #n ")" ::: "memory")
; #define WAIT_L(n) asm volatile("s_waitcnt lgkmcnt(" #n ")" ::: "memory")
; #define BAR __builtin_amdgcn_s_barrier()
; #define SCHED __builtin_amdgcn_sched_barrier(0)
; template <class Epi>
; __device__ __forceinline__ void gemm_phase(const bfr* __restrict__ A, int lda, const bfr* __restrict__ Bt, int K,
;                                            int nM, int nN, const Epi& epi, bfr* shm, int wv, int nMfull, int ksplit) {
;     ...
;     for (int t = 0; t < nt - 2; t += 2) {
;       LDB(B0, 0, 0); SCHED; LDA(At, 0, 0); STAGE(SA(1, 1), Ak, brow + G_HALF, t + 1);
;       WAIT_L(8); BAR; WAIT_L(0); MMA(0, 0, At, B0); BAR; SCHED;
;       LDB(B1, 0, 1); STAGE(SB(0, 0), Bk, bcol, t + 2);
;       BAR; WAIT_L(0); MMA(0, 1, At, B1); BAR;
;       LDA(At, 0, 1); STAGE(SA(0, 0), Ak, brow, t + 2);
;       BAR; WAIT_L(0); MMA(1, 0, At, B0); BAR; SCHED;
;       STAGE(SB(0, 1), Bk, bcol + G_HALF, t + 2);
;       WAIT_V(6); BAR; MMA(1, 1, At, B1); BAR;
;       LDB(B0, 1, 0); SCHED; LDA(At, 1, 0); STAGE(SA(0, 1), Ak, brow + G_HALF, t + 2);
;       WAIT_L(8); BAR; WAIT_L(0); MMA(0, 0, At, B0); BAR; SCHED;
;       LDB(B1, 1, 1); STAGE(SB(1, 0), Bk, bcol, t + 3);
;       BAR; WAIT_L(0); MMA(0, 1, At, B1); BAR;
;       LDA(At, 1, 1); STAGE(SA(1, 0), Ak, brow, t + 3);
;       BAR; WAIT_L(0); MMA(1, 0, At, B0); BAR; SCHED;
;       STAGE(SB(1, 1), Bk, bcol + G_HALF, t + 3);
;       WAIT_V(6); BAR; MMA(1, 1, At, B1); BAR;
;     }
	ds_read_b128 v[154:157], v129 offset:49152
	ds_read_b128 v[158:161], v129 offset:50176
	ds_read_b128 v[162:165], v129 offset:51200
	ds_read_b128 v[172:175], v129 offset:52224
	ds_read_b128 v[180:183], v129 offset:53248
	ds_read_b128 v[184:187], v129 offset:54272
	ds_read_b128 v[188:191], v129 offset:55296
	ds_read_b128 v[192:195], v129 offset:56320
	s_mov_b32 m0, s46
	s_mov_b64 s[26:27], 0xb00180
	v_lshl_add_u64 v[216:217], v[176:177], 0, s[26:27]
	global_load_lds_dwordx4 v[216:217], off
	s_mov_b32 m0, s47
	s_mov_b64 s[26:27], 0xb20180
	v_lshl_add_u64 v[218:219], v[176:177], 0, s[26:27]
	global_load_lds_dwordx4 v[218:219], off
	s_mov_b32 m0, s48
	s_mov_b64 s[26:27], 0x180
	v_lshl_add_u64 v[214:215], v[166:167], 0, s[26:27]
	global_load_lds_dwordx4 v[214:215], off
	s_mov_b32 m0, s49
	s_mov_b64 s[26:27], 0x20180
	v_lshl_add_u64 v[216:217], v[166:167], 0, s[26:27]
	global_load_lds_dwordx4 v[216:217], off
	s_mov_b32 m0, s50
	s_mov_b64 s[26:27], 0xb40180
	v_lshl_add_u64 v[218:219], v[176:177], 0, s[26:27]
	global_load_lds_dwordx4 v[218:219], off
	s_mov_b32 m0, s51
	s_mov_b64 s[26:27], 0xb60180
	v_lshl_add_u64 v[214:215], v[176:177], 0, s[26:27]
	global_load_lds_dwordx4 v[214:215], off
	s_waitcnt vmcnt(6)
	s_waitcnt lgkmcnt(0)
	s_barrier
	v_mfma_f32_16x16x32_bf16 v[60:63], v[154:157], v[138:141], v[60:63]
	v_mfma_f32_16x16x32_bf16 v[56:59], v[154:157], v[146:149], v[56:59]
	v_mfma_f32_16x16x32_bf16 v[52:55], v[162:165], v[138:141], v[52:55]
	v_mfma_f32_16x16x32_bf16 v[48:51], v[162:165], v[146:149], v[48:51]
	v_mfma_f32_16x16x32_bf16 v[44:47], v[180:183], v[138:141], v[44:47]
	v_mfma_f32_16x16x32_bf16 v[40:43], v[180:183], v[146:149], v[40:43]
	v_mfma_f32_16x16x32_bf16 v[36:39], v[188:191], v[138:141], v[36:39]
	v_mfma_f32_16x16x32_bf16 v[32:35], v[188:191], v[146:149], v[32:35]
	v_mfma_f32_16x16x32_bf16 v[60:63], v[158:161], v[142:145], v[60:63]
	v_mfma_f32_16x16x32_bf16 v[56:59], v[158:161], v[150:153], v[56:59]
	v_mfma_f32_16x16x32_bf16 v[52:55], v[172:175], v[142:145], v[52:55]
	v_mfma_f32_16x16x32_bf16 v[48:51], v[172:175], v[150:153], v[48:51]
	v_mfma_f32_16x16x32_bf16 v[44:47], v[184:187], v[142:145], v[44:47]
	v_mfma_f32_16x16x32_bf16 v[40:43], v[184:187], v[150:153], v[40:43]
	v_mfma_f32_16x16x32_bf16 v[36:39], v[192:195], v[142:145], v[36:39]
	v_mfma_f32_16x16x32_bf16 v[32:35], v[192:195], v[150:153], v[32:35]
	v_mfma_f32_16x16x32_bf16 v[28:31], v[154:157], v[196:199], v[28:31]
	v_mfma_f32_16x16x32_bf16 v[24:27], v[154:157], v[204:207], v[24:27]
	v_mfma_f32_16x16x32_bf16 v[20:23], v[162:165], v[196:199], v[20:23]
	v_mfma_f32_16x16x32_bf16 v[16:19], v[162:165], v[204:207], v[16:19]
	v_mfma_f32_16x16x32_bf16 v[12:15], v[180:183], v[196:199], v[12:15]
	v_mfma_f32_16x16x32_bf16 v[8:11], v[180:183], v[204:207], v[8:11]
	v_mfma_f32_16x16x32_bf16 v[4:7], v[188:191], v[196:199], v[4:7]
	v_mfma_f32_16x16x32_bf16 v[0:3], v[188:191], v[204:207], v[0:3]
	v_mfma_f32_16x16x32_bf16 v[28:31], v[158:161], v[200:203], v[28:31]
	v_mfma_f32_16x16x32_bf16 v[24:27], v[158:161], v[208:211], v[24:27]
	v_mfma_f32_16x16x32_bf16 v[20:23], v[172:175], v[200:203], v[20:23]
	v_mfma_f32_16x16x32_bf16 v[16:19], v[172:175], v[208:211], v[16:19]
	v_mfma_f32_16x16x32_bf16 v[12:15], v[184:187], v[200:203], v[12:15]
	v_mfma_f32_16x16x32_bf16 v[8:11], v[184:187], v[208:211], v[8:11]
	v_mfma_f32_16x16x32_bf16 v[4:7], v[192:195], v[200:203], v[4:7]
	v_mfma_f32_16x16x32_bf16 v[0:3], v[192:195], v[208:211], v[0:3]
	s_add_i32 s3, s3, 2
	s_add_u32 s6, s6, 0x100
	s_addc_u32 s7, s7, 0
	s_add_u32 s24, s24, 0x100
	s_addc_u32 s25, s25, 0
	s_cmp_ge_i32 s3, s2
	s_barrier
	s_cbranch_scc0 .LBB0_673

; #define STAGE(P, BASE, br, kt) do { const char* _g = (const char*)((BASE) + (size_t)(br) * K + (size_t)(kt) * G_BK); \
;     _Pragma("unroll") for (int _i = 0; _i < 2; ++_i) { \
;       __builtin_amdgcn_global_load_lds((const unsigned*)(_g + (size_t)_i * 128 * K + sg_off), (unsigned*)((char*)(P) + wid * 1024 + _i * 8192), 16, 0, 0); } } while (0)
; #define LDA(dst, b, h) _Pragma("unroll") for (int m = 0; m < 4; ++m) _Pragma("unroll") for (int k = 0; k < 2; ++k) \
;     dst[m][k] = *reinterpret_cast<const bf16x8*>((const char*)shm + aoff + (((b) * 2 + (h)) * 16384 + m * 2048 + k * 1024))
; #define LDB(dst, b, h) _Pragma("unroll") for (int n = 0; n < 2; ++n) _Pragma("unroll") for (int k = 0; k < 2; ++k) \
;     dst[n][k] = *reinterpret_cast<const bf16x8*>((const char*)shm + boff + (((b) * 2 + (h)) * 16384 + n * 2048 + k * 1024))
; #define WAIT_V(n) asm volatile("s_waitcnt vmcnt(" #n ")" ::: "memory")
; #define WAIT_L(n) asm volatile("s_waitcnt lgkmcnt(" #n ")" ::: "memory")
; #define BAR __builtin_amdgcn_s_barrier()
; #define SCHED __builtin_amdgcn_sched_barrier(0)
; template <class Epi>
; __device__ __forceinline__ void gemm_phase(const bfr* __restrict__ A, int lda, const bfr* __restrict__ Bt, int K,
;                                            int nM, int nN, const Epi& epi, bfr* shm, int wv, int nMfull, int ksplit) {
;     ...
;     for (int t = 0; t < nt - 2; t += 2) {
;       LDB(B0, 0, 0); SCHED; LDA(At, 0, 0); STAGE(SA(1, 1), Ak, brow + G_HALF, t + 1);
;       WAIT_L(8); BAR; WAIT_L(0); MMA(0, 0, At, B0); BAR; SCHED;
;       LDB(B1, 0, 1); STAGE(SB(0, 0), Bk, bcol, t + 2);
;       BAR; WAIT_L(0); MMA(0, 1, At, B1); BAR;
;       LDA(At, 0, 1); STAGE(SA(0, 0), Ak, brow, t + 2);
;       BAR; WAIT_L(0); MMA(1, 0, At, B0); BAR; SCHED;
;       STAGE(SB(0, 1), Bk, bcol + G_HALF, t + 2);
;       WAIT_V(6); BAR; MMA(1, 1, At, B1); BAR;
;       LDB(B0, 1, 0); SCHED; LDA(At, 1, 0); STAGE(SA(0, 1), Ak, brow + G_HALF, t + 2);
;       WAIT_L(8); BAR; WAIT_L(0); MMA(0, 0, At, B0); BAR; SCHED;
;       LDB(B1, 1, 1); STAGE(SB(1, 0), Bk, bcol, t + 3);
;       BAR; WAIT_L(0); MMA(0, 1, At, B1); BAR;
;       LDA(At, 1, 1); STAGE(SA(1, 0), Ak, brow, t + 3);
;       BAR; WAIT_L(0); MMA(1, 0, At, B0); BAR; SCHED;
;       STAGE(SB(1, 1), Bk, bcol + G_HALF, t + 3);
;       WAIT_V(6); BAR; MMA(1, 1, At, B1); BAR;
;     }
.LBB0_729:
	ds_read_b128 v[138:141], v179
	ds_read_b128 v[142:145], v179 offset:1024
	ds_read_b128 v[146:149], v179 offset:2048
	ds_read_b128 v[150:153], v179 offset:3072
	ds_read_b128 v[154:157], v178
	ds_read_b128 v[158:161], v178 offset:1024
	ds_read_b128 v[162:165], v178 offset:2048
	ds_read_b128 v[166:169], v178 offset:3072
	ds_read_b128 v[170:173], v178 offset:4096
	ds_read_b128 v[174:177], v178 offset:5120
	ds_read_b128 v[184:187], v178 offset:6144
	ds_read_b128 v[188:191], v178 offset:7168
	ds_read_b128 v[192:195], v179 offset:16384
	ds_read_b128 v[196:199], v179 offset:17408
	ds_read_b128 v[200:203], v179 offset:18432
	ds_read_b128 v[204:207], v179 offset:19456
	v_lshl_add_u64 v[208:209], s[34:35], 0, v[136:137]
	v_lshl_add_u64 v[210:211], s[38:39], 0, v[136:137]
	s_mov_b32 m0, s52
	v_lshl_add_u64 v[214:215], v[208:209], 0, s[16:17]
	global_load_lds_dwordx4 v[214:215], off
	s_mov_b32 m0, s53
	v_lshl_add_u64 v[216:217], v[208:209], 0, s[18:19]
	global_load_lds_dwordx4 v[216:217], off
	s_waitcnt lgkmcnt(0)
	s_barrier
	v_mfma_f32_16x16x32_bf16 v[124:127], v[154:157], v[138:141], v[124:127]
	v_mfma_f32_16x16x32_bf16 v[120:123], v[154:157], v[146:149], v[120:123]
	v_mfma_f32_16x16x32_bf16 v[116:119], v[162:165], v[138:141], v[116:119]
	v_mfma_f32_16x16x32_bf16 v[112:115], v[162:165], v[146:149], v[112:115]
	v_mfma_f32_16x16x32_bf16 v[108:111], v[170:173], v[138:141], v[108:111]
	v_mfma_f32_16x16x32_bf16 v[104:107], v[170:173], v[146:149], v[104:107]
	v_mfma_f32_16x16x32_bf16 v[100:103], v[184:187], v[138:141], v[100:103]
	v_mfma_f32_16x16x32_bf16 v[96:99], v[184:187], v[146:149], v[96:99]
	v_mfma_f32_16x16x32_bf16 v[124:127], v[158:161], v[142:145], v[124:127]
	v_mfma_f32_16x16x32_bf16 v[120:123], v[158:161], v[150:153], v[120:123]
	v_mfma_f32_16x16x32_bf16 v[116:119], v[166:169], v[142:145], v[116:119]
	v_mfma_f32_16x16x32_bf16 v[112:115], v[166:169], v[150:153], v[112:115]
	v_mfma_f32_16x16x32_bf16 v[108:111], v[174:177], v[142:145], v[108:111]
	v_mfma_f32_16x16x32_bf16 v[104:107], v[174:177], v[150:153], v[104:107]
	v_mfma_f32_16x16x32_bf16 v[100:103], v[188:191], v[142:145], v[100:103]
	v_mfma_f32_16x16x32_bf16 v[96:99], v[188:191], v[150:153], v[96:99]
	v_mfma_f32_16x16x32_bf16 v[92:95], v[154:157], v[192:195], v[92:95]
	v_mfma_f32_16x16x32_bf16 v[88:91], v[154:157], v[200:203], v[88:91]
	v_mfma_f32_16x16x32_bf16 v[84:87], v[162:165], v[192:195], v[84:87]
	v_mfma_f32_16x16x32_bf16 v[80:83], v[162:165], v[200:203], v[80:83]
	v_mfma_f32_16x16x32_bf16 v[76:79], v[170:173], v[192:195], v[76:79]
	v_mfma_f32_16x16x32_bf16 v[72:75], v[170:173], v[200:203], v[72:75]
	v_mfma_f32_16x16x32_bf16 v[68:71], v[184:187], v[192:195], v[68:71]
	v_mfma_f32_16x16x32_bf16 v[64:67], v[184:187], v[200:203], v[64:67]
	v_mfma_f32_16x16x32_bf16 v[92:95], v[158:161], v[196:199], v[92:95]
	v_mfma_f32_16x16x32_bf16 v[88:91], v[158:161], v[204:207], v[88:91]
	v_mfma_f32_16x16x32_bf16 v[84:87], v[166:169], v[196:199], v[84:87]
	v_mfma_f32_16x16x32_bf16 v[80:83], v[166:169], v[204:207], v[80:83]
	v_mfma_f32_16x16x32_bf16 v[76:79], v[174:177], v[196:199], v[76:79]
	v_mfma_f32_16x16x32_bf16 v[72:75], v[174:177], v[204:207], v[72:75]
	v_mfma_f32_16x16x32_bf16 v[68:71], v[188:191], v[196:199], v[68:71]
	v_mfma_f32_16x16x32_bf16 v[64:67], v[188:191], v[204:207], v[64:67]
	s_barrier
	ds_read_b128 v[154:157], v178 offset:16384
	ds_read_b128 v[158:161], v178 offset:17408
	ds_read_b128 v[162:165], v178 offset:18432
	ds_read_b128 v[166:169], v178 offset:19456
	ds_read_b128 v[170:173], v178 offset:20480
	ds_read_b128 v[174:177], v178 offset:21504
	ds_read_b128 v[184:187], v178 offset:22528
	ds_read_b128 v[188:191], v178 offset:23552
	s_mov_b32 m0, s54
	s_mov_b64 s[40:41], 0x580100
	v_lshl_add_u64 v[218:219], v[210:211], 0, s[40:41]
	global_load_lds_dwordx4 v[218:219], off
	s_mov_b32 m0, s55
	s_mov_b64 s[40:41], 0x5d8100
	v_lshl_add_u64 v[214:215], v[210:211], 0, s[40:41]
	global_load_lds_dwordx4 v[214:215], off
	s_mov_b32 m0, s51
	s_mov_b64 s[40:41], 0x100
	v_lshl_add_u64 v[216:217], v[208:209], 0, s[40:41]
	global_load_lds_dwordx4 v[216:217], off
	s_mov_b32 m0, s56
	s_mov_b64 s[40:41], 0x58100
	v_lshl_add_u64 v[218:219], v[208:209], 0, s[40:41]
	global_load_lds_dwordx4 v[218:219], off
	s_mov_b32 m0, s57
	s_mov_b64 s[40:41], 0x630100
	v_lshl_add_u64 v[214:215], v[210:211], 0, s[40:41]
	global_load_lds_dwordx4 v[214:215], off
	s_mov_b32 m0, s58
	s_mov_b64 s[40:41], 0x688100
	v_lshl_add_u64 v[216:217], v[210:211], 0, s[40:41]
	global_load_lds_dwordx4 v[216:217], off
	s_waitcnt vmcnt(6)
	s_waitcnt lgkmcnt(0)
	s_barrier
; #define STAGE(P, BASE, br, kt) do { const char* _g = (const char*)((BASE) + (size_t)(br) * K + (size_t)(kt) * G_BK); \
;     _Pragma("unroll") for (int _i = 0; _i < 2; ++_i) { \
;       __builtin_amdgcn_global_load_lds((const unsigned*)(_g + (size_t)_i * 128 * K + sg_off), (unsigned*)((char*)(P) + wid * 1024 + _i * 8192), 16, 0, 0); } } while (0)
; #define LDA(dst, b, h) _Pragma("unroll") for (int m = 0; m < 4; ++m) _Pragma("unroll") for (int k = 0; k < 2; ++k) \
;     dst[m][k] = *reinterpret_cast<const bf16x8*>((const char*)shm + aoff + (((b) * 2 + (h)) * 16384 + m * 2048 + k * 1024))
; #define LDB(dst, b, h) _Pragma("unroll") for (int n = 0; n < 2; ++n) _Pragma("unroll") for (int k = 0; k < 2; ++k) \
;     dst[n][k] = *reinterpret_cast<const bf16x8*>((const char*)shm + boff + (((b) * 2 + (h)) * 16384 + n * 2048 + k * 1024))
; #define WAIT_V(n) asm volatile("s_waitcnt vmcnt(" #n ")" ::: "memory")
; #define WAIT_L(n) asm volatile("s_waitcnt lgkmcnt(" #n ")" ::: "memory")
; #define BAR __builtin_amdgcn_s_barrier()
; #define SCHED __builtin_amdgcn_sched_barrier(0)
; template <class Epi>
; __device__ __forceinline__ void gemm_phase(const bfr* __restrict__ A, int lda, const bfr* __restrict__ Bt, int K,
;                                            int nM, int nN, const Epi& epi, bfr* shm, int wv, int nMfull, int ksplit) {
;     ...
;     for (int t = 0; t < nt - 2; t += 2) {
;       LDB(B0, 0, 0); SCHED; LDA(At, 0, 0); STAGE(SA(1, 1), Ak, brow + G_HALF, t + 1);
;       WAIT_L(8); BAR; WAIT_L(0); MMA(0, 0, At, B0); BAR; SCHED;
;       LDB(B1, 0, 1); STAGE(SB(0, 0), Bk, bcol, t + 2);
;       BAR; WAIT_L(0); MMA(0, 1, At, B1); BAR;
;       LDA(At, 0, 1); STAGE(SA(0, 0), Ak, brow, t + 2);
;       BAR; WAIT_L(0); MMA(1, 0, At, B0); BAR; SCHED;
;       STAGE(SB(0, 1), Bk, bcol + G_HALF, t + 2);
;       WAIT_V(6); BAR; MMA(1, 1, At, B1); BAR;
;       LDB(B0, 1, 0); SCHED; LDA(At, 1, 0); STAGE(SA(0, 1), Ak, brow + G_HALF, t + 2);
;       WAIT_L(8); BAR; WAIT_L(0); MMA(0, 0, At, B0); BAR; SCHED;
;       LDB(B1, 1, 1); STAGE(SB(1, 0), Bk, bcol, t + 3);
;       BAR; WAIT_L(0); MMA(0, 1, At, B1); BAR;
;       LDA(At, 1, 1); STAGE(SA(1, 0), Ak, brow, t + 3);
;       BAR; WAIT_L(0); MMA(1, 0, At, B0); BAR; SCHED;
;       STAGE(SB(1, 1), Bk, bcol + G_HALF, t + 3);
;       WAIT_V(6); BAR; MMA(1, 1, At, B1); BAR;
;     }
	v_mfma_f32_16x16x32_bf16 v[60:63], v[154:157], v[138:141], v[60:63]
	v_mfma_f32_16x16x32_bf16 v[56:59], v[154:157], v[146:149], v[56:59]
	v_mfma_f32_16x16x32_bf16 v[52:55], v[162:165], v[138:141], v[52:55]
	v_mfma_f32_16x16x32_bf16 v[48:51], v[162:165], v[146:149], v[48:51]
	v_mfma_f32_16x16x32_bf16 v[44:47], v[170:173], v[138:141], v[44:47]
	v_mfma_f32_16x16x32_bf16 v[40:43], v[170:173], v[146:149], v[40:43]
	v_mfma_f32_16x16x32_bf16 v[36:39], v[184:187], v[138:141], v[36:39]
	v_mfma_f32_16x16x32_bf16 v[32:35], v[184:187], v[146:149], v[32:35]
	v_mfma_f32_16x16x32_bf16 v[60:63], v[158:161], v[142:145], v[60:63]
	v_mfma_f32_16x16x32_bf16 v[56:59], v[158:161], v[150:153], v[56:59]
	v_mfma_f32_16x16x32_bf16 v[52:55], v[166:169], v[142:145], v[52:55]
	v_mfma_f32_16x16x32_bf16 v[48:51], v[166:169], v[150:153], v[48:51]
	v_mfma_f32_16x16x32_bf16 v[44:47], v[174:177], v[142:145], v[44:47]
	v_mfma_f32_16x16x32_bf16 v[40:43], v[174:177], v[150:153], v[40:43]
	v_mfma_f32_16x16x32_bf16 v[36:39], v[188:191], v[142:145], v[36:39]
	v_mfma_f32_16x16x32_bf16 v[32:35], v[188:191], v[150:153], v[32:35]
	v_mfma_f32_16x16x32_bf16 v[28:31], v[154:157], v[192:195], v[28:31]
	v_mfma_f32_16x16x32_bf16 v[24:27], v[154:157], v[200:203], v[24:27]
	v_mfma_f32_16x16x32_bf16 v[20:23], v[162:165], v[192:195], v[20:23]
	v_mfma_f32_16x16x32_bf16 v[16:19], v[162:165], v[200:203], v[16:19]
	v_mfma_f32_16x16x32_bf16 v[12:15], v[170:173], v[192:195], v[12:15]
	v_mfma_f32_16x16x32_bf16 v[8:11], v[170:173], v[200:203], v[8:11]
	v_mfma_f32_16x16x32_bf16 v[4:7], v[184:187], v[192:195], v[4:7]
	v_mfma_f32_16x16x32_bf16 v[0:3], v[184:187], v[200:203], v[0:3]
	v_mfma_f32_16x16x32_bf16 v[28:31], v[158:161], v[196:199], v[28:31]
	v_mfma_f32_16x16x32_bf16 v[24:27], v[158:161], v[204:207], v[24:27]
	v_mfma_f32_16x16x32_bf16 v[20:23], v[166:169], v[196:199], v[20:23]
	v_mfma_f32_16x16x32_bf16 v[16:19], v[166:169], v[204:207], v[16:19]
	v_mfma_f32_16x16x32_bf16 v[12:15], v[174:177], v[196:199], v[12:15]
	v_mfma_f32_16x16x32_bf16 v[8:11], v[174:177], v[204:207], v[8:11]
	v_mfma_f32_16x16x32_bf16 v[4:7], v[188:191], v[196:199], v[4:7]
	v_mfma_f32_16x16x32_bf16 v[0:3], v[188:191], v[204:207], v[0:3]
	s_barrier
	ds_read_b128 v[138:141], v179 offset:32768
	ds_read_b128 v[142:145], v179 offset:33792
	ds_read_b128 v[146:149], v179 offset:34816
	ds_read_b128 v[150:153], v179 offset:35840
	ds_read_b128 v[154:157], v178 offset:32768
	ds_read_b128 v[158:161], v178 offset:33792
	ds_read_b128 v[162:165], v178 offset:34816
	ds_read_b128 v[166:169], v178 offset:35840
	ds_read_b128 v[170:173], v178 offset:36864
	ds_read_b128 v[174:177], v178 offset:37888
	ds_read_b128 v[184:187], v178 offset:38912
	ds_read_b128 v[188:191], v178 offset:39936
	ds_read_b128 v[192:195], v179 offset:49152
	ds_read_b128 v[196:199], v179 offset:50176
	ds_read_b128 v[200:203], v179 offset:51200
	ds_read_b128 v[204:207], v179 offset:52224
	s_mov_b32 m0, s59
	s_mov_b64 s[40:41], 0xb0100
	v_lshl_add_u64 v[218:219], v[208:209], 0, s[40:41]
	global_load_lds_dwordx4 v[218:219], off
	s_mov_b32 m0, s82
	s_mov_b64 s[40:41], 0x108100
	v_lshl_add_u64 v[214:215], v[208:209], 0, s[40:41]
	global_load_lds_dwordx4 v[214:215], off
	s_waitcnt lgkmcnt(0)
	s_barrier
	v_mfma_f32_16x16x32_bf16 v[124:127], v[154:157], v[138:141], v[124:127]
	v_mfma_f32_16x16x32_bf16 v[120:123], v[154:157], v[146:149], v[120:123]
	v_mfma_f32_16x16x32_bf16 v[116:119], v[162:165], v[138:141], v[116:119]
	v_mfma_f32_16x16x32_bf16 v[112:115], v[162:165], v[146:149], v[112:115]
	v_mfma_f32_16x16x32_bf16 v[108:111], v[170:173], v[138:141], v[108:111]
	v_mfma_f32_16x16x32_bf16 v[104:107], v[170:173], v[146:149], v[104:107]
	v_mfma_f32_16x16x32_bf16 v[100:103], v[184:187], v[138:141], v[100:103]
	v_mfma_f32_16x16x32_bf16 v[96:99], v[184:187], v[146:149], v[96:99]
	v_mfma_f32_16x16x32_bf16 v[124:127], v[158:161], v[142:145], v[124:127]
	v_mfma_f32_16x16x32_bf16 v[120:123], v[158:161], v[150:153], v[120:123]
	v_mfma_f32_16x16x32_bf16 v[116:119], v[166:169], v[142:145], v[116:119]
	v_mfma_f32_16x16x32_bf16 v[112:115], v[166:169], v[150:153], v[112:115]
	v_mfma_f32_16x16x32_bf16 v[108:111], v[174:177], v[142:145], v[108:111]
	v_mfma_f32_16x16x32_bf16 v[104:107], v[174:177], v[150:153], v[104:107]
	v_mfma_f32_16x16x32_bf16 v[100:103], v[188:191], v[142:145], v[100:103]
	v_mfma_f32_16x16x32_bf16 v[96:99], v[188:191], v[150:153], v[96:99]
	v_mfma_f32_16x16x32_bf16 v[92:95], v[154:157], v[192:195], v[92:95]
	v_mfma_f32_16x16x32_bf16 v[88:91], v[154:157], v[200:203], v[88:91]
	v_mfma_f32_16x16x32_bf16 v[84:87], v[162:165], v[192:195], v[84:87]
	v_mfma_f32_16x16x32_bf16 v[80:83], v[162:165], v[200:203], v[80:83]
	v_mfma_f32_16x16x32_bf16 v[76:79], v[170:173], v[192:195], v[76:79]
	v_mfma_f32_16x16x32_bf16 v[72:75], v[170:173], v[200:203], v[72:75]
	v_mfma_f32_16x16x32_bf16 v[68:71], v[184:187], v[192:195], v[68:71]
	v_mfma_f32_16x16x32_bf16 v[64:67], v[184:187], v[200:203], v[64:67]
	v_mfma_f32_16x16x32_bf16 v[92:95], v[158:161], v[196:199], v[92:95]
	v_mfma_f32_16x16x32_bf16 v[88:91], v[158:161], v[204:207], v[88:91]
	v_mfma_f32_16x16x32_bf16 v[84:87], v[166:169], v[196:199], v[84:87]
	v_mfma_f32_16x16x32_bf16 v[80:83], v[166:169], v[204:207], v[80:83]
	v_mfma_f32_16x16x32_bf16 v[76:79], v[174:177], v[196:199], v[76:79]
	v_mfma_f32_16x16x32_bf16 v[72:75], v[174:177], v[204:207], v[72:75]
	v_mfma_f32_16x16x32_bf16 v[68:71], v[188:191], v[196:199], v[68:71]
	v_mfma_f32_16x16x32_bf16 v[64:67], v[188:191], v[204:207], v[64:67]
	s_barrier
; #define STAGE(P, BASE, br, kt) do { const char* _g = (const char*)((BASE) + (size_t)(br) * K + (size_t)(kt) * G_BK); \
;     _Pragma("unroll") for (int _i = 0; _i < 2; ++_i) { \
;       __builtin_amdgcn_global_load_lds((const unsigned*)(_g + (size_t)_i * 128 * K + sg_off), (unsigned*)((char*)(P) + wid * 1024 + _i * 8192), 16, 0, 0); } } while (0)
; #define LDA(dst, b, h) _Pragma("unroll") for (int m = 0; m < 4; ++m) _Pragma("unroll") for (int k = 0; k < 2; ++k) \
;     dst[m][k] = *reinterpret_cast<const bf16x8*>((const char*)shm + aoff + (((b) * 2 + (h)) * 16384 + m * 2048 + k * 1024))
; #define LDB(dst, b, h) _Pragma("unroll") for (int n = 0; n < 2; ++n) _Pragma("unroll") for (int k = 0; k < 2; ++k) \
;     dst[n][k] = *reinterpret_cast<const bf16x8*>((const char*)shm + boff + (((b) * 2 + (h)) * 16384 + n * 2048 + k * 1024))
; #define WAIT_V(n) asm volatile("s_waitcnt vmcnt(" #n ")" ::: "memory")
; #define WAIT_L(n) asm volatile("s_waitcnt lgkmcnt(" #n ")" ::: "memory")
; #define BAR __builtin_amdgcn_s_barrier()
; #define SCHED __builtin_amdgcn_sched_barrier(0)
; template <class Epi>
; __device__ __forceinline__ void gemm_phase(const bfr* __restrict__ A, int lda, const bfr* __restrict__ Bt, int K,
;                                            int nM, int nN, const Epi& epi, bfr* shm, int wv, int nMfull, int ksplit) {
;     ...
;     for (int t = 0; t < nt - 2; t += 2) {
;       LDB(B0, 0, 0); SCHED; LDA(At, 0, 0); STAGE(SA(1, 1), Ak, brow + G_HALF, t + 1);
;       WAIT_L(8); BAR; WAIT_L(0); MMA(0, 0, At, B0); BAR; SCHED;
;       LDB(B1, 0, 1); STAGE(SB(0, 0), Bk, bcol, t + 2);
;       BAR; WAIT_L(0); MMA(0, 1, At, B1); BAR;
;       LDA(At, 0, 1); STAGE(SA(0, 0), Ak, brow, t + 2);
;       BAR; WAIT_L(0); MMA(1, 0, At, B0); BAR; SCHED;
;       STAGE(SB(0, 1), Bk, bcol + G_HALF, t + 2);
;       WAIT_V(6); BAR; MMA(1, 1, At, B1); BAR;
;       LDB(B0, 1, 0); SCHED; LDA(At, 1, 0); STAGE(SA(0, 1), Ak, brow + G_HALF, t + 2);
;       WAIT_L(8); BAR; WAIT_L(0); MMA(0, 0, At, B0); BAR; SCHED;
;       LDB(B1, 1, 1); STAGE(SB(1, 0), Bk, bcol, t + 3);
;       BAR; WAIT_L(0); MMA(0, 1, At, B1); BAR;
;       LDA(At, 1, 1); STAGE(SA(1, 0), Ak, brow, t + 3);
;       BAR; WAIT_L(0); MMA(1, 0, At, B0); BAR; SCHED;
;       STAGE(SB(1, 1), Bk, bcol + G_HALF, t + 3);
;       WAIT_V(6); BAR; MMA(1, 1, At, B1); BAR;
;     }
	ds_read_b128 v[154:157], v178 offset:49152
	ds_read_b128 v[158:161], v178 offset:50176
	ds_read_b128 v[162:165], v178 offset:51200
	ds_read_b128 v[166:169], v178 offset:52224
	ds_read_b128 v[170:173], v178 offset:53248
	ds_read_b128 v[174:177], v178 offset:54272
	ds_read_b128 v[184:187], v178 offset:55296
	ds_read_b128 v[188:191], v178 offset:56320
	s_mov_b32 m0, s83
	s_mov_b64 s[40:41], 0x580180
	v_lshl_add_u64 v[216:217], v[210:211], 0, s[40:41]
	global_load_lds_dwordx4 v[216:217], off
	s_mov_b32 m0, s84
	s_mov_b64 s[40:41], 0x5d8180
	v_lshl_add_u64 v[218:219], v[210:211], 0, s[40:41]
	global_load_lds_dwordx4 v[218:219], off
	s_mov_b32 m0, s85
	s_mov_b64 s[40:41], 0x180
	v_lshl_add_u64 v[214:215], v[208:209], 0, s[40:41]
	global_load_lds_dwordx4 v[214:215], off
	s_mov_b32 m0, s90
	s_mov_b64 s[40:41], 0x58180
	v_lshl_add_u64 v[216:217], v[208:209], 0, s[40:41]
	global_load_lds_dwordx4 v[216:217], off
	s_mov_b32 m0, s91
	s_mov_b64 s[40:41], 0x630180
	v_lshl_add_u64 v[218:219], v[210:211], 0, s[40:41]
	global_load_lds_dwordx4 v[218:219], off
	s_mov_b32 m0, s92
	s_mov_b64 s[40:41], 0x688180
	v_lshl_add_u64 v[214:215], v[210:211], 0, s[40:41]
	global_load_lds_dwordx4 v[214:215], off
	s_waitcnt vmcnt(6)
	s_waitcnt lgkmcnt(0)
	s_barrier
	v_mfma_f32_16x16x32_bf16 v[60:63], v[154:157], v[138:141], v[60:63]
	v_mfma_f32_16x16x32_bf16 v[56:59], v[154:157], v[146:149], v[56:59]
	v_mfma_f32_16x16x32_bf16 v[52:55], v[162:165], v[138:141], v[52:55]
	v_mfma_f32_16x16x32_bf16 v[48:51], v[162:165], v[146:149], v[48:51]
	v_mfma_f32_16x16x32_bf16 v[44:47], v[170:173], v[138:141], v[44:47]
	v_mfma_f32_16x16x32_bf16 v[40:43], v[170:173], v[146:149], v[40:43]
	v_mfma_f32_16x16x32_bf16 v[36:39], v[184:187], v[138:141], v[36:39]
	v_mfma_f32_16x16x32_bf16 v[32:35], v[184:187], v[146:149], v[32:35]
	v_mfma_f32_16x16x32_bf16 v[60:63], v[158:161], v[142:145], v[60:63]
	v_mfma_f32_16x16x32_bf16 v[56:59], v[158:161], v[150:153], v[56:59]
	v_mfma_f32_16x16x32_bf16 v[52:55], v[166:169], v[142:145], v[52:55]
	v_mfma_f32_16x16x32_bf16 v[48:51], v[166:169], v[150:153], v[48:51]
	v_mfma_f32_16x16x32_bf16 v[44:47], v[174:177], v[142:145], v[44:47]
	v_mfma_f32_16x16x32_bf16 v[40:43], v[174:177], v[150:153], v[40:43]
	v_mfma_f32_16x16x32_bf16 v[36:39], v[188:191], v[142:145], v[36:39]
	v_mfma_f32_16x16x32_bf16 v[32:35], v[188:191], v[150:153], v[32:35]
	v_mfma_f32_16x16x32_bf16 v[28:31], v[154:157], v[192:195], v[28:31]
	v_mfma_f32_16x16x32_bf16 v[24:27], v[154:157], v[200:203], v[24:27]
	v_mfma_f32_16x16x32_bf16 v[20:23], v[162:165], v[192:195], v[20:23]
	v_mfma_f32_16x16x32_bf16 v[16:19], v[162:165], v[200:203], v[16:19]
	v_mfma_f32_16x16x32_bf16 v[12:15], v[170:173], v[192:195], v[12:15]
	v_mfma_f32_16x16x32_bf16 v[8:11], v[170:173], v[200:203], v[8:11]
	v_mfma_f32_16x16x32_bf16 v[4:7], v[184:187], v[192:195], v[4:7]
	v_mfma_f32_16x16x32_bf16 v[0:3], v[184:187], v[200:203], v[0:3]
	v_mfma_f32_16x16x32_bf16 v[28:31], v[158:161], v[196:199], v[28:31]
	v_mfma_f32_16x16x32_bf16 v[24:27], v[158:161], v[204:207], v[24:27]
	v_mfma_f32_16x16x32_bf16 v[20:23], v[166:169], v[196:199], v[20:23]
	v_mfma_f32_16x16x32_bf16 v[16:19], v[166:169], v[204:207], v[16:19]
	v_mfma_f32_16x16x32_bf16 v[12:15], v[174:177], v[196:199], v[12:15]
	v_mfma_f32_16x16x32_bf16 v[8:11], v[174:177], v[204:207], v[8:11]
	v_mfma_f32_16x16x32_bf16 v[4:7], v[188:191], v[196:199], v[4:7]
	v_mfma_f32_16x16x32_bf16 v[0:3], v[188:191], v[204:207], v[0:3]
	s_add_i32 s37, s37, 2
	s_add_u32 s38, s38, 0x100
	s_addc_u32 s39, s39, 0
	s_add_u32 s34, s34, 0x100
	s_addc_u32 s35, s35, 0
	s_cmp_ge_i32 s37, s2
	s_barrier
	s_cbranch_scc0 .LBB0_729

; #define STAGE(P, BASE, br, kt) do { const char* _g = (const char*)((BASE) + (size_t)(br) * K + (size_t)(kt) * G_BK); \
;     _Pragma("unroll") for (int _i = 0; _i < 2; ++_i) { \
;       __builtin_amdgcn_global_load_lds((const unsigned*)(_g + (size_t)_i * 128 * K + sg_off), (unsigned*)((char*)(P) + wid * 1024 + _i * 8192), 16, 0, 0); } } while (0)
; #define LDA(dst, b, h) _Pragma("unroll") for (int m = 0; m < 4; ++m) _Pragma("unroll") for (int k = 0; k < 2; ++k) \
;     dst[m][k] = *reinterpret_cast<const bf16x8*>((const char*)shm + aoff + (((b) * 2 + (h)) * 16384 + m * 2048 + k * 1024))
; #define LDB(dst, b, h) _Pragma("unroll") for (int n = 0; n < 2; ++n) _Pragma("unroll") for (int k = 0; k < 2; ++k) \
;     dst[n][k] = *reinterpret_cast<const bf16x8*>((const char*)shm + boff + (((b) * 2 + (h)) * 16384 + n * 2048 + k * 1024))
; #define WAIT_V(n) asm volatile("s_waitcnt vmcnt(" #n ")" ::: "memory")
; #define WAIT_L(n) asm volatile("s_waitcnt lgkmcnt(" #n ")" ::: "memory")
; #define BAR __builtin_amdgcn_s_barrier()
; #define SCHED __builtin_amdgcn_sched_barrier(0)
; template <class Epi>
; __device__ __forceinline__ void gemm_phase(const bfr* __restrict__ A, int lda, const bfr* __restrict__ Bt, int K,
;                                            int nM, int nN, const Epi& epi, bfr* shm, int wv, int nMfull, int ksplit) {
;     ...
;     for (int t = 0; t < nt - 2; t += 2) {
;       LDB(B0, 0, 0); SCHED; LDA(At, 0, 0); STAGE(SA(1, 1), Ak, brow + G_HALF, t + 1);
;       WAIT_L(8); BAR; WAIT_L(0); MMA(0, 0, At, B0); BAR; SCHED;
;       LDB(B1, 0, 1); STAGE(SB(0, 0), Bk, bcol, t + 2);
;       BAR; WAIT_L(0); MMA(0, 1, At, B1); BAR;
;       LDA(At, 0, 1); STAGE(SA(0, 0), Ak, brow, t + 2);
;       BAR; WAIT_L(0); MMA(1, 0, At, B0); BAR; SCHED;
;       STAGE(SB(0, 1), Bk, bcol + G_HALF, t + 2);
;       WAIT_V(6); BAR; MMA(1, 1, At, B1); BAR;
;       LDB(B0, 1, 0); SCHED; LDA(At, 1, 0); STAGE(SA(0, 1), Ak, brow + G_HALF, t + 2);
;       WAIT_L(8); BAR; WAIT_L(0); MMA(0, 0, At, B0); BAR; SCHED;
;       LDB(B1, 1, 1); STAGE(SB(1, 0), Bk, bcol, t + 3);
;       BAR; WAIT_L(0); MMA(0, 1, At, B1); BAR;
;       LDA(At, 1, 1); STAGE(SA(1, 0), Ak, brow, t + 3);
;       BAR; WAIT_L(0); MMA(1, 0, At, B0); BAR; SCHED;
;       STAGE(SB(1, 1), Bk, bcol + G_HALF, t + 3);
;       WAIT_V(6); BAR; MMA(1, 1, At, B1); BAR;
;     }
.LBB0_879:
	ds_read_b128 v[138:141], v169
	ds_read_b128 v[142:145], v169 offset:1024
	ds_read_b128 v[146:149], v169 offset:2048
	ds_read_b128 v[150:153], v169 offset:3072
	ds_read_b128 v[154:157], v129
	ds_read_b128 v[158:161], v129 offset:1024
	ds_read_b128 v[162:165], v129 offset:2048
	ds_read_b128 v[172:175], v129 offset:3072
	ds_read_b128 v[180:183], v129 offset:4096
	ds_read_b128 v[184:187], v129 offset:5120
	ds_read_b128 v[188:191], v129 offset:6144
	ds_read_b128 v[192:195], v129 offset:7168
	ds_read_b128 v[196:199], v169 offset:16384
	ds_read_b128 v[200:203], v169 offset:17408
	ds_read_b128 v[204:207], v169 offset:18432
	ds_read_b128 v[208:211], v169 offset:19456
	v_lshl_add_u64 v[166:167], s[22:23], 0, v[136:137]
	v_lshl_add_u64 v[176:177], s[4:5], 0, v[136:137]
	s_mov_b32 m0, s50
	s_mov_b64 s[26:27], 0x40080
	v_lshl_add_u64 v[214:215], v[166:167], 0, s[26:27]
	global_load_lds_dwordx4 v[214:215], off
	s_mov_b32 m0, s51
	s_mov_b64 s[26:27], 0x60080
	v_lshl_add_u64 v[216:217], v[166:167], 0, s[26:27]
	global_load_lds_dwordx4 v[216:217], off
	s_waitcnt lgkmcnt(0)
	s_barrier
	v_mfma_f32_16x16x32_bf16 v[124:127], v[154:157], v[138:141], v[124:127]
	v_mfma_f32_16x16x32_bf16 v[120:123], v[154:157], v[146:149], v[120:123]
	v_mfma_f32_16x16x32_bf16 v[116:119], v[162:165], v[138:141], v[116:119]
	v_mfma_f32_16x16x32_bf16 v[112:115], v[162:165], v[146:149], v[112:115]
	v_mfma_f32_16x16x32_bf16 v[108:111], v[180:183], v[138:141], v[108:111]
	v_mfma_f32_16x16x32_bf16 v[104:107], v[180:183], v[146:149], v[104:107]
	v_mfma_f32_16x16x32_bf16 v[100:103], v[188:191], v[138:141], v[100:103]
	v_mfma_f32_16x16x32_bf16 v[96:99], v[188:191], v[146:149], v[96:99]
	v_mfma_f32_16x16x32_bf16 v[124:127], v[158:161], v[142:145], v[124:127]
	v_mfma_f32_16x16x32_bf16 v[120:123], v[158:161], v[150:153], v[120:123]
	v_mfma_f32_16x16x32_bf16 v[116:119], v[172:175], v[142:145], v[116:119]
	v_mfma_f32_16x16x32_bf16 v[112:115], v[172:175], v[150:153], v[112:115]
	v_mfma_f32_16x16x32_bf16 v[108:111], v[184:187], v[142:145], v[108:111]
	v_mfma_f32_16x16x32_bf16 v[104:107], v[184:187], v[150:153], v[104:107]
	v_mfma_f32_16x16x32_bf16 v[100:103], v[192:195], v[142:145], v[100:103]
	v_mfma_f32_16x16x32_bf16 v[96:99], v[192:195], v[150:153], v[96:99]
	v_mfma_f32_16x16x32_bf16 v[92:95], v[154:157], v[196:199], v[92:95]
	v_mfma_f32_16x16x32_bf16 v[88:91], v[154:157], v[204:207], v[88:91]
	v_mfma_f32_16x16x32_bf16 v[84:87], v[162:165], v[196:199], v[84:87]
	v_mfma_f32_16x16x32_bf16 v[80:83], v[162:165], v[204:207], v[80:83]
	v_mfma_f32_16x16x32_bf16 v[76:79], v[180:183], v[196:199], v[76:79]
	v_mfma_f32_16x16x32_bf16 v[72:75], v[180:183], v[204:207], v[72:75]
	v_mfma_f32_16x16x32_bf16 v[68:71], v[188:191], v[196:199], v[68:71]
	v_mfma_f32_16x16x32_bf16 v[64:67], v[188:191], v[204:207], v[64:67]
	v_mfma_f32_16x16x32_bf16 v[92:95], v[158:161], v[200:203], v[92:95]
	v_mfma_f32_16x16x32_bf16 v[88:91], v[158:161], v[208:211], v[88:91]
	v_mfma_f32_16x16x32_bf16 v[84:87], v[172:175], v[200:203], v[84:87]
	v_mfma_f32_16x16x32_bf16 v[80:83], v[172:175], v[208:211], v[80:83]
	v_mfma_f32_16x16x32_bf16 v[76:79], v[184:187], v[200:203], v[76:79]
	v_mfma_f32_16x16x32_bf16 v[72:75], v[184:187], v[208:211], v[72:75]
	v_mfma_f32_16x16x32_bf16 v[68:71], v[192:195], v[200:203], v[68:71]
	v_mfma_f32_16x16x32_bf16 v[64:67], v[192:195], v[208:211], v[64:67]
	s_barrier
	ds_read_b128 v[154:157], v129 offset:16384
	ds_read_b128 v[158:161], v129 offset:17408
	ds_read_b128 v[162:165], v129 offset:18432
	ds_read_b128 v[172:175], v129 offset:19456
	ds_read_b128 v[180:183], v129 offset:20480
	ds_read_b128 v[184:187], v129 offset:21504
	ds_read_b128 v[188:191], v129 offset:22528
	ds_read_b128 v[192:195], v129 offset:23552
	s_mov_b32 m0, s37
	s_mov_b64 s[26:27], 0x1600100
	v_lshl_add_u64 v[218:219], v[176:177], 0, s[26:27]
	global_load_lds_dwordx4 v[218:219], off
	s_mov_b32 m0, s38
	s_mov_b64 s[26:27], 0x1620100
	v_lshl_add_u64 v[214:215], v[176:177], 0, s[26:27]
	global_load_lds_dwordx4 v[214:215], off
	s_mov_b32 m0, s36
	s_mov_b64 s[26:27], 0x100
	v_lshl_add_u64 v[216:217], v[166:167], 0, s[26:27]
	global_load_lds_dwordx4 v[216:217], off
	s_mov_b32 m0, s39
	s_mov_b64 s[26:27], 0x20100
	v_lshl_add_u64 v[218:219], v[166:167], 0, s[26:27]
	global_load_lds_dwordx4 v[218:219], off
	s_mov_b32 m0, s40
	s_mov_b64 s[26:27], 0x1640100
	v_lshl_add_u64 v[214:215], v[176:177], 0, s[26:27]
	global_load_lds_dwordx4 v[214:215], off
	s_mov_b32 m0, s41
	s_mov_b64 s[26:27], 0x1660100
	v_lshl_add_u64 v[216:217], v[176:177], 0, s[26:27]
	global_load_lds_dwordx4 v[216:217], off
	s_waitcnt vmcnt(6)
	s_waitcnt lgkmcnt(0)
	s_barrier
; #define STAGE(P, BASE, br, kt) do { const char* _g = (const char*)((BASE) + (size_t)(br) * K + (size_t)(kt) * G_BK); \
;     _Pragma("unroll") for (int _i = 0; _i < 2; ++_i) { \
;       __builtin_amdgcn_global_load_lds((const unsigned*)(_g + (size_t)_i * 128 * K + sg_off), (unsigned*)((char*)(P) + wid * 1024 + _i * 8192), 16, 0, 0); } } while (0)
; #define LDA(dst, b, h) _Pragma("unroll") for (int m = 0; m < 4; ++m) _Pragma("unroll") for (int k = 0; k < 2; ++k) \
;     dst[m][k] = *reinterpret_cast<const bf16x8*>((const char*)shm + aoff + (((b) * 2 + (h)) * 16384 + m * 2048 + k * 1024))
; #define LDB(dst, b, h) _Pragma("unroll") for (int n = 0; n < 2; ++n) _Pragma("unroll") for (int k = 0; k < 2; ++k) \
;     dst[n][k] = *reinterpret_cast<const bf16x8*>((const char*)shm + boff + (((b) * 2 + (h)) * 16384 + n * 2048 + k * 1024))
; #define WAIT_V(n) asm volatile("s_waitcnt vmcnt(" #n ")" ::: "memory")
; #define WAIT_L(n) asm volatile("s_waitcnt lgkmcnt(" #n ")" ::: "memory")
; #define BAR __builtin_amdgcn_s_barrier()
; #define SCHED __builtin_amdgcn_sched_barrier(0)
; template <class Epi>
; __device__ __forceinline__ void gemm_phase(const bfr* __restrict__ A, int lda, const bfr* __restrict__ Bt, int K,
;                                            int nM, int nN, const Epi& epi, bfr* shm, int wv, int nMfull, int ksplit) {
;     ...
;     for (int t = 0; t < nt - 2; t += 2) {
;       LDB(B0, 0, 0); SCHED; LDA(At, 0, 0); STAGE(SA(1, 1), Ak, brow + G_HALF, t + 1);
;       WAIT_L(8); BAR; WAIT_L(0); MMA(0, 0, At, B0); BAR; SCHED;
;       LDB(B1, 0, 1); STAGE(SB(0, 0), Bk, bcol, t + 2);
;       BAR; WAIT_L(0); MMA(0, 1, At, B1); BAR;
;       LDA(At, 0, 1); STAGE(SA(0, 0), Ak, brow, t + 2);
;       BAR; WAIT_L(0); MMA(1, 0, At, B0); BAR; SCHED;
;       STAGE(SB(0, 1), Bk, bcol + G_HALF, t + 2);
;       WAIT_V(6); BAR; MMA(1, 1, At, B1); BAR;
;       LDB(B0, 1, 0); SCHED; LDA(At, 1, 0); STAGE(SA(0, 1), Ak, brow + G_HALF, t + 2);
;       WAIT_L(8); BAR; WAIT_L(0); MMA(0, 0, At, B0); BAR; SCHED;
;       LDB(B1, 1, 1); STAGE(SB(1, 0), Bk, bcol, t + 3);
;       BAR; WAIT_L(0); MMA(0, 1, At, B1); BAR;
;       LDA(At, 1, 1); STAGE(SA(1, 0), Ak, brow, t + 3);
;       BAR; WAIT_L(0); MMA(1, 0, At, B0); BAR; SCHED;
;       STAGE(SB(1, 1), Bk, bcol + G_HALF, t + 3);
;       WAIT_V(6); BAR; MMA(1, 1, At, B1); BAR;
;     }
	v_mfma_f32_16x16x32_bf16 v[60:63], v[154:157], v[138:141], v[60:63]
	v_mfma_f32_16x16x32_bf16 v[56:59], v[154:157], v[146:149], v[56:59]
	v_mfma_f32_16x16x32_bf16 v[52:55], v[162:165], v[138:141], v[52:55]
	v_mfma_f32_16x16x32_bf16 v[48:51], v[162:165], v[146:149], v[48:51]
	v_mfma_f32_16x16x32_bf16 v[44:47], v[180:183], v[138:141], v[44:47]
	v_mfma_f32_16x16x32_bf16 v[40:43], v[180:183], v[146:149], v[40:43]
	v_mfma_f32_16x16x32_bf16 v[36:39], v[188:191], v[138:141], v[36:39]
	v_mfma_f32_16x16x32_bf16 v[32:35], v[188:191], v[146:149], v[32:35]
	v_mfma_f32_16x16x32_bf16 v[60:63], v[158:161], v[142:145], v[60:63]
	v_mfma_f32_16x16x32_bf16 v[56:59], v[158:161], v[150:153], v[56:59]
	v_mfma_f32_16x16x32_bf16 v[52:55], v[172:175], v[142:145], v[52:55]
	v_mfma_f32_16x16x32_bf16 v[48:51], v[172:175], v[150:153], v[48:51]
	v_mfma_f32_16x16x32_bf16 v[44:47], v[184:187], v[142:145], v[44:47]
	v_mfma_f32_16x16x32_bf16 v[40:43], v[184:187], v[150:153], v[40:43]
	v_mfma_f32_16x16x32_bf16 v[36:39], v[192:195], v[142:145], v[36:39]
	v_mfma_f32_16x16x32_bf16 v[32:35], v[192:195], v[150:153], v[32:35]
	v_mfma_f32_16x16x32_bf16 v[28:31], v[154:157], v[196:199], v[28:31]
	v_mfma_f32_16x16x32_bf16 v[24:27], v[154:157], v[204:207], v[24:27]
	v_mfma_f32_16x16x32_bf16 v[20:23], v[162:165], v[196:199], v[20:23]
	v_mfma_f32_16x16x32_bf16 v[16:19], v[162:165], v[204:207], v[16:19]
	v_mfma_f32_16x16x32_bf16 v[12:15], v[180:183], v[196:199], v[12:15]
	v_mfma_f32_16x16x32_bf16 v[8:11], v[180:183], v[204:207], v[8:11]
	v_mfma_f32_16x16x32_bf16 v[4:7], v[188:191], v[196:199], v[4:7]
	v_mfma_f32_16x16x32_bf16 v[0:3], v[188:191], v[204:207], v[0:3]
	v_mfma_f32_16x16x32_bf16 v[28:31], v[158:161], v[200:203], v[28:31]
	v_mfma_f32_16x16x32_bf16 v[24:27], v[158:161], v[208:211], v[24:27]
	v_mfma_f32_16x16x32_bf16 v[20:23], v[172:175], v[200:203], v[20:23]
	v_mfma_f32_16x16x32_bf16 v[16:19], v[172:175], v[208:211], v[16:19]
	v_mfma_f32_16x16x32_bf16 v[12:15], v[184:187], v[200:203], v[12:15]
	v_mfma_f32_16x16x32_bf16 v[8:11], v[184:187], v[208:211], v[8:11]
	v_mfma_f32_16x16x32_bf16 v[4:7], v[192:195], v[200:203], v[4:7]
	v_mfma_f32_16x16x32_bf16 v[0:3], v[192:195], v[208:211], v[0:3]
	s_barrier
	ds_read_b128 v[138:141], v169 offset:32768
	ds_read_b128 v[142:145], v169 offset:33792
	ds_read_b128 v[146:149], v169 offset:34816
	ds_read_b128 v[150:153], v169 offset:35840
	ds_read_b128 v[154:157], v129 offset:32768
	ds_read_b128 v[158:161], v129 offset:33792
	ds_read_b128 v[162:165], v129 offset:34816
	ds_read_b128 v[172:175], v129 offset:35840
	ds_read_b128 v[180:183], v129 offset:36864
	ds_read_b128 v[184:187], v129 offset:37888
	ds_read_b128 v[188:191], v129 offset:38912
	ds_read_b128 v[192:195], v129 offset:39936
	ds_read_b128 v[196:199], v169 offset:49152
	ds_read_b128 v[200:203], v169 offset:50176
	ds_read_b128 v[204:207], v169 offset:51200
	ds_read_b128 v[208:211], v169 offset:52224
	s_mov_b32 m0, s42
	s_mov_b64 s[26:27], 0x40100
	v_lshl_add_u64 v[218:219], v[166:167], 0, s[26:27]
	global_load_lds_dwordx4 v[218:219], off
	s_mov_b32 m0, s43
	s_mov_b64 s[26:27], 0x60100
	v_lshl_add_u64 v[214:215], v[166:167], 0, s[26:27]
	global_load_lds_dwordx4 v[214:215], off
	s_waitcnt lgkmcnt(0)
	s_barrier
	v_mfma_f32_16x16x32_bf16 v[124:127], v[154:157], v[138:141], v[124:127]
	v_mfma_f32_16x16x32_bf16 v[120:123], v[154:157], v[146:149], v[120:123]
	v_mfma_f32_16x16x32_bf16 v[116:119], v[162:165], v[138:141], v[116:119]
	v_mfma_f32_16x16x32_bf16 v[112:115], v[162:165], v[146:149], v[112:115]
	v_mfma_f32_16x16x32_bf16 v[108:111], v[180:183], v[138:141], v[108:111]
	v_mfma_f32_16x16x32_bf16 v[104:107], v[180:183], v[146:149], v[104:107]
	v_mfma_f32_16x16x32_bf16 v[100:103], v[188:191], v[138:141], v[100:103]
	v_mfma_f32_16x16x32_bf16 v[96:99], v[188:191], v[146:149], v[96:99]
	v_mfma_f32_16x16x32_bf16 v[124:127], v[158:161], v[142:145], v[124:127]
	v_mfma_f32_16x16x32_bf16 v[120:123], v[158:161], v[150:153], v[120:123]
	v_mfma_f32_16x16x32_bf16 v[116:119], v[172:175], v[142:145], v[116:119]
	v_mfma_f32_16x16x32_bf16 v[112:115], v[172:175], v[150:153], v[112:115]
	v_mfma_f32_16x16x32_bf16 v[108:111], v[184:187], v[142:145], v[108:111]
	v_mfma_f32_16x16x32_bf16 v[104:107], v[184:187], v[150:153], v[104:107]
	v_mfma_f32_16x16x32_bf16 v[100:103], v[192:195], v[142:145], v[100:103]
	v_mfma_f32_16x16x32_bf16 v[96:99], v[192:195], v[150:153], v[96:99]
	v_mfma_f32_16x16x32_bf16 v[92:95], v[154:157], v[196:199], v[92:95]
	v_mfma_f32_16x16x32_bf16 v[88:91], v[154:157], v[204:207], v[88:91]
	v_mfma_f32_16x16x32_bf16 v[84:87], v[162:165], v[196:199], v[84:87]
	v_mfma_f32_16x16x32_bf16 v[80:83], v[162:165], v[204:207], v[80:83]
	v_mfma_f32_16x16x32_bf16 v[76:79], v[180:183], v[196:199], v[76:79]
	v_mfma_f32_16x16x32_bf16 v[72:75], v[180:183], v[204:207], v[72:75]
	v_mfma_f32_16x16x32_bf16 v[68:71], v[188:191], v[196:199], v[68:71]
	v_mfma_f32_16x16x32_bf16 v[64:67], v[188:191], v[204:207], v[64:67]
	v_mfma_f32_16x16x32_bf16 v[92:95], v[158:161], v[200:203], v[92:95]
	v_mfma_f32_16x16x32_bf16 v[88:91], v[158:161], v[208:211], v[88:91]
	v_mfma_f32_16x16x32_bf16 v[84:87], v[172:175], v[200:203], v[84:87]
	v_mfma_f32_16x16x32_bf16 v[80:83], v[172:175], v[208:211], v[80:83]
	v_mfma_f32_16x16x32_bf16 v[76:79], v[184:187], v[200:203], v[76:79]
	v_mfma_f32_16x16x32_bf16 v[72:75], v[184:187], v[208:211], v[72:75]
	v_mfma_f32_16x16x32_bf16 v[68:71], v[192:195], v[200:203], v[68:71]
	v_mfma_f32_16x16x32_bf16 v[64:67], v[192:195], v[208:211], v[64:67]
	s_barrier
; #define STAGE(P, BASE, br, kt) do { const char* _g = (const char*)((BASE) + (size_t)(br) * K + (size_t)(kt) * G_BK); \
;     _Pragma("unroll") for (int _i = 0; _i < 2; ++_i) { \
;       __builtin_amdgcn_global_load_lds((const unsigned*)(_g + (size_t)_i * 128 * K + sg_off), (unsigned*)((char*)(P) + wid * 1024 + _i * 8192), 16, 0, 0); } } while (0)
; #define LDA(dst, b, h) _Pragma("unroll") for (int m = 0; m < 4; ++m) _Pragma("unroll") for (int k = 0; k < 2; ++k) \
;     dst[m][k] = *reinterpret_cast<const bf16x8*>((const char*)shm + aoff + (((b) * 2 + (h)) * 16384 + m * 2048 + k * 1024))
; #define LDB(dst, b, h) _Pragma("unroll") for (int n = 0; n < 2; ++n) _Pragma("unroll") for (int k = 0; k < 2; ++k) \
;     dst[n][k] = *reinterpret_cast<const bf16x8*>((const char*)shm + boff + (((b) * 2 + (h)) * 16384 + n * 2048 + k * 1024))
; #define WAIT_V(n) asm volatile("s_waitcnt vmcnt(" #n ")" ::: "memory")
; #define WAIT_L(n) asm volatile("s_waitcnt lgkmcnt(" #n ")" ::: "memory")
; #define BAR __builtin_amdgcn_s_barrier()
; #define SCHED __builtin_amdgcn_sched_barrier(0)
; template <class Epi>
; __device__ __forceinline__ void gemm_phase(const bfr* __restrict__ A, int lda, const bfr* __restrict__ Bt, int K,
;                                            int nM, int nN, const Epi& epi, bfr* shm, int wv, int nMfull, int ksplit) {
;     ...
;     for (int t = 0; t < nt - 2; t += 2) {
;       LDB(B0, 0, 0); SCHED; LDA(At, 0, 0); STAGE(SA(1, 1), Ak, brow + G_HALF, t + 1);
;       WAIT_L(8); BAR; WAIT_L(0); MMA(0, 0, At, B0); BAR; SCHED;
;       LDB(B1, 0, 1); STAGE(SB(0, 0), Bk, bcol, t + 2);
;       BAR; WAIT_L(0); MMA(0, 1, At, B1); BAR;
;       LDA(At, 0, 1); STAGE(SA(0, 0), Ak, brow, t + 2);
;       BAR; WAIT_L(0); MMA(1, 0, At, B0); BAR; SCHED;
;       STAGE(SB(0, 1), Bk, bcol + G_HALF, t + 2);
;       WAIT_V(6); BAR; MMA(1, 1, At, B1); BAR;
;       LDB(B0, 1, 0); SCHED; LDA(At, 1, 0); STAGE(SA(0, 1), Ak, brow + G_HALF, t + 2);
;       WAIT_L(8); BAR; WAIT_L(0); MMA(0, 0, At, B0); BAR; SCHED;
;       LDB(B1, 1, 1); STAGE(SB(1, 0), Bk, bcol, t + 3);
;       BAR; WAIT_L(0); MMA(0, 1, At, B1); BAR;
;       LDA(At, 1, 1); STAGE(SA(1, 0), Ak, brow, t + 3);
;       BAR; WAIT_L(0); MMA(1, 0, At, B0); BAR; SCHED;
;       STAGE(SB(1, 1), Bk, bcol + G_HALF, t + 3);
;       WAIT_V(6); BAR; MMA(1, 1, At, B1); BAR;
;     }
	ds_read_b128 v[154:157], v129 offset:49152
	ds_read_b128 v[158:161], v129 offset:50176
	ds_read_b128 v[162:165], v129 offset:51200
	ds_read_b128 v[172:175], v129 offset:52224
	ds_read_b128 v[180:183], v129 offset:53248
	ds_read_b128 v[184:187], v129 offset:54272
	ds_read_b128 v[188:191], v129 offset:55296
	ds_read_b128 v[192:195], v129 offset:56320
	s_mov_b32 m0, s44
	s_mov_b64 s[26:27], 0x1600180
	v_lshl_add_u64 v[216:217], v[176:177], 0, s[26:27]
	global_load_lds_dwordx4 v[216:217], off
	s_mov_b32 m0, s45
	s_mov_b64 s[26:27], 0x1620180
	v_lshl_add_u64 v[218:219], v[176:177], 0, s[26:27]
	global_load_lds_dwordx4 v[218:219], off
	s_mov_b32 m0, s46
	s_mov_b64 s[26:27], 0x180
	v_lshl_add_u64 v[214:215], v[166:167], 0, s[26:27]
	global_load_lds_dwordx4 v[214:215], off
	s_mov_b32 m0, s47
	s_mov_b64 s[26:27], 0x20180
	v_lshl_add_u64 v[216:217], v[166:167], 0, s[26:27]
	global_load_lds_dwordx4 v[216:217], off
	s_mov_b32 m0, s48
	s_mov_b64 s[26:27], 0x1640180
	v_lshl_add_u64 v[218:219], v[176:177], 0, s[26:27]
	global_load_lds_dwordx4 v[218:219], off
	s_mov_b32 m0, s49
	s_mov_b64 s[26:27], 0x1660180
	v_lshl_add_u64 v[214:215], v[176:177], 0, s[26:27]
	global_load_lds_dwordx4 v[214:215], off
	s_waitcnt vmcnt(6)
	s_waitcnt lgkmcnt(0)
	s_barrier
	v_mfma_f32_16x16x32_bf16 v[60:63], v[154:157], v[138:141], v[60:63]
	v_mfma_f32_16x16x32_bf16 v[56:59], v[154:157], v[146:149], v[56:59]
	v_mfma_f32_16x16x32_bf16 v[52:55], v[162:165], v[138:141], v[52:55]
	v_mfma_f32_16x16x32_bf16 v[48:51], v[162:165], v[146:149], v[48:51]
	v_mfma_f32_16x16x32_bf16 v[44:47], v[180:183], v[138:141], v[44:47]
	v_mfma_f32_16x16x32_bf16 v[40:43], v[180:183], v[146:149], v[40:43]
	v_mfma_f32_16x16x32_bf16 v[36:39], v[188:191], v[138:141], v[36:39]
	v_mfma_f32_16x16x32_bf16 v[32:35], v[188:191], v[146:149], v[32:35]
	v_mfma_f32_16x16x32_bf16 v[60:63], v[158:161], v[142:145], v[60:63]
	v_mfma_f32_16x16x32_bf16 v[56:59], v[158:161], v[150:153], v[56:59]
	v_mfma_f32_16x16x32_bf16 v[52:55], v[172:175], v[142:145], v[52:55]
	v_mfma_f32_16x16x32_bf16 v[48:51], v[172:175], v[150:153], v[48:51]
	v_mfma_f32_16x16x32_bf16 v[44:47], v[184:187], v[142:145], v[44:47]
	v_mfma_f32_16x16x32_bf16 v[40:43], v[184:187], v[150:153], v[40:43]
	v_mfma_f32_16x16x32_bf16 v[36:39], v[192:195], v[142:145], v[36:39]
	v_mfma_f32_16x16x32_bf16 v[32:35], v[192:195], v[150:153], v[32:35]
	v_mfma_f32_16x16x32_bf16 v[28:31], v[154:157], v[196:199], v[28:31]
	v_mfma_f32_16x16x32_bf16 v[24:27], v[154:157], v[204:207], v[24:27]
	v_mfma_f32_16x16x32_bf16 v[20:23], v[162:165], v[196:199], v[20:23]
	v_mfma_f32_16x16x32_bf16 v[16:19], v[162:165], v[204:207], v[16:19]
	v_mfma_f32_16x16x32_bf16 v[12:15], v[180:183], v[196:199], v[12:15]
	v_mfma_f32_16x16x32_bf16 v[8:11], v[180:183], v[204:207], v[8:11]
	v_mfma_f32_16x16x32_bf16 v[4:7], v[188:191], v[196:199], v[4:7]
	v_mfma_f32_16x16x32_bf16 v[0:3], v[188:191], v[204:207], v[0:3]
	v_mfma_f32_16x16x32_bf16 v[28:31], v[158:161], v[200:203], v[28:31]
	v_mfma_f32_16x16x32_bf16 v[24:27], v[158:161], v[208:211], v[24:27]
	v_mfma_f32_16x16x32_bf16 v[20:23], v[172:175], v[200:203], v[20:23]
	v_mfma_f32_16x16x32_bf16 v[16:19], v[172:175], v[208:211], v[16:19]
	v_mfma_f32_16x16x32_bf16 v[12:15], v[184:187], v[200:203], v[12:15]
	v_mfma_f32_16x16x32_bf16 v[8:11], v[184:187], v[208:211], v[8:11]
	v_mfma_f32_16x16x32_bf16 v[4:7], v[192:195], v[200:203], v[4:7]
	v_mfma_f32_16x16x32_bf16 v[0:3], v[192:195], v[208:211], v[0:3]
	s_add_i32 s24, s24, 2
	s_add_u32 s4, s4, 0x100
	s_addc_u32 s5, s5, 0
	s_add_u32 s22, s22, 0x100
	s_addc_u32 s23, s23, 0
	s_cmp_ge_i32 s24, s21
	s_barrier
	s_cbranch_scc0 .LBB0_879

; #define STAGE(P, BASE, br, kt) do { const char* _g = (const char*)((BASE) + (size_t)(br) * K + (size_t)(kt) * G_BK); \
;     _Pragma("unroll") for (int _i = 0; _i < 2; ++_i) { \
;       __builtin_amdgcn_global_load_lds((const unsigned*)(_g + (size_t)_i * 128 * K + sg_off), (unsigned*)((char*)(P) + wid * 1024 + _i * 8192), 16, 0, 0); } } while (0)
; #define LDA(dst, b, h) _Pragma("unroll") for (int m = 0; m < 4; ++m) _Pragma("unroll") for (int k = 0; k < 2; ++k) \
;     dst[m][k] = *reinterpret_cast<const bf16x8*>((const char*)shm + aoff + (((b) * 2 + (h)) * 16384 + m * 2048 + k * 1024))
; #define LDB(dst, b, h) _Pragma("unroll") for (int n = 0; n < 2; ++n) _Pragma("unroll") for (int k = 0; k < 2; ++k) \
;     dst[n][k] = *reinterpret_cast<const bf16x8*>((const char*)shm + boff + (((b) * 2 + (h)) * 16384 + n * 2048 + k * 1024))
; #define WAIT_V(n) asm volatile("s_waitcnt vmcnt(" #n ")" ::: "memory")
; #define WAIT_L(n) asm volatile("s_waitcnt lgkmcnt(" #n ")" ::: "memory")
; #define BAR __builtin_amdgcn_s_barrier()
; #define SCHED __builtin_amdgcn_sched_barrier(0)
; template <class Epi>
; __device__ __forceinline__ void gemm_phase(const bfr* __restrict__ A, int lda, const bfr* __restrict__ Bt, int K,
;                                            int nM, int nN, const Epi& epi, bfr* shm, int wv, int nMfull, int ksplit) {
;     ...
;     for (int t = 0; t < nt - 2; t += 2) {
;       LDB(B0, 0, 0); SCHED; LDA(At, 0, 0); STAGE(SA(1, 1), Ak, brow + G_HALF, t + 1);
;       WAIT_L(8); BAR; WAIT_L(0); MMA(0, 0, At, B0); BAR; SCHED;
;       LDB(B1, 0, 1); STAGE(SB(0, 0), Bk, bcol, t + 2);
;       BAR; WAIT_L(0); MMA(0, 1, At, B1); BAR;
;       LDA(At, 0, 1); STAGE(SA(0, 0), Ak, brow, t + 2);
;       BAR; WAIT_L(0); MMA(1, 0, At, B0); BAR; SCHED;
;       STAGE(SB(0, 1), Bk, bcol + G_HALF, t + 2);
;       WAIT_V(6); BAR; MMA(1, 1, At, B1); BAR;
;       LDB(B0, 1, 0); SCHED; LDA(At, 1, 0); STAGE(SA(0, 1), Ak, brow + G_HALF, t + 2);
;       WAIT_L(8); BAR; WAIT_L(0); MMA(0, 0, At, B0); BAR; SCHED;
;       LDB(B1, 1, 1); STAGE(SB(1, 0), Bk, bcol, t + 3);
;       BAR; WAIT_L(0); MMA(0, 1, At, B1); BAR;
;       LDA(At, 1, 1); STAGE(SA(1, 0), Ak, brow, t + 3);
;       BAR; WAIT_L(0); MMA(1, 0, At, B0); BAR; SCHED;
;       STAGE(SB(1, 1), Bk, bcol + G_HALF, t + 3);
;       WAIT_V(6); BAR; MMA(1, 1, At, B1); BAR;
;     }
.LBB0_935:
	ds_read_b128 v[138:141], v179
	ds_read_b128 v[142:145], v179 offset:1024
	ds_read_b128 v[146:149], v179 offset:2048
	ds_read_b128 v[150:153], v179 offset:3072
	ds_read_b128 v[154:157], v178
	ds_read_b128 v[158:161], v178 offset:1024
	ds_read_b128 v[162:165], v178 offset:2048
	ds_read_b128 v[166:169], v178 offset:3072
	ds_read_b128 v[170:173], v178 offset:4096
	ds_read_b128 v[174:177], v178 offset:5120
	ds_read_b128 v[184:187], v178 offset:6144
	ds_read_b128 v[188:191], v178 offset:7168
	ds_read_b128 v[192:195], v179 offset:16384
	ds_read_b128 v[196:199], v179 offset:17408
	ds_read_b128 v[200:203], v179 offset:18432
	ds_read_b128 v[204:207], v179 offset:19456
	v_lshl_add_u64 v[208:209], s[30:31], 0, v[136:137]
	v_lshl_add_u64 v[210:211], s[36:37], 0, v[136:137]
	s_mov_b32 m0, s50
	v_lshl_add_u64 v[214:215], v[208:209], 0, s[12:13]
	global_load_lds_dwordx4 v[214:215], off
	s_mov_b32 m0, s51
	v_lshl_add_u64 v[216:217], v[208:209], 0, s[14:15]
	global_load_lds_dwordx4 v[216:217], off
	s_waitcnt lgkmcnt(0)
	s_barrier
	v_mfma_f32_16x16x32_bf16 v[124:127], v[154:157], v[138:141], v[124:127]
	v_mfma_f32_16x16x32_bf16 v[120:123], v[154:157], v[146:149], v[120:123]
	v_mfma_f32_16x16x32_bf16 v[116:119], v[162:165], v[138:141], v[116:119]
	v_mfma_f32_16x16x32_bf16 v[112:115], v[162:165], v[146:149], v[112:115]
	v_mfma_f32_16x16x32_bf16 v[108:111], v[170:173], v[138:141], v[108:111]
	v_mfma_f32_16x16x32_bf16 v[104:107], v[170:173], v[146:149], v[104:107]
	v_mfma_f32_16x16x32_bf16 v[100:103], v[184:187], v[138:141], v[100:103]
	v_mfma_f32_16x16x32_bf16 v[96:99], v[184:187], v[146:149], v[96:99]
	v_mfma_f32_16x16x32_bf16 v[124:127], v[158:161], v[142:145], v[124:127]
	v_mfma_f32_16x16x32_bf16 v[120:123], v[158:161], v[150:153], v[120:123]
	v_mfma_f32_16x16x32_bf16 v[116:119], v[166:169], v[142:145], v[116:119]
	v_mfma_f32_16x16x32_bf16 v[112:115], v[166:169], v[150:153], v[112:115]
	v_mfma_f32_16x16x32_bf16 v[108:111], v[174:177], v[142:145], v[108:111]
	v_mfma_f32_16x16x32_bf16 v[104:107], v[174:177], v[150:153], v[104:107]
	v_mfma_f32_16x16x32_bf16 v[100:103], v[188:191], v[142:145], v[100:103]
	v_mfma_f32_16x16x32_bf16 v[96:99], v[188:191], v[150:153], v[96:99]
	v_mfma_f32_16x16x32_bf16 v[92:95], v[154:157], v[192:195], v[92:95]
	v_mfma_f32_16x16x32_bf16 v[88:91], v[154:157], v[200:203], v[88:91]
	v_mfma_f32_16x16x32_bf16 v[84:87], v[162:165], v[192:195], v[84:87]
	v_mfma_f32_16x16x32_bf16 v[80:83], v[162:165], v[200:203], v[80:83]
	v_mfma_f32_16x16x32_bf16 v[76:79], v[170:173], v[192:195], v[76:79]
	v_mfma_f32_16x16x32_bf16 v[72:75], v[170:173], v[200:203], v[72:75]
	v_mfma_f32_16x16x32_bf16 v[68:71], v[184:187], v[192:195], v[68:71]
	v_mfma_f32_16x16x32_bf16 v[64:67], v[184:187], v[200:203], v[64:67]
	v_mfma_f32_16x16x32_bf16 v[92:95], v[158:161], v[196:199], v[92:95]
	v_mfma_f32_16x16x32_bf16 v[88:91], v[158:161], v[204:207], v[88:91]
	v_mfma_f32_16x16x32_bf16 v[84:87], v[166:169], v[196:199], v[84:87]
	v_mfma_f32_16x16x32_bf16 v[80:83], v[166:169], v[204:207], v[80:83]
	v_mfma_f32_16x16x32_bf16 v[76:79], v[174:177], v[196:199], v[76:79]
	v_mfma_f32_16x16x32_bf16 v[72:75], v[174:177], v[204:207], v[72:75]
	v_mfma_f32_16x16x32_bf16 v[68:71], v[188:191], v[196:199], v[68:71]
	v_mfma_f32_16x16x32_bf16 v[64:67], v[188:191], v[204:207], v[64:67]
	s_barrier
	ds_read_b128 v[154:157], v178 offset:16384
	ds_read_b128 v[158:161], v178 offset:17408
	ds_read_b128 v[162:165], v178 offset:18432
	ds_read_b128 v[166:169], v178 offset:19456
	ds_read_b128 v[170:173], v178 offset:20480
	ds_read_b128 v[174:177], v178 offset:21504
	ds_read_b128 v[184:187], v178 offset:22528
	ds_read_b128 v[188:191], v178 offset:23552
	s_mov_b32 m0, s52
	s_mov_b64 s[40:41], 0xb00100
	v_lshl_add_u64 v[218:219], v[210:211], 0, s[40:41]
	global_load_lds_dwordx4 v[218:219], off
	s_mov_b32 m0, s53
	s_mov_b64 s[40:41], 0xb58100
	v_lshl_add_u64 v[214:215], v[210:211], 0, s[40:41]
	global_load_lds_dwordx4 v[214:215], off
	s_mov_b32 m0, s49
	s_mov_b64 s[40:41], 0x100
	v_lshl_add_u64 v[216:217], v[208:209], 0, s[40:41]
	global_load_lds_dwordx4 v[216:217], off
	s_mov_b32 m0, s54
	s_mov_b64 s[40:41], 0x58100
	v_lshl_add_u64 v[218:219], v[208:209], 0, s[40:41]
	global_load_lds_dwordx4 v[218:219], off
	s_mov_b32 m0, s55
	s_mov_b64 s[40:41], 0xbb0100
	v_lshl_add_u64 v[214:215], v[210:211], 0, s[40:41]
	global_load_lds_dwordx4 v[214:215], off
	s_mov_b32 m0, s56
	s_mov_b64 s[40:41], 0xc08100
	v_lshl_add_u64 v[216:217], v[210:211], 0, s[40:41]
	global_load_lds_dwordx4 v[216:217], off
	s_waitcnt vmcnt(6)
	s_waitcnt lgkmcnt(0)
	s_barrier
; #define STAGE(P, BASE, br, kt) do { const char* _g = (const char*)((BASE) + (size_t)(br) * K + (size_t)(kt) * G_BK); \
;     _Pragma("unroll") for (int _i = 0; _i < 2; ++_i) { \
;       __builtin_amdgcn_global_load_lds((const unsigned*)(_g + (size_t)_i * 128 * K + sg_off), (unsigned*)((char*)(P) + wid * 1024 + _i * 8192), 16, 0, 0); } } while (0)
; #define LDA(dst, b, h) _Pragma("unroll") for (int m = 0; m < 4; ++m) _Pragma("unroll") for (int k = 0; k < 2; ++k) \
;     dst[m][k] = *reinterpret_cast<const bf16x8*>((const char*)shm + aoff + (((b) * 2 + (h)) * 16384 + m * 2048 + k * 1024))
; #define LDB(dst, b, h) _Pragma("unroll") for (int n = 0; n < 2; ++n) _Pragma("unroll") for (int k = 0; k < 2; ++k) \
;     dst[n][k] = *reinterpret_cast<const bf16x8*>((const char*)shm + boff + (((b) * 2 + (h)) * 16384 + n * 2048 + k * 1024))
; #define WAIT_V(n) asm volatile("s_waitcnt vmcnt(" #n ")" ::: "memory")
; #define WAIT_L(n) asm volatile("s_waitcnt lgkmcnt(" #n ")" ::: "memory")
; #define BAR __builtin_amdgcn_s_barrier()
; #define SCHED __builtin_amdgcn_sched_barrier(0)
; template <class Epi>
; __device__ __forceinline__ void gemm_phase(const bfr* __restrict__ A, int lda, const bfr* __restrict__ Bt, int K,
;                                            int nM, int nN, const Epi& epi, bfr* shm, int wv, int nMfull, int ksplit) {
;     ...
;     for (int t = 0; t < nt - 2; t += 2) {
;       LDB(B0, 0, 0); SCHED; LDA(At, 0, 0); STAGE(SA(1, 1), Ak, brow + G_HALF, t + 1);
;       WAIT_L(8); BAR; WAIT_L(0); MMA(0, 0, At, B0); BAR; SCHED;
;       LDB(B1, 0, 1); STAGE(SB(0, 0), Bk, bcol, t + 2);
;       BAR; WAIT_L(0); MMA(0, 1, At, B1); BAR;
;       LDA(At, 0, 1); STAGE(SA(0, 0), Ak, brow, t + 2);
;       BAR; WAIT_L(0); MMA(1, 0, At, B0); BAR; SCHED;
;       STAGE(SB(0, 1), Bk, bcol + G_HALF, t + 2);
;       WAIT_V(6); BAR; MMA(1, 1, At, B1); BAR;
;       LDB(B0, 1, 0); SCHED; LDA(At, 1, 0); STAGE(SA(0, 1), Ak, brow + G_HALF, t + 2);
;       WAIT_L(8); BAR; WAIT_L(0); MMA(0, 0, At, B0); BAR; SCHED;
;       LDB(B1, 1, 1); STAGE(SB(1, 0), Bk, bcol, t + 3);
;       BAR; WAIT_L(0); MMA(0, 1, At, B1); BAR;
;       LDA(At, 1, 1); STAGE(SA(1, 0), Ak, brow, t + 3);
;       BAR; WAIT_L(0); MMA(1, 0, At, B0); BAR; SCHED;
;       STAGE(SB(1, 1), Bk, bcol + G_HALF, t + 3);
;       WAIT_V(6); BAR; MMA(1, 1, At, B1); BAR;
;     }
	v_mfma_f32_16x16x32_bf16 v[60:63], v[154:157], v[138:141], v[60:63]
	v_mfma_f32_16x16x32_bf16 v[56:59], v[154:157], v[146:149], v[56:59]
	v_mfma_f32_16x16x32_bf16 v[52:55], v[162:165], v[138:141], v[52:55]
	v_mfma_f32_16x16x32_bf16 v[48:51], v[162:165], v[146:149], v[48:51]
	v_mfma_f32_16x16x32_bf16 v[44:47], v[170:173], v[138:141], v[44:47]
	v_mfma_f32_16x16x32_bf16 v[40:43], v[170:173], v[146:149], v[40:43]
	v_mfma_f32_16x16x32_bf16 v[36:39], v[184:187], v[138:141], v[36:39]
	v_mfma_f32_16x16x32_bf16 v[32:35], v[184:187], v[146:149], v[32:35]
	v_mfma_f32_16x16x32_bf16 v[60:63], v[158:161], v[142:145], v[60:63]
	v_mfma_f32_16x16x32_bf16 v[56:59], v[158:161], v[150:153], v[56:59]
	v_mfma_f32_16x16x32_bf16 v[52:55], v[166:169], v[142:145], v[52:55]
	v_mfma_f32_16x16x32_bf16 v[48:51], v[166:169], v[150:153], v[48:51]
	v_mfma_f32_16x16x32_bf16 v[44:47], v[174:177], v[142:145], v[44:47]
	v_mfma_f32_16x16x32_bf16 v[40:43], v[174:177], v[150:153], v[40:43]
	v_mfma_f32_16x16x32_bf16 v[36:39], v[188:191], v[142:145], v[36:39]
	v_mfma_f32_16x16x32_bf16 v[32:35], v[188:191], v[150:153], v[32:35]
	v_mfma_f32_16x16x32_bf16 v[28:31], v[154:157], v[192:195], v[28:31]
	v_mfma_f32_16x16x32_bf16 v[24:27], v[154:157], v[200:203], v[24:27]
	v_mfma_f32_16x16x32_bf16 v[20:23], v[162:165], v[192:195], v[20:23]
	v_mfma_f32_16x16x32_bf16 v[16:19], v[162:165], v[200:203], v[16:19]
	v_mfma_f32_16x16x32_bf16 v[12:15], v[170:173], v[192:195], v[12:15]
	v_mfma_f32_16x16x32_bf16 v[8:11], v[170:173], v[200:203], v[8:11]
	v_mfma_f32_16x16x32_bf16 v[4:7], v[184:187], v[192:195], v[4:7]
	v_mfma_f32_16x16x32_bf16 v[0:3], v[184:187], v[200:203], v[0:3]
	v_mfma_f32_16x16x32_bf16 v[28:31], v[158:161], v[196:199], v[28:31]
	v_mfma_f32_16x16x32_bf16 v[24:27], v[158:161], v[204:207], v[24:27]
	v_mfma_f32_16x16x32_bf16 v[20:23], v[166:169], v[196:199], v[20:23]
	v_mfma_f32_16x16x32_bf16 v[16:19], v[166:169], v[204:207], v[16:19]
	v_mfma_f32_16x16x32_bf16 v[12:15], v[174:177], v[196:199], v[12:15]
	v_mfma_f32_16x16x32_bf16 v[8:11], v[174:177], v[204:207], v[8:11]
	v_mfma_f32_16x16x32_bf16 v[4:7], v[188:191], v[196:199], v[4:7]
	v_mfma_f32_16x16x32_bf16 v[0:3], v[188:191], v[204:207], v[0:3]
	s_barrier
	ds_read_b128 v[138:141], v179 offset:32768
	ds_read_b128 v[142:145], v179 offset:33792
	ds_read_b128 v[146:149], v179 offset:34816
	ds_read_b128 v[150:153], v179 offset:35840
	ds_read_b128 v[154:157], v178 offset:32768
	ds_read_b128 v[158:161], v178 offset:33792
	ds_read_b128 v[162:165], v178 offset:34816
	ds_read_b128 v[166:169], v178 offset:35840
	ds_read_b128 v[170:173], v178 offset:36864
	ds_read_b128 v[174:177], v178 offset:37888
	ds_read_b128 v[184:187], v178 offset:38912
	ds_read_b128 v[188:191], v178 offset:39936
	ds_read_b128 v[192:195], v179 offset:49152
	ds_read_b128 v[196:199], v179 offset:50176
	ds_read_b128 v[200:203], v179 offset:51200
	ds_read_b128 v[204:207], v179 offset:52224
	s_mov_b32 m0, s57
	s_mov_b64 s[40:41], 0xb0100
	v_lshl_add_u64 v[218:219], v[208:209], 0, s[40:41]
	global_load_lds_dwordx4 v[218:219], off
	s_mov_b32 m0, s58
	s_mov_b64 s[40:41], 0x108100
	v_lshl_add_u64 v[214:215], v[208:209], 0, s[40:41]
	global_load_lds_dwordx4 v[214:215], off
	s_waitcnt lgkmcnt(0)
	s_barrier
	v_mfma_f32_16x16x32_bf16 v[124:127], v[154:157], v[138:141], v[124:127]
	v_mfma_f32_16x16x32_bf16 v[120:123], v[154:157], v[146:149], v[120:123]
	v_mfma_f32_16x16x32_bf16 v[116:119], v[162:165], v[138:141], v[116:119]
	v_mfma_f32_16x16x32_bf16 v[112:115], v[162:165], v[146:149], v[112:115]
	v_mfma_f32_16x16x32_bf16 v[108:111], v[170:173], v[138:141], v[108:111]
	v_mfma_f32_16x16x32_bf16 v[104:107], v[170:173], v[146:149], v[104:107]
	v_mfma_f32_16x16x32_bf16 v[100:103], v[184:187], v[138:141], v[100:103]
	v_mfma_f32_16x16x32_bf16 v[96:99], v[184:187], v[146:149], v[96:99]
	v_mfma_f32_16x16x32_bf16 v[124:127], v[158:161], v[142:145], v[124:127]
	v_mfma_f32_16x16x32_bf16 v[120:123], v[158:161], v[150:153], v[120:123]
	v_mfma_f32_16x16x32_bf16 v[116:119], v[166:169], v[142:145], v[116:119]
	v_mfma_f32_16x16x32_bf16 v[112:115], v[166:169], v[150:153], v[112:115]
	v_mfma_f32_16x16x32_bf16 v[108:111], v[174:177], v[142:145], v[108:111]
	v_mfma_f32_16x16x32_bf16 v[104:107], v[174:177], v[150:153], v[104:107]
	v_mfma_f32_16x16x32_bf16 v[100:103], v[188:191], v[142:145], v[100:103]
	v_mfma_f32_16x16x32_bf16 v[96:99], v[188:191], v[150:153], v[96:99]
	v_mfma_f32_16x16x32_bf16 v[92:95], v[154:157], v[192:195], v[92:95]
	v_mfma_f32_16x16x32_bf16 v[88:91], v[154:157], v[200:203], v[88:91]
	v_mfma_f32_16x16x32_bf16 v[84:87], v[162:165], v[192:195], v[84:87]
	v_mfma_f32_16x16x32_bf16 v[80:83], v[162:165], v[200:203], v[80:83]
	v_mfma_f32_16x16x32_bf16 v[76:79], v[170:173], v[192:195], v[76:79]
	v_mfma_f32_16x16x32_bf16 v[72:75], v[170:173], v[200:203], v[72:75]
	v_mfma_f32_16x16x32_bf16 v[68:71], v[184:187], v[192:195], v[68:71]
	v_mfma_f32_16x16x32_bf16 v[64:67], v[184:187], v[200:203], v[64:67]
	v_mfma_f32_16x16x32_bf16 v[92:95], v[158:161], v[196:199], v[92:95]
	v_mfma_f32_16x16x32_bf16 v[88:91], v[158:161], v[204:207], v[88:91]
	v_mfma_f32_16x16x32_bf16 v[84:87], v[166:169], v[196:199], v[84:87]
	v_mfma_f32_16x16x32_bf16 v[80:83], v[166:169], v[204:207], v[80:83]
	v_mfma_f32_16x16x32_bf16 v[76:79], v[174:177], v[196:199], v[76:79]
	v_mfma_f32_16x16x32_bf16 v[72:75], v[174:177], v[204:207], v[72:75]
	v_mfma_f32_16x16x32_bf16 v[68:71], v[188:191], v[196:199], v[68:71]
	v_mfma_f32_16x16x32_bf16 v[64:67], v[188:191], v[204:207], v[64:67]
	s_barrier
; #define STAGE(P, BASE, br, kt) do { const char* _g = (const char*)((BASE) + (size_t)(br) * K + (size_t)(kt) * G_BK); \
;     _Pragma("unroll") for (int _i = 0; _i < 2; ++_i) { \
;       __builtin_amdgcn_global_load_lds((const unsigned*)(_g + (size_t)_i * 128 * K + sg_off), (unsigned*)((char*)(P) + wid * 1024 + _i * 8192), 16, 0, 0); } } while (0)
; #define LDA(dst, b, h) _Pragma("unroll") for (int m = 0; m < 4; ++m) _Pragma("unroll") for (int k = 0; k < 2; ++k) \
;     dst[m][k] = *reinterpret_cast<const bf16x8*>((const char*)shm + aoff + (((b) * 2 + (h)) * 16384 + m * 2048 + k * 1024))
; #define LDB(dst, b, h) _Pragma("unroll") for (int n = 0; n < 2; ++n) _Pragma("unroll") for (int k = 0; k < 2; ++k) \
;     dst[n][k] = *reinterpret_cast<const bf16x8*>((const char*)shm + boff + (((b) * 2 + (h)) * 16384 + n * 2048 + k * 1024))
; #define WAIT_V(n) asm volatile("s_waitcnt vmcnt(" #n ")" ::: "memory")
; #define WAIT_L(n) asm volatile("s_waitcnt lgkmcnt(" #n ")" ::: "memory")
; #define BAR __builtin_amdgcn_s_barrier()
; #define SCHED __builtin_amdgcn_sched_barrier(0)
; template <class Epi>
; __device__ __forceinline__ void gemm_phase(const bfr* __restrict__ A, int lda, const bfr* __restrict__ Bt, int K,
;                                            int nM, int nN, const Epi& epi, bfr* shm, int wv, int nMfull, int ksplit) {
;     ...
;     for (int t = 0; t < nt - 2; t += 2) {
;       LDB(B0, 0, 0); SCHED; LDA(At, 0, 0); STAGE(SA(1, 1), Ak, brow + G_HALF, t + 1);
;       WAIT_L(8); BAR; WAIT_L(0); MMA(0, 0, At, B0); BAR; SCHED;
;       LDB(B1, 0, 1); STAGE(SB(0, 0), Bk, bcol, t + 2);
;       BAR; WAIT_L(0); MMA(0, 1, At, B1); BAR;
;       LDA(At, 0, 1); STAGE(SA(0, 0), Ak, brow, t + 2);
;       BAR; WAIT_L(0); MMA(1, 0, At, B0); BAR; SCHED;
;       STAGE(SB(0, 1), Bk, bcol + G_HALF, t + 2);
;       WAIT_V(6); BAR; MMA(1, 1, At, B1); BAR;
;       LDB(B0, 1, 0); SCHED; LDA(At, 1, 0); STAGE(SA(0, 1), Ak, brow + G_HALF, t + 2);
;       WAIT_L(8); BAR; WAIT_L(0); MMA(0, 0, At, B0); BAR; SCHED;
;       LDB(B1, 1, 1); STAGE(SB(1, 0), Bk, bcol, t + 3);
;       BAR; WAIT_L(0); MMA(0, 1, At, B1); BAR;
;       LDA(At, 1, 1); STAGE(SA(1, 0), Ak, brow, t + 3);
;       BAR; WAIT_L(0); MMA(1, 0, At, B0); BAR; SCHED;
;       STAGE(SB(1, 1), Bk, bcol + G_HALF, t + 3);
;       WAIT_V(6); BAR; MMA(1, 1, At, B1); BAR;
;     }
	ds_read_b128 v[154:157], v178 offset:49152
	ds_read_b128 v[158:161], v178 offset:50176
	ds_read_b128 v[162:165], v178 offset:51200
	ds_read_b128 v[166:169], v178 offset:52224
	ds_read_b128 v[170:173], v178 offset:53248
	ds_read_b128 v[174:177], v178 offset:54272
	ds_read_b128 v[184:187], v178 offset:55296
	ds_read_b128 v[188:191], v178 offset:56320
	s_mov_b32 m0, s59
	s_mov_b64 s[40:41], 0xb00180
	v_lshl_add_u64 v[216:217], v[210:211], 0, s[40:41]
	global_load_lds_dwordx4 v[216:217], off
	s_mov_b32 m0, s82
	s_mov_b64 s[40:41], 0xb58180
	v_lshl_add_u64 v[218:219], v[210:211], 0, s[40:41]
	global_load_lds_dwordx4 v[218:219], off
	s_mov_b32 m0, s83
	s_mov_b64 s[40:41], 0x180
	v_lshl_add_u64 v[214:215], v[208:209], 0, s[40:41]
	global_load_lds_dwordx4 v[214:215], off
	s_mov_b32 m0, s84
	s_mov_b64 s[40:41], 0x58180
	v_lshl_add_u64 v[216:217], v[208:209], 0, s[40:41]
	global_load_lds_dwordx4 v[216:217], off
	s_mov_b32 m0, s85
	s_mov_b64 s[40:41], 0xbb0180
	v_lshl_add_u64 v[218:219], v[210:211], 0, s[40:41]
	global_load_lds_dwordx4 v[218:219], off
	s_mov_b32 m0, s90
	s_mov_b64 s[40:41], 0xc08180
	v_lshl_add_u64 v[214:215], v[210:211], 0, s[40:41]
	global_load_lds_dwordx4 v[214:215], off
	s_waitcnt vmcnt(6)
	s_waitcnt lgkmcnt(0)
	s_barrier
	v_mfma_f32_16x16x32_bf16 v[60:63], v[154:157], v[138:141], v[60:63]
	v_mfma_f32_16x16x32_bf16 v[56:59], v[154:157], v[146:149], v[56:59]
	v_mfma_f32_16x16x32_bf16 v[52:55], v[162:165], v[138:141], v[52:55]
	v_mfma_f32_16x16x32_bf16 v[48:51], v[162:165], v[146:149], v[48:51]
	v_mfma_f32_16x16x32_bf16 v[44:47], v[170:173], v[138:141], v[44:47]
	v_mfma_f32_16x16x32_bf16 v[40:43], v[170:173], v[146:149], v[40:43]
	v_mfma_f32_16x16x32_bf16 v[36:39], v[184:187], v[138:141], v[36:39]
	v_mfma_f32_16x16x32_bf16 v[32:35], v[184:187], v[146:149], v[32:35]
	v_mfma_f32_16x16x32_bf16 v[60:63], v[158:161], v[142:145], v[60:63]
	v_mfma_f32_16x16x32_bf16 v[56:59], v[158:161], v[150:153], v[56:59]
	v_mfma_f32_16x16x32_bf16 v[52:55], v[166:169], v[142:145], v[52:55]
	v_mfma_f32_16x16x32_bf16 v[48:51], v[166:169], v[150:153], v[48:51]
	v_mfma_f32_16x16x32_bf16 v[44:47], v[174:177], v[142:145], v[44:47]
	v_mfma_f32_16x16x32_bf16 v[40:43], v[174:177], v[150:153], v[40:43]
	v_mfma_f32_16x16x32_bf16 v[36:39], v[188:191], v[142:145], v[36:39]
	v_mfma_f32_16x16x32_bf16 v[32:35], v[188:191], v[150:153], v[32:35]
	v_mfma_f32_16x16x32_bf16 v[28:31], v[154:157], v[192:195], v[28:31]
	v_mfma_f32_16x16x32_bf16 v[24:27], v[154:157], v[200:203], v[24:27]
	v_mfma_f32_16x16x32_bf16 v[20:23], v[162:165], v[192:195], v[20:23]
	v_mfma_f32_16x16x32_bf16 v[16:19], v[162:165], v[200:203], v[16:19]
	v_mfma_f32_16x16x32_bf16 v[12:15], v[170:173], v[192:195], v[12:15]
	v_mfma_f32_16x16x32_bf16 v[8:11], v[170:173], v[200:203], v[8:11]
	v_mfma_f32_16x16x32_bf16 v[4:7], v[184:187], v[192:195], v[4:7]
	v_mfma_f32_16x16x32_bf16 v[0:3], v[184:187], v[200:203], v[0:3]
	v_mfma_f32_16x16x32_bf16 v[28:31], v[158:161], v[196:199], v[28:31]
	v_mfma_f32_16x16x32_bf16 v[24:27], v[158:161], v[204:207], v[24:27]
	v_mfma_f32_16x16x32_bf16 v[20:23], v[166:169], v[196:199], v[20:23]
	v_mfma_f32_16x16x32_bf16 v[16:19], v[166:169], v[204:207], v[16:19]
	v_mfma_f32_16x16x32_bf16 v[12:15], v[174:177], v[196:199], v[12:15]
	v_mfma_f32_16x16x32_bf16 v[8:11], v[174:177], v[204:207], v[8:11]
	v_mfma_f32_16x16x32_bf16 v[4:7], v[188:191], v[196:199], v[4:7]
	v_mfma_f32_16x16x32_bf16 v[0:3], v[188:191], v[204:207], v[0:3]
	s_add_i32 s39, s39, 2
	s_add_u32 s36, s36, 0x100
	s_addc_u32 s37, s37, 0
	s_add_u32 s30, s30, 0x100
	s_addc_u32 s31, s31, 0
	s_cmp_ge_i32 s39, s35
	s_barrier
	s_cbranch_scc0 .LBB0_935

; #define STAGE(P, BASE, br, kt) do { const char* _g = (const char*)((BASE) + (size_t)(br) * K + (size_t)(kt) * G_BK); \
;     _Pragma("unroll") for (int _i = 0; _i < 2; ++_i) { \
;       __builtin_amdgcn_global_load_lds((const unsigned*)(_g + (size_t)_i * 128 * K + sg_off), (unsigned*)((char*)(P) + wid * 1024 + _i * 8192), 16, 0, 0); } } while (0)
; #define LDA(dst, b, h) _Pragma("unroll") for (int m = 0; m < 4; ++m) _Pragma("unroll") for (int k = 0; k < 2; ++k) \
;     dst[m][k] = *reinterpret_cast<const bf16x8*>((const char*)shm + aoff + (((b) * 2 + (h)) * 16384 + m * 2048 + k * 1024))
; #define LDB(dst, b, h) _Pragma("unroll") for (int n = 0; n < 2; ++n) _Pragma("unroll") for (int k = 0; k < 2; ++k) \
;     dst[n][k] = *reinterpret_cast<const bf16x8*>((const char*)shm + boff + (((b) * 2 + (h)) * 16384 + n * 2048 + k * 1024))
; #define WAIT_V(n) asm volatile("s_waitcnt vmcnt(" #n ")" ::: "memory")
; #define WAIT_L(n) asm volatile("s_waitcnt lgkmcnt(" #n ")" ::: "memory")
; #define BAR __builtin_amdgcn_s_barrier()
; #define SCHED __builtin_amdgcn_sched_barrier(0)
; template <class Epi>
; __device__ __forceinline__ void gemm_phase(const bfr* __restrict__ A, int lda, const bfr* __restrict__ Bt, int K,
;                                            int nM, int nN, const Epi& epi, bfr* shm, int wv, int nMfull, int ksplit) {
;     ...
;     for (int t = 0; t < nt - 2; t += 2) {
;       LDB(B0, 0, 0); SCHED; LDA(At, 0, 0); STAGE(SA(1, 1), Ak, brow + G_HALF, t + 1);
;       WAIT_L(8); BAR; WAIT_L(0); MMA(0, 0, At, B0); BAR; SCHED;
;       LDB(B1, 0, 1); STAGE(SB(0, 0), Bk, bcol, t + 2);
;       BAR; WAIT_L(0); MMA(0, 1, At, B1); BAR;
;       LDA(At, 0, 1); STAGE(SA(0, 0), Ak, brow, t + 2);
;       BAR; WAIT_L(0); MMA(1, 0, At, B0); BAR; SCHED;
;       STAGE(SB(0, 1), Bk, bcol + G_HALF, t + 2);
;       WAIT_V(6); BAR; MMA(1, 1, At, B1); BAR;
;       LDB(B0, 1, 0); SCHED; LDA(At, 1, 0); STAGE(SA(0, 1), Ak, brow + G_HALF, t + 2);
;       WAIT_L(8); BAR; WAIT_L(0); MMA(0, 0, At, B0); BAR; SCHED;
;       LDB(B1, 1, 1); STAGE(SB(1, 0), Bk, bcol, t + 3);
;       BAR; WAIT_L(0); MMA(0, 1, At, B1); BAR;
;       LDA(At, 1, 1); STAGE(SA(1, 0), Ak, brow, t + 3);
;       BAR; WAIT_L(0); MMA(1, 0, At, B0); BAR; SCHED;
;       STAGE(SB(1, 1), Bk, bcol + G_HALF, t + 3);
;       WAIT_V(6); BAR; MMA(1, 1, At, B1); BAR;
;     }
.LBB0_1086:
	ds_read_b128 v[148:151], v137
	ds_read_b128 v[152:155], v137 offset:1024
	ds_read_b128 v[162:165], v137 offset:2048
	ds_read_b128 v[166:169], v137 offset:3072
	ds_read_b128 v[170:173], v129
	ds_read_b128 v[174:177], v129 offset:1024
	ds_read_b128 v[178:181], v129 offset:2048
	ds_read_b128 v[182:185], v129 offset:3072
	ds_read_b128 v[186:189], v129 offset:4096
	ds_read_b128 v[190:193], v129 offset:5120
	ds_read_b128 v[194:197], v129 offset:6144
	ds_read_b128 v[198:201], v129 offset:7168
	ds_read_b128 v[202:205], v137 offset:16384
	ds_read_b128 v[206:209], v137 offset:17408
	ds_read_b128 v[210:213], v137 offset:18432
	ds_read_b128 v[214:217], v137 offset:19456
	v_lshl_add_u64 v[142:143], s[36:37], 0, v[140:141]
	v_lshl_add_u64 v[218:219], s[2:3], 0, v[140:141]
	s_mov_b32 m0, s95
	s_mov_b64 s[42:43], 0x40080
	v_lshl_add_u64 v[222:223], v[142:143], 0, s[42:43]
	global_load_lds_dwordx4 v[222:223], off
	s_mov_b32 m0, s96
	s_mov_b64 s[42:43], 0x60080
	v_lshl_add_u64 v[224:225], v[142:143], 0, s[42:43]
	global_load_lds_dwordx4 v[224:225], off
	s_waitcnt lgkmcnt(0)
	s_barrier
	v_mfma_f32_16x16x32_bf16 v[124:127], v[170:173], v[148:151], v[124:127]
	v_mfma_f32_16x16x32_bf16 v[120:123], v[170:173], v[162:165], v[120:123]
	v_mfma_f32_16x16x32_bf16 v[116:119], v[178:181], v[148:151], v[116:119]
	v_mfma_f32_16x16x32_bf16 v[112:115], v[178:181], v[162:165], v[112:115]
	v_mfma_f32_16x16x32_bf16 v[108:111], v[186:189], v[148:151], v[108:111]
	v_mfma_f32_16x16x32_bf16 v[104:107], v[186:189], v[162:165], v[104:107]
	v_mfma_f32_16x16x32_bf16 v[100:103], v[194:197], v[148:151], v[100:103]
	v_mfma_f32_16x16x32_bf16 v[96:99], v[194:197], v[162:165], v[96:99]
	v_mfma_f32_16x16x32_bf16 v[124:127], v[174:177], v[152:155], v[124:127]
	v_mfma_f32_16x16x32_bf16 v[120:123], v[174:177], v[166:169], v[120:123]
	v_mfma_f32_16x16x32_bf16 v[116:119], v[182:185], v[152:155], v[116:119]
	v_mfma_f32_16x16x32_bf16 v[112:115], v[182:185], v[166:169], v[112:115]
	v_mfma_f32_16x16x32_bf16 v[108:111], v[190:193], v[152:155], v[108:111]
	v_mfma_f32_16x16x32_bf16 v[104:107], v[190:193], v[166:169], v[104:107]
	v_mfma_f32_16x16x32_bf16 v[100:103], v[198:201], v[152:155], v[100:103]
	v_mfma_f32_16x16x32_bf16 v[96:99], v[198:201], v[166:169], v[96:99]
	v_mfma_f32_16x16x32_bf16 v[92:95], v[170:173], v[202:205], v[92:95]
	v_mfma_f32_16x16x32_bf16 v[88:91], v[170:173], v[210:213], v[88:91]
	v_mfma_f32_16x16x32_bf16 v[84:87], v[178:181], v[202:205], v[84:87]
	v_mfma_f32_16x16x32_bf16 v[80:83], v[178:181], v[210:213], v[80:83]
	v_mfma_f32_16x16x32_bf16 v[76:79], v[186:189], v[202:205], v[76:79]
	v_mfma_f32_16x16x32_bf16 v[72:75], v[186:189], v[210:213], v[72:75]
	v_mfma_f32_16x16x32_bf16 v[68:71], v[194:197], v[202:205], v[68:71]
	v_mfma_f32_16x16x32_bf16 v[64:67], v[194:197], v[210:213], v[64:67]
	v_mfma_f32_16x16x32_bf16 v[92:95], v[174:177], v[206:209], v[92:95]
	v_mfma_f32_16x16x32_bf16 v[88:91], v[174:177], v[214:217], v[88:91]
	v_mfma_f32_16x16x32_bf16 v[84:87], v[182:185], v[206:209], v[84:87]
	v_mfma_f32_16x16x32_bf16 v[80:83], v[182:185], v[214:217], v[80:83]
	v_mfma_f32_16x16x32_bf16 v[76:79], v[190:193], v[206:209], v[76:79]
	v_mfma_f32_16x16x32_bf16 v[72:75], v[190:193], v[214:217], v[72:75]
	v_mfma_f32_16x16x32_bf16 v[68:71], v[198:201], v[206:209], v[68:71]
	v_mfma_f32_16x16x32_bf16 v[64:67], v[198:201], v[214:217], v[64:67]
	s_barrier
	ds_read_b128 v[170:173], v129 offset:16384
	ds_read_b128 v[174:177], v129 offset:17408
	ds_read_b128 v[178:181], v129 offset:18432
	ds_read_b128 v[182:185], v129 offset:19456
	ds_read_b128 v[186:189], v129 offset:20480
	ds_read_b128 v[190:193], v129 offset:21504
	ds_read_b128 v[194:197], v129 offset:22528
	ds_read_b128 v[198:201], v129 offset:23552
	s_mov_b32 m0, s97
	v_lshl_add_u64 v[226:227], v[218:219], 0, s[8:9]
	global_load_lds_dwordx4 v[226:227], off
	s_mov_b32 m0, s92
	v_lshl_add_u64 v[222:223], v[218:219], 0, s[10:11]
	global_load_lds_dwordx4 v[222:223], off
	s_mov_b32 m0, s31
	v_lshl_add_u64 v[224:225], v[142:143], 0, s[8:9]
	global_load_lds_dwordx4 v[224:225], off
	s_mov_b32 m0, s94
	v_lshl_add_u64 v[226:227], v[142:143], 0, s[10:11]
	global_load_lds_dwordx4 v[226:227], off
	s_mov_b32 m0, s91
	v_lshl_add_u64 v[222:223], v[218:219], 0, s[12:13]
	global_load_lds_dwordx4 v[222:223], off
	s_mov_b32 m0, s93
	v_lshl_add_u64 v[224:225], v[218:219], 0, s[14:15]
	global_load_lds_dwordx4 v[224:225], off
	s_waitcnt vmcnt(6)
	s_waitcnt lgkmcnt(0)
	s_barrier
	v_mfma_f32_16x16x32_bf16 v[60:63], v[170:173], v[148:151], v[60:63]
	v_mfma_f32_16x16x32_bf16 v[56:59], v[170:173], v[162:165], v[56:59]
	v_mfma_f32_16x16x32_bf16 v[52:55], v[178:181], v[148:151], v[52:55]
	v_mfma_f32_16x16x32_bf16 v[48:51], v[178:181], v[162:165], v[48:51]
	v_mfma_f32_16x16x32_bf16 v[44:47], v[186:189], v[148:151], v[44:47]
	v_mfma_f32_16x16x32_bf16 v[40:43], v[186:189], v[162:165], v[40:43]
	v_mfma_f32_16x16x32_bf16 v[36:39], v[194:197], v[148:151], v[36:39]
	v_mfma_f32_16x16x32_bf16 v[32:35], v[194:197], v[162:165], v[32:35]
	v_mfma_f32_16x16x32_bf16 v[60:63], v[174:177], v[152:155], v[60:63]
	v_mfma_f32_16x16x32_bf16 v[56:59], v[174:177], v[166:169], v[56:59]
	v_mfma_f32_16x16x32_bf16 v[52:55], v[182:185], v[152:155], v[52:55]
	v_mfma_f32_16x16x32_bf16 v[48:51], v[182:185], v[166:169], v[48:51]
	v_mfma_f32_16x16x32_bf16 v[44:47], v[190:193], v[152:155], v[44:47]
	v_mfma_f32_16x16x32_bf16 v[40:43], v[190:193], v[166:169], v[40:43]
	v_mfma_f32_16x16x32_bf16 v[36:39], v[198:201], v[152:155], v[36:39]
	v_mfma_f32_16x16x32_bf16 v[32:35], v[198:201], v[166:169], v[32:35]
	v_mfma_f32_16x16x32_bf16 v[28:31], v[170:173], v[202:205], v[28:31]
	v_mfma_f32_16x16x32_bf16 v[24:27], v[170:173], v[210:213], v[24:27]
	v_mfma_f32_16x16x32_bf16 v[20:23], v[178:181], v[202:205], v[20:23]
	v_mfma_f32_16x16x32_bf16 v[16:19], v[178:181], v[210:213], v[16:19]
	v_mfma_f32_16x16x32_bf16 v[12:15], v[186:189], v[202:205], v[12:15]
	v_mfma_f32_16x16x32_bf16 v[8:11], v[186:189], v[210:213], v[8:11]
	v_mfma_f32_16x16x32_bf16 v[4:7], v[194:197], v[202:205], v[4:7]
	v_mfma_f32_16x16x32_bf16 v[0:3], v[194:197], v[210:213], v[0:3]
	v_mfma_f32_16x16x32_bf16 v[28:31], v[174:177], v[206:209], v[28:31]
	v_mfma_f32_16x16x32_bf16 v[24:27], v[174:177], v[214:217], v[24:27]
	v_mfma_f32_16x16x32_bf16 v[20:23], v[182:185], v[206:209], v[20:23]
	v_mfma_f32_16x16x32_bf16 v[16:19], v[182:185], v[214:217], v[16:19]
	v_mfma_f32_16x16x32_bf16 v[12:15], v[190:193], v[206:209], v[12:15]
	v_mfma_f32_16x16x32_bf16 v[8:11], v[190:193], v[214:217], v[8:11]
	v_mfma_f32_16x16x32_bf16 v[4:7], v[198:201], v[206:209], v[4:7]
	v_mfma_f32_16x16x32_bf16 v[0:3], v[198:201], v[214:217], v[0:3]
	s_barrier
; #define STAGE(P, BASE, br, kt) do { const char* _g = (const char*)((BASE) + (size_t)(br) * K + (size_t)(kt) * G_BK); \
;     _Pragma("unroll") for (int _i = 0; _i < 2; ++_i) { \
;       __builtin_amdgcn_global_load_lds((const unsigned*)(_g + (size_t)_i * 128 * K + sg_off), (unsigned*)((char*)(P) + wid * 1024 + _i * 8192), 16, 0, 0); } } while (0)
; #define LDA(dst, b, h) _Pragma("unroll") for (int m = 0; m < 4; ++m) _Pragma("unroll") for (int k = 0; k < 2; ++k) \
;     dst[m][k] = *reinterpret_cast<const bf16x8*>((const char*)shm + aoff + (((b) * 2 + (h)) * 16384 + m * 2048 + k * 1024))
; #define LDB(dst, b, h) _Pragma("unroll") for (int n = 0; n < 2; ++n) _Pragma("unroll") for (int k = 0; k < 2; ++k) \
;     dst[n][k] = *reinterpret_cast<const bf16x8*>((const char*)shm + boff + (((b) * 2 + (h)) * 16384 + n * 2048 + k * 1024))
; #define WAIT_V(n) asm volatile("s_waitcnt vmcnt(" #n ")" ::: "memory")
; #define WAIT_L(n) asm volatile("s_waitcnt lgkmcnt(" #n ")" ::: "memory")
; #define BAR __builtin_amdgcn_s_barrier()
; #define SCHED __builtin_amdgcn_sched_barrier(0)
; template <class Epi>
; __device__ __forceinline__ void gemm_phase(const bfr* __restrict__ A, int lda, const bfr* __restrict__ Bt, int K,
;                                            int nM, int nN, const Epi& epi, bfr* shm, int wv, int nMfull, int ksplit) {
;     ...
;     for (int t = 0; t < nt - 2; t += 2) {
;       LDB(B0, 0, 0); SCHED; LDA(At, 0, 0); STAGE(SA(1, 1), Ak, brow + G_HALF, t + 1);
;       WAIT_L(8); BAR; WAIT_L(0); MMA(0, 0, At, B0); BAR; SCHED;
;       LDB(B1, 0, 1); STAGE(SB(0, 0), Bk, bcol, t + 2);
;       BAR; WAIT_L(0); MMA(0, 1, At, B1); BAR;
;       LDA(At, 0, 1); STAGE(SA(0, 0), Ak, brow, t + 2);
;       BAR; WAIT_L(0); MMA(1, 0, At, B0); BAR; SCHED;
;       STAGE(SB(0, 1), Bk, bcol + G_HALF, t + 2);
;       WAIT_V(6); BAR; MMA(1, 1, At, B1); BAR;
;       LDB(B0, 1, 0); SCHED; LDA(At, 1, 0); STAGE(SA(0, 1), Ak, brow + G_HALF, t + 2);
;       WAIT_L(8); BAR; WAIT_L(0); MMA(0, 0, At, B0); BAR; SCHED;
;       LDB(B1, 1, 1); STAGE(SB(1, 0), Bk, bcol, t + 3);
;       BAR; WAIT_L(0); MMA(0, 1, At, B1); BAR;
;       LDA(At, 1, 1); STAGE(SA(1, 0), Ak, brow, t + 3);
;       BAR; WAIT_L(0); MMA(1, 0, At, B0); BAR; SCHED;
;       STAGE(SB(1, 1), Bk, bcol + G_HALF, t + 3);
;       WAIT_V(6); BAR; MMA(1, 1, At, B1); BAR;
;     }
	ds_read_b128 v[148:151], v137 offset:32768
	ds_read_b128 v[152:155], v137 offset:33792
	ds_read_b128 v[162:165], v137 offset:34816
	ds_read_b128 v[166:169], v137 offset:35840
	ds_read_b128 v[170:173], v129 offset:32768
	ds_read_b128 v[174:177], v129 offset:33792
	ds_read_b128 v[178:181], v129 offset:34816
	ds_read_b128 v[182:185], v129 offset:35840
	ds_read_b128 v[186:189], v129 offset:36864
	ds_read_b128 v[190:193], v129 offset:37888
	ds_read_b128 v[194:197], v129 offset:38912
	ds_read_b128 v[198:201], v129 offset:39936
	ds_read_b128 v[202:205], v137 offset:49152
	ds_read_b128 v[206:209], v137 offset:50176
	ds_read_b128 v[210:213], v137 offset:51200
	ds_read_b128 v[214:217], v137 offset:52224
	s_mov_b32 m0, s22
	v_lshl_add_u64 v[226:227], v[142:143], 0, s[12:13]
	global_load_lds_dwordx4 v[226:227], off
	s_mov_b32 m0, s23
	v_lshl_add_u64 v[222:223], v[142:143], 0, s[14:15]
	global_load_lds_dwordx4 v[222:223], off
	s_waitcnt lgkmcnt(0)
	s_barrier
	v_mfma_f32_16x16x32_bf16 v[124:127], v[170:173], v[148:151], v[124:127]
	v_mfma_f32_16x16x32_bf16 v[120:123], v[170:173], v[162:165], v[120:123]
	v_mfma_f32_16x16x32_bf16 v[116:119], v[178:181], v[148:151], v[116:119]
	v_mfma_f32_16x16x32_bf16 v[112:115], v[178:181], v[162:165], v[112:115]
	v_mfma_f32_16x16x32_bf16 v[108:111], v[186:189], v[148:151], v[108:111]
	v_mfma_f32_16x16x32_bf16 v[104:107], v[186:189], v[162:165], v[104:107]
	v_mfma_f32_16x16x32_bf16 v[100:103], v[194:197], v[148:151], v[100:103]
	v_mfma_f32_16x16x32_bf16 v[96:99], v[194:197], v[162:165], v[96:99]
	v_mfma_f32_16x16x32_bf16 v[124:127], v[174:177], v[152:155], v[124:127]
	v_mfma_f32_16x16x32_bf16 v[120:123], v[174:177], v[166:169], v[120:123]
	v_mfma_f32_16x16x32_bf16 v[116:119], v[182:185], v[152:155], v[116:119]
	v_mfma_f32_16x16x32_bf16 v[112:115], v[182:185], v[166:169], v[112:115]
	v_mfma_f32_16x16x32_bf16 v[108:111], v[190:193], v[152:155], v[108:111]
	v_mfma_f32_16x16x32_bf16 v[104:107], v[190:193], v[166:169], v[104:107]
	v_mfma_f32_16x16x32_bf16 v[100:103], v[198:201], v[152:155], v[100:103]
	v_mfma_f32_16x16x32_bf16 v[96:99], v[198:201], v[166:169], v[96:99]
	v_mfma_f32_16x16x32_bf16 v[92:95], v[170:173], v[202:205], v[92:95]
	v_mfma_f32_16x16x32_bf16 v[88:91], v[170:173], v[210:213], v[88:91]
	v_mfma_f32_16x16x32_bf16 v[84:87], v[178:181], v[202:205], v[84:87]
	v_mfma_f32_16x16x32_bf16 v[80:83], v[178:181], v[210:213], v[80:83]
	v_mfma_f32_16x16x32_bf16 v[76:79], v[186:189], v[202:205], v[76:79]
	v_mfma_f32_16x16x32_bf16 v[72:75], v[186:189], v[210:213], v[72:75]
	v_mfma_f32_16x16x32_bf16 v[68:71], v[194:197], v[202:205], v[68:71]
	v_mfma_f32_16x16x32_bf16 v[64:67], v[194:197], v[210:213], v[64:67]
	v_mfma_f32_16x16x32_bf16 v[92:95], v[174:177], v[206:209], v[92:95]
	v_mfma_f32_16x16x32_bf16 v[88:91], v[174:177], v[214:217], v[88:91]
	v_mfma_f32_16x16x32_bf16 v[84:87], v[182:185], v[206:209], v[84:87]
	v_mfma_f32_16x16x32_bf16 v[80:83], v[182:185], v[214:217], v[80:83]
	v_mfma_f32_16x16x32_bf16 v[76:79], v[190:193], v[206:209], v[76:79]
	v_mfma_f32_16x16x32_bf16 v[72:75], v[190:193], v[214:217], v[72:75]
	v_mfma_f32_16x16x32_bf16 v[68:71], v[198:201], v[206:209], v[68:71]
	v_mfma_f32_16x16x32_bf16 v[64:67], v[198:201], v[214:217], v[64:67]
	s_barrier
	ds_read_b128 v[170:173], v129 offset:49152
	ds_read_b128 v[174:177], v129 offset:50176
	ds_read_b128 v[178:181], v129 offset:51200
	ds_read_b128 v[182:185], v129 offset:52224
	ds_read_b128 v[186:189], v129 offset:53248
	ds_read_b128 v[190:193], v129 offset:54272
	ds_read_b128 v[194:197], v129 offset:55296
	ds_read_b128 v[198:201], v129 offset:56320
	s_mov_b32 m0, s24
	v_lshl_add_u64 v[224:225], v[218:219], 0, s[16:17]
	global_load_lds_dwordx4 v[224:225], off
	s_mov_b32 m0, s25
	v_lshl_add_u64 v[226:227], v[218:219], 0, s[18:19]
	global_load_lds_dwordx4 v[226:227], off
	s_mov_b32 m0, s28
	v_lshl_add_u64 v[222:223], v[142:143], 0, s[16:17]
	global_load_lds_dwordx4 v[222:223], off
	s_mov_b32 m0, s20
	v_lshl_add_u64 v[224:225], v[142:143], 0, s[18:19]
	global_load_lds_dwordx4 v[224:225], off
	s_mov_b32 m0, s21
	s_mov_b64 s[42:43], 0x40180
	v_lshl_add_u64 v[226:227], v[218:219], 0, s[42:43]
	global_load_lds_dwordx4 v[226:227], off
	s_mov_b32 m0, s29
	s_mov_b64 s[42:43], 0x60180
	v_lshl_add_u64 v[222:223], v[218:219], 0, s[42:43]
	global_load_lds_dwordx4 v[222:223], off
	s_waitcnt vmcnt(6)
	s_waitcnt lgkmcnt(0)
	s_barrier
	v_mfma_f32_16x16x32_bf16 v[60:63], v[170:173], v[148:151], v[60:63]
	v_mfma_f32_16x16x32_bf16 v[56:59], v[170:173], v[162:165], v[56:59]
	v_mfma_f32_16x16x32_bf16 v[52:55], v[178:181], v[148:151], v[52:55]
	v_mfma_f32_16x16x32_bf16 v[48:51], v[178:181], v[162:165], v[48:51]
	v_mfma_f32_16x16x32_bf16 v[44:47], v[186:189], v[148:151], v[44:47]
	v_mfma_f32_16x16x32_bf16 v[40:43], v[186:189], v[162:165], v[40:43]
	v_mfma_f32_16x16x32_bf16 v[36:39], v[194:197], v[148:151], v[36:39]
	v_mfma_f32_16x16x32_bf16 v[32:35], v[194:197], v[162:165], v[32:35]
	v_mfma_f32_16x16x32_bf16 v[60:63], v[174:177], v[152:155], v[60:63]
	v_mfma_f32_16x16x32_bf16 v[56:59], v[174:177], v[166:169], v[56:59]
	v_mfma_f32_16x16x32_bf16 v[52:55], v[182:185], v[152:155], v[52:55]
	v_mfma_f32_16x16x32_bf16 v[48:51], v[182:185], v[166:169], v[48:51]
	v_mfma_f32_16x16x32_bf16 v[44:47], v[190:193], v[152:155], v[44:47]
	v_mfma_f32_16x16x32_bf16 v[40:43], v[190:193], v[166:169], v[40:43]
	v_mfma_f32_16x16x32_bf16 v[36:39], v[198:201], v[152:155], v[36:39]
	v_mfma_f32_16x16x32_bf16 v[32:35], v[198:201], v[166:169], v[32:35]
	v_mfma_f32_16x16x32_bf16 v[28:31], v[170:173], v[202:205], v[28:31]
	v_mfma_f32_16x16x32_bf16 v[24:27], v[170:173], v[210:213], v[24:27]
	v_mfma_f32_16x16x32_bf16 v[20:23], v[178:181], v[202:205], v[20:23]
	v_mfma_f32_16x16x32_bf16 v[16:19], v[178:181], v[210:213], v[16:19]
	v_mfma_f32_16x16x32_bf16 v[12:15], v[186:189], v[202:205], v[12:15]
	v_mfma_f32_16x16x32_bf16 v[8:11], v[186:189], v[210:213], v[8:11]
	v_mfma_f32_16x16x32_bf16 v[4:7], v[194:197], v[202:205], v[4:7]
	v_mfma_f32_16x16x32_bf16 v[0:3], v[194:197], v[210:213], v[0:3]
	v_mfma_f32_16x16x32_bf16 v[28:31], v[174:177], v[206:209], v[28:31]
	v_mfma_f32_16x16x32_bf16 v[24:27], v[174:177], v[214:217], v[24:27]
	v_mfma_f32_16x16x32_bf16 v[20:23], v[182:185], v[206:209], v[20:23]
	v_mfma_f32_16x16x32_bf16 v[16:19], v[182:185], v[214:217], v[16:19]
	v_mfma_f32_16x16x32_bf16 v[12:15], v[190:193], v[206:209], v[12:15]
	v_mfma_f32_16x16x32_bf16 v[8:11], v[190:193], v[214:217], v[8:11]
	v_mfma_f32_16x16x32_bf16 v[4:7], v[198:201], v[206:209], v[4:7]
	v_mfma_f32_16x16x32_bf16 v[0:3], v[198:201], v[214:217], v[0:3]
	s_add_i32 s40, s40, 2
	s_add_u32 s2, s2, 0x100
	s_addc_u32 s3, s3, 0
	s_add_u32 s36, s36, 0x100
	s_addc_u32 s37, s37, 0
	s_cmp_ge_i32 s40, s39
	s_barrier
	s_cbranch_scc0 .LBB0_1086

; #define STAGE(P, BASE, br, kt) do { const char* _g = (const char*)((BASE) + (size_t)(br) * K + (size_t)(kt) * G_BK); \
;     _Pragma("unroll") for (int _i = 0; _i < 2; ++_i) { \
;       __builtin_amdgcn_global_load_lds((const unsigned*)(_g + (size_t)_i * 128 * K + sg_off), (unsigned*)((char*)(P) + wid * 1024 + _i * 8192), 16, 0, 0); } } while (0)
; #define LDA(dst, b, h) _Pragma("unroll") for (int m = 0; m < 4; ++m) _Pragma("unroll") for (int k = 0; k < 2; ++k) \
;     dst[m][k] = *reinterpret_cast<const bf16x8*>((const char*)shm + aoff + (((b) * 2 + (h)) * 16384 + m * 2048 + k * 1024))
; #define LDB(dst, b, h) _Pragma("unroll") for (int n = 0; n < 2; ++n) _Pragma("unroll") for (int k = 0; k < 2; ++k) \
;     dst[n][k] = *reinterpret_cast<const bf16x8*>((const char*)shm + boff + (((b) * 2 + (h)) * 16384 + n * 2048 + k * 1024))
; #define WAIT_V(n) asm volatile("s_waitcnt vmcnt(" #n ")" ::: "memory")
; #define WAIT_L(n) asm volatile("s_waitcnt lgkmcnt(" #n ")" ::: "memory")
; #define BAR __builtin_amdgcn_s_barrier()
; #define SCHED __builtin_amdgcn_sched_barrier(0)
; template <class Epi>
; __device__ __forceinline__ void gemm_phase(const bfr* __restrict__ A, int lda, const bfr* __restrict__ Bt, int K,
;                                            int nM, int nN, const Epi& epi, bfr* shm, int wv, int nMfull, int ksplit) {
;     ...
;     for (int t = 0; t < nt - 2; t += 2) {
;       LDB(B0, 0, 0); SCHED; LDA(At, 0, 0); STAGE(SA(1, 1), Ak, brow + G_HALF, t + 1);
;       WAIT_L(8); BAR; WAIT_L(0); MMA(0, 0, At, B0); BAR; SCHED;
;       LDB(B1, 0, 1); STAGE(SB(0, 0), Bk, bcol, t + 2);
;       BAR; WAIT_L(0); MMA(0, 1, At, B1); BAR;
;       LDA(At, 0, 1); STAGE(SA(0, 0), Ak, brow, t + 2);
;       BAR; WAIT_L(0); MMA(1, 0, At, B0); BAR; SCHED;
;       STAGE(SB(0, 1), Bk, bcol + G_HALF, t + 2);
;       WAIT_V(6); BAR; MMA(1, 1, At, B1); BAR;
;       LDB(B0, 1, 0); SCHED; LDA(At, 1, 0); STAGE(SA(0, 1), Ak, brow + G_HALF, t + 2);
;       WAIT_L(8); BAR; WAIT_L(0); MMA(0, 0, At, B0); BAR; SCHED;
;       LDB(B1, 1, 1); STAGE(SB(1, 0), Bk, bcol, t + 3);
;       BAR; WAIT_L(0); MMA(0, 1, At, B1); BAR;
;       LDA(At, 1, 1); STAGE(SA(1, 0), Ak, brow, t + 3);
;       BAR; WAIT_L(0); MMA(1, 0, At, B0); BAR; SCHED;
;       STAGE(SB(1, 1), Bk, bcol + G_HALF, t + 3);
;       WAIT_V(6); BAR; MMA(1, 1, At, B1); BAR;
;     }
.LBB0_1216:
	ds_read_b128 v[142:145], v169
	ds_read_b128 v[146:149], v169 offset:1024
	ds_read_b128 v[150:153], v169 offset:2048
	ds_read_b128 v[154:157], v169 offset:3072
	ds_read_b128 v[158:161], v168
	ds_read_b128 v[162:165], v168 offset:1024
	ds_read_b128 v[174:177], v168 offset:2048
	ds_read_b128 v[178:181], v168 offset:3072
	ds_read_b128 v[182:185], v168 offset:4096
	ds_read_b128 v[186:189], v168 offset:5120
	ds_read_b128 v[190:193], v168 offset:6144
	ds_read_b128 v[194:197], v168 offset:7168
	ds_read_b128 v[198:201], v169 offset:16384
	ds_read_b128 v[202:205], v169 offset:17408
	ds_read_b128 v[206:209], v169 offset:18432
	ds_read_b128 v[210:213], v169 offset:19456
	v_lshl_add_u64 v[166:167], s[44:45], 0, v[140:141]
	v_lshl_add_u64 v[214:215], s[42:43], 0, v[140:141]
	s_mov_b32 m0, s82
	s_mov_b64 s[46:47], 0x40080
	v_lshl_add_u64 v[218:219], v[166:167], 0, s[46:47]
	global_load_lds_dwordx4 v[218:219], off
	s_mov_b32 m0, s83
	s_mov_b64 s[46:47], 0x60080
	v_lshl_add_u64 v[220:221], v[166:167], 0, s[46:47]
	global_load_lds_dwordx4 v[220:221], off
	s_waitcnt lgkmcnt(0)
	s_barrier
	v_mfma_f32_16x16x32_bf16 v[124:127], v[158:161], v[142:145], v[124:127]
	v_mfma_f32_16x16x32_bf16 v[120:123], v[158:161], v[150:153], v[120:123]
	v_mfma_f32_16x16x32_bf16 v[116:119], v[174:177], v[142:145], v[116:119]
	v_mfma_f32_16x16x32_bf16 v[112:115], v[174:177], v[150:153], v[112:115]
	v_mfma_f32_16x16x32_bf16 v[108:111], v[182:185], v[142:145], v[108:111]
	v_mfma_f32_16x16x32_bf16 v[104:107], v[182:185], v[150:153], v[104:107]
	v_mfma_f32_16x16x32_bf16 v[100:103], v[190:193], v[142:145], v[100:103]
	v_mfma_f32_16x16x32_bf16 v[96:99], v[190:193], v[150:153], v[96:99]
	v_mfma_f32_16x16x32_bf16 v[124:127], v[162:165], v[146:149], v[124:127]
	v_mfma_f32_16x16x32_bf16 v[120:123], v[162:165], v[154:157], v[120:123]
	v_mfma_f32_16x16x32_bf16 v[116:119], v[178:181], v[146:149], v[116:119]
	v_mfma_f32_16x16x32_bf16 v[112:115], v[178:181], v[154:157], v[112:115]
	v_mfma_f32_16x16x32_bf16 v[108:111], v[186:189], v[146:149], v[108:111]
	v_mfma_f32_16x16x32_bf16 v[104:107], v[186:189], v[154:157], v[104:107]
	v_mfma_f32_16x16x32_bf16 v[100:103], v[194:197], v[146:149], v[100:103]
	v_mfma_f32_16x16x32_bf16 v[96:99], v[194:197], v[154:157], v[96:99]
	v_mfma_f32_16x16x32_bf16 v[92:95], v[158:161], v[198:201], v[92:95]
	v_mfma_f32_16x16x32_bf16 v[88:91], v[158:161], v[206:209], v[88:91]
	v_mfma_f32_16x16x32_bf16 v[84:87], v[174:177], v[198:201], v[84:87]
	v_mfma_f32_16x16x32_bf16 v[80:83], v[174:177], v[206:209], v[80:83]
	v_mfma_f32_16x16x32_bf16 v[76:79], v[182:185], v[198:201], v[76:79]
	v_mfma_f32_16x16x32_bf16 v[72:75], v[182:185], v[206:209], v[72:75]
	v_mfma_f32_16x16x32_bf16 v[68:71], v[190:193], v[198:201], v[68:71]
	v_mfma_f32_16x16x32_bf16 v[64:67], v[190:193], v[206:209], v[64:67]
	v_mfma_f32_16x16x32_bf16 v[92:95], v[162:165], v[202:205], v[92:95]
	v_mfma_f32_16x16x32_bf16 v[88:91], v[162:165], v[210:213], v[88:91]
	v_mfma_f32_16x16x32_bf16 v[84:87], v[178:181], v[202:205], v[84:87]
	v_mfma_f32_16x16x32_bf16 v[80:83], v[178:181], v[210:213], v[80:83]
	v_mfma_f32_16x16x32_bf16 v[76:79], v[186:189], v[202:205], v[76:79]
	v_mfma_f32_16x16x32_bf16 v[72:75], v[186:189], v[210:213], v[72:75]
	v_mfma_f32_16x16x32_bf16 v[68:71], v[194:197], v[202:205], v[68:71]
	v_mfma_f32_16x16x32_bf16 v[64:67], v[194:197], v[210:213], v[64:67]
	s_barrier
	ds_read_b128 v[158:161], v168 offset:16384
	ds_read_b128 v[162:165], v168 offset:17408
	ds_read_b128 v[174:177], v168 offset:18432
	ds_read_b128 v[178:181], v168 offset:19456
	ds_read_b128 v[182:185], v168 offset:20480
	ds_read_b128 v[186:189], v168 offset:21504
	ds_read_b128 v[190:193], v168 offset:22528
	ds_read_b128 v[194:197], v168 offset:23552
	s_mov_b32 m0, s84
	v_lshl_add_u64 v[222:223], v[214:215], 0, s[78:79]
	global_load_lds_dwordx4 v[222:223], off
	s_mov_b32 m0, s85
	v_lshl_add_u64 v[218:219], v[214:215], 0, s[80:81]
	global_load_lds_dwordx4 v[218:219], off
	s_mov_b32 m0, s71
	v_lshl_add_u64 v[220:221], v[166:167], 0, s[78:79]
	global_load_lds_dwordx4 v[220:221], off
	s_mov_b32 m0, s87
	v_lshl_add_u64 v[222:223], v[166:167], 0, s[80:81]
	global_load_lds_dwordx4 v[222:223], off
	s_mov_b32 m0, s90
	v_lshl_add_u64 v[218:219], v[214:215], 0, s[88:89]
	global_load_lds_dwordx4 v[218:219], off
	s_mov_b32 m0, s91
	v_lshl_add_u64 v[220:221], v[214:215], 0, s[34:35]
	global_load_lds_dwordx4 v[220:221], off
	s_waitcnt vmcnt(6)
	s_waitcnt lgkmcnt(0)
	s_barrier
	v_mfma_f32_16x16x32_bf16 v[60:63], v[158:161], v[142:145], v[60:63]
	v_mfma_f32_16x16x32_bf16 v[56:59], v[158:161], v[150:153], v[56:59]
	v_mfma_f32_16x16x32_bf16 v[52:55], v[174:177], v[142:145], v[52:55]
	v_mfma_f32_16x16x32_bf16 v[48:51], v[174:177], v[150:153], v[48:51]
	v_mfma_f32_16x16x32_bf16 v[44:47], v[182:185], v[142:145], v[44:47]
	v_mfma_f32_16x16x32_bf16 v[40:43], v[182:185], v[150:153], v[40:43]
	v_mfma_f32_16x16x32_bf16 v[36:39], v[190:193], v[142:145], v[36:39]
	v_mfma_f32_16x16x32_bf16 v[32:35], v[190:193], v[150:153], v[32:35]
	v_mfma_f32_16x16x32_bf16 v[60:63], v[162:165], v[146:149], v[60:63]
	v_mfma_f32_16x16x32_bf16 v[56:59], v[162:165], v[154:157], v[56:59]
	v_mfma_f32_16x16x32_bf16 v[52:55], v[178:181], v[146:149], v[52:55]
	v_mfma_f32_16x16x32_bf16 v[48:51], v[178:181], v[154:157], v[48:51]
	v_mfma_f32_16x16x32_bf16 v[44:47], v[186:189], v[146:149], v[44:47]
	v_mfma_f32_16x16x32_bf16 v[40:43], v[186:189], v[154:157], v[40:43]
	v_mfma_f32_16x16x32_bf16 v[36:39], v[194:197], v[146:149], v[36:39]
	v_mfma_f32_16x16x32_bf16 v[32:35], v[194:197], v[154:157], v[32:35]
	v_mfma_f32_16x16x32_bf16 v[28:31], v[158:161], v[198:201], v[28:31]
	v_mfma_f32_16x16x32_bf16 v[24:27], v[158:161], v[206:209], v[24:27]
	v_mfma_f32_16x16x32_bf16 v[20:23], v[174:177], v[198:201], v[20:23]
	v_mfma_f32_16x16x32_bf16 v[16:19], v[174:177], v[206:209], v[16:19]
	v_mfma_f32_16x16x32_bf16 v[12:15], v[182:185], v[198:201], v[12:15]
	v_mfma_f32_16x16x32_bf16 v[8:11], v[182:185], v[206:209], v[8:11]
	v_mfma_f32_16x16x32_bf16 v[4:7], v[190:193], v[198:201], v[4:7]
	v_mfma_f32_16x16x32_bf16 v[0:3], v[190:193], v[206:209], v[0:3]
	v_mfma_f32_16x16x32_bf16 v[28:31], v[162:165], v[202:205], v[28:31]
	v_mfma_f32_16x16x32_bf16 v[24:27], v[162:165], v[210:213], v[24:27]
	v_mfma_f32_16x16x32_bf16 v[20:23], v[178:181], v[202:205], v[20:23]
	v_mfma_f32_16x16x32_bf16 v[16:19], v[178:181], v[210:213], v[16:19]
	v_mfma_f32_16x16x32_bf16 v[12:15], v[186:189], v[202:205], v[12:15]
	v_mfma_f32_16x16x32_bf16 v[8:11], v[186:189], v[210:213], v[8:11]
	v_mfma_f32_16x16x32_bf16 v[4:7], v[194:197], v[202:205], v[4:7]
	v_mfma_f32_16x16x32_bf16 v[0:3], v[194:197], v[210:213], v[0:3]
	s_barrier
; #define STAGE(P, BASE, br, kt) do { const char* _g = (const char*)((BASE) + (size_t)(br) * K + (size_t)(kt) * G_BK); \
;     _Pragma("unroll") for (int _i = 0; _i < 2; ++_i) { \
;       __builtin_amdgcn_global_load_lds((const unsigned*)(_g + (size_t)_i * 128 * K + sg_off), (unsigned*)((char*)(P) + wid * 1024 + _i * 8192), 16, 0, 0); } } while (0)
; #define LDA(dst, b, h) _Pragma("unroll") for (int m = 0; m < 4; ++m) _Pragma("unroll") for (int k = 0; k < 2; ++k) \
;     dst[m][k] = *reinterpret_cast<const bf16x8*>((const char*)shm + aoff + (((b) * 2 + (h)) * 16384 + m * 2048 + k * 1024))
; #define LDB(dst, b, h) _Pragma("unroll") for (int n = 0; n < 2; ++n) _Pragma("unroll") for (int k = 0; k < 2; ++k) \
;     dst[n][k] = *reinterpret_cast<const bf16x8*>((const char*)shm + boff + (((b) * 2 + (h)) * 16384 + n * 2048 + k * 1024))
; #define WAIT_V(n) asm volatile("s_waitcnt vmcnt(" #n ")" ::: "memory")
; #define WAIT_L(n) asm volatile("s_waitcnt lgkmcnt(" #n ")" ::: "memory")
; #define BAR __builtin_amdgcn_s_barrier()
; #define SCHED __builtin_amdgcn_sched_barrier(0)
; template <class Epi>
; __device__ __forceinline__ void gemm_phase(const bfr* __restrict__ A, int lda, const bfr* __restrict__ Bt, int K,
;                                            int nM, int nN, const Epi& epi, bfr* shm, int wv, int nMfull, int ksplit) {
;     ...
;     for (int t = 0; t < nt - 2; t += 2) {
;       LDB(B0, 0, 0); SCHED; LDA(At, 0, 0); STAGE(SA(1, 1), Ak, brow + G_HALF, t + 1);
;       WAIT_L(8); BAR; WAIT_L(0); MMA(0, 0, At, B0); BAR; SCHED;
;       LDB(B1, 0, 1); STAGE(SB(0, 0), Bk, bcol, t + 2);
;       BAR; WAIT_L(0); MMA(0, 1, At, B1); BAR;
;       LDA(At, 0, 1); STAGE(SA(0, 0), Ak, brow, t + 2);
;       BAR; WAIT_L(0); MMA(1, 0, At, B0); BAR; SCHED;
;       STAGE(SB(0, 1), Bk, bcol + G_HALF, t + 2);
;       WAIT_V(6); BAR; MMA(1, 1, At, B1); BAR;
;       LDB(B0, 1, 0); SCHED; LDA(At, 1, 0); STAGE(SA(0, 1), Ak, brow + G_HALF, t + 2);
;       WAIT_L(8); BAR; WAIT_L(0); MMA(0, 0, At, B0); BAR; SCHED;
;       LDB(B1, 1, 1); STAGE(SB(1, 0), Bk, bcol, t + 3);
;       BAR; WAIT_L(0); MMA(0, 1, At, B1); BAR;
;       LDA(At, 1, 1); STAGE(SA(1, 0), Ak, brow, t + 3);
;       BAR; WAIT_L(0); MMA(1, 0, At, B0); BAR; SCHED;
;       STAGE(SB(1, 1), Bk, bcol + G_HALF, t + 3);
;       WAIT_V(6); BAR; MMA(1, 1, At, B1); BAR;
;     }
	ds_read_b128 v[142:145], v169 offset:32768
	ds_read_b128 v[146:149], v169 offset:33792
	ds_read_b128 v[150:153], v169 offset:34816
	ds_read_b128 v[154:157], v169 offset:35840
	ds_read_b128 v[158:161], v168 offset:32768
	ds_read_b128 v[162:165], v168 offset:33792
	ds_read_b128 v[174:177], v168 offset:34816
	ds_read_b128 v[178:181], v168 offset:35840
	ds_read_b128 v[182:185], v168 offset:36864
	ds_read_b128 v[186:189], v168 offset:37888
	ds_read_b128 v[190:193], v168 offset:38912
	ds_read_b128 v[194:197], v168 offset:39936
	ds_read_b128 v[198:201], v169 offset:49152
	ds_read_b128 v[202:205], v169 offset:50176
	ds_read_b128 v[206:209], v169 offset:51200
	ds_read_b128 v[210:213], v169 offset:52224
	s_mov_b32 m0, s92
	v_lshl_add_u64 v[222:223], v[166:167], 0, s[88:89]
	global_load_lds_dwordx4 v[222:223], off
	s_mov_b32 m0, s93
	v_lshl_add_u64 v[218:219], v[166:167], 0, s[34:35]
	global_load_lds_dwordx4 v[218:219], off
	s_waitcnt lgkmcnt(0)
	s_barrier
	v_mfma_f32_16x16x32_bf16 v[124:127], v[158:161], v[142:145], v[124:127]
	v_mfma_f32_16x16x32_bf16 v[120:123], v[158:161], v[150:153], v[120:123]
	v_mfma_f32_16x16x32_bf16 v[116:119], v[174:177], v[142:145], v[116:119]
	v_mfma_f32_16x16x32_bf16 v[112:115], v[174:177], v[150:153], v[112:115]
	v_mfma_f32_16x16x32_bf16 v[108:111], v[182:185], v[142:145], v[108:111]
	v_mfma_f32_16x16x32_bf16 v[104:107], v[182:185], v[150:153], v[104:107]
	v_mfma_f32_16x16x32_bf16 v[100:103], v[190:193], v[142:145], v[100:103]
	v_mfma_f32_16x16x32_bf16 v[96:99], v[190:193], v[150:153], v[96:99]
	v_mfma_f32_16x16x32_bf16 v[124:127], v[162:165], v[146:149], v[124:127]
	v_mfma_f32_16x16x32_bf16 v[120:123], v[162:165], v[154:157], v[120:123]
	v_mfma_f32_16x16x32_bf16 v[116:119], v[178:181], v[146:149], v[116:119]
	v_mfma_f32_16x16x32_bf16 v[112:115], v[178:181], v[154:157], v[112:115]
	v_mfma_f32_16x16x32_bf16 v[108:111], v[186:189], v[146:149], v[108:111]
	v_mfma_f32_16x16x32_bf16 v[104:107], v[186:189], v[154:157], v[104:107]
	v_mfma_f32_16x16x32_bf16 v[100:103], v[194:197], v[146:149], v[100:103]
	v_mfma_f32_16x16x32_bf16 v[96:99], v[194:197], v[154:157], v[96:99]
	v_mfma_f32_16x16x32_bf16 v[92:95], v[158:161], v[198:201], v[92:95]
	v_mfma_f32_16x16x32_bf16 v[88:91], v[158:161], v[206:209], v[88:91]
	v_mfma_f32_16x16x32_bf16 v[84:87], v[174:177], v[198:201], v[84:87]
	v_mfma_f32_16x16x32_bf16 v[80:83], v[174:177], v[206:209], v[80:83]
	v_mfma_f32_16x16x32_bf16 v[76:79], v[182:185], v[198:201], v[76:79]
	v_mfma_f32_16x16x32_bf16 v[72:75], v[182:185], v[206:209], v[72:75]
	v_mfma_f32_16x16x32_bf16 v[68:71], v[190:193], v[198:201], v[68:71]
	v_mfma_f32_16x16x32_bf16 v[64:67], v[190:193], v[206:209], v[64:67]
	v_mfma_f32_16x16x32_bf16 v[92:95], v[162:165], v[202:205], v[92:95]
	v_mfma_f32_16x16x32_bf16 v[88:91], v[162:165], v[210:213], v[88:91]
	v_mfma_f32_16x16x32_bf16 v[84:87], v[178:181], v[202:205], v[84:87]
	v_mfma_f32_16x16x32_bf16 v[80:83], v[178:181], v[210:213], v[80:83]
	v_mfma_f32_16x16x32_bf16 v[76:79], v[186:189], v[202:205], v[76:79]
	v_mfma_f32_16x16x32_bf16 v[72:75], v[186:189], v[210:213], v[72:75]
	v_mfma_f32_16x16x32_bf16 v[68:71], v[194:197], v[202:205], v[68:71]
	v_mfma_f32_16x16x32_bf16 v[64:67], v[194:197], v[210:213], v[64:67]
	s_barrier
	ds_read_b128 v[158:161], v168 offset:49152
	ds_read_b128 v[162:165], v168 offset:50176
	ds_read_b128 v[174:177], v168 offset:51200
	ds_read_b128 v[178:181], v168 offset:52224
	ds_read_b128 v[182:185], v168 offset:53248
	ds_read_b128 v[186:189], v168 offset:54272
	ds_read_b128 v[190:193], v168 offset:55296
	ds_read_b128 v[194:197], v168 offset:56320
	s_mov_b32 m0, s94
	v_lshl_add_u64 v[220:221], v[214:215], 0, s[20:21]
	global_load_lds_dwordx4 v[220:221], off
	s_mov_b32 m0, s95
	v_lshl_add_u64 v[222:223], v[214:215], 0, s[22:23]
	global_load_lds_dwordx4 v[222:223], off
	s_mov_b32 m0, s96
	v_lshl_add_u64 v[218:219], v[166:167], 0, s[20:21]
	global_load_lds_dwordx4 v[218:219], off
	s_mov_b32 m0, s97
	v_lshl_add_u64 v[220:221], v[166:167], 0, s[22:23]
	global_load_lds_dwordx4 v[220:221], off
	s_mov_b32 m0, s0
	s_mov_b64 s[46:47], 0x40180
	v_lshl_add_u64 v[222:223], v[214:215], 0, s[46:47]
	global_load_lds_dwordx4 v[222:223], off
	s_mov_b32 m0, s1
	s_mov_b64 s[46:47], 0x60180
	v_lshl_add_u64 v[218:219], v[214:215], 0, s[46:47]
	global_load_lds_dwordx4 v[218:219], off
	s_waitcnt vmcnt(6)
	s_waitcnt lgkmcnt(0)
	s_barrier
	v_mfma_f32_16x16x32_bf16 v[60:63], v[158:161], v[142:145], v[60:63]
	v_mfma_f32_16x16x32_bf16 v[56:59], v[158:161], v[150:153], v[56:59]
	v_mfma_f32_16x16x32_bf16 v[52:55], v[174:177], v[142:145], v[52:55]
	v_mfma_f32_16x16x32_bf16 v[48:51], v[174:177], v[150:153], v[48:51]
	v_mfma_f32_16x16x32_bf16 v[44:47], v[182:185], v[142:145], v[44:47]
	v_mfma_f32_16x16x32_bf16 v[40:43], v[182:185], v[150:153], v[40:43]
	v_mfma_f32_16x16x32_bf16 v[36:39], v[190:193], v[142:145], v[36:39]
	v_mfma_f32_16x16x32_bf16 v[32:35], v[190:193], v[150:153], v[32:35]
	v_mfma_f32_16x16x32_bf16 v[60:63], v[162:165], v[146:149], v[60:63]
	v_mfma_f32_16x16x32_bf16 v[56:59], v[162:165], v[154:157], v[56:59]
	v_mfma_f32_16x16x32_bf16 v[52:55], v[178:181], v[146:149], v[52:55]
	v_mfma_f32_16x16x32_bf16 v[48:51], v[178:181], v[154:157], v[48:51]
	v_mfma_f32_16x16x32_bf16 v[44:47], v[186:189], v[146:149], v[44:47]
	v_mfma_f32_16x16x32_bf16 v[40:43], v[186:189], v[154:157], v[40:43]
	v_mfma_f32_16x16x32_bf16 v[36:39], v[194:197], v[146:149], v[36:39]
	v_mfma_f32_16x16x32_bf16 v[32:35], v[194:197], v[154:157], v[32:35]
	v_mfma_f32_16x16x32_bf16 v[28:31], v[158:161], v[198:201], v[28:31]
	v_mfma_f32_16x16x32_bf16 v[24:27], v[158:161], v[206:209], v[24:27]
	v_mfma_f32_16x16x32_bf16 v[20:23], v[174:177], v[198:201], v[20:23]
	v_mfma_f32_16x16x32_bf16 v[16:19], v[174:177], v[206:209], v[16:19]
	v_mfma_f32_16x16x32_bf16 v[12:15], v[182:185], v[198:201], v[12:15]
	v_mfma_f32_16x16x32_bf16 v[8:11], v[182:185], v[206:209], v[8:11]
	v_mfma_f32_16x16x32_bf16 v[4:7], v[190:193], v[198:201], v[4:7]
	v_mfma_f32_16x16x32_bf16 v[0:3], v[190:193], v[206:209], v[0:3]
	v_mfma_f32_16x16x32_bf16 v[28:31], v[162:165], v[202:205], v[28:31]
	v_mfma_f32_16x16x32_bf16 v[24:27], v[162:165], v[210:213], v[24:27]
	v_mfma_f32_16x16x32_bf16 v[20:23], v[178:181], v[202:205], v[20:23]
	v_mfma_f32_16x16x32_bf16 v[16:19], v[178:181], v[210:213], v[16:19]
	v_mfma_f32_16x16x32_bf16 v[12:15], v[186:189], v[202:205], v[12:15]
	v_mfma_f32_16x16x32_bf16 v[8:11], v[186:189], v[210:213], v[8:11]
	v_mfma_f32_16x16x32_bf16 v[4:7], v[194:197], v[202:205], v[4:7]
	v_mfma_f32_16x16x32_bf16 v[0:3], v[194:197], v[210:213], v[0:3]
	s_add_i32 s39, s39, 2
	s_add_u32 s42, s42, 0x100
	s_addc_u32 s43, s43, 0
	s_add_u32 s44, s44, 0x100
	s_addc_u32 s45, s45, 0
	s_cmp_ge_i32 s39, s31
	s_barrier
	s_cbranch_scc0 .LBB0_1216

; #define STAGE(P, BASE, br, kt) do { const char* _g = (const char*)((BASE) + (size_t)(br) * K + (size_t)(kt) * G_BK); \
;     _Pragma("unroll") for (int _i = 0; _i < 2; ++_i) { \
;       __builtin_amdgcn_global_load_lds((const unsigned*)(_g + (size_t)_i * 128 * K + sg_off), (unsigned*)((char*)(P) + wid * 1024 + _i * 8192), 16, 0, 0); } } while (0)
; #define LDA(dst, b, h) _Pragma("unroll") for (int m = 0; m < 4; ++m) _Pragma("unroll") for (int k = 0; k < 2; ++k) \
;     dst[m][k] = *reinterpret_cast<const bf16x8*>((const char*)shm + aoff + (((b) * 2 + (h)) * 16384 + m * 2048 + k * 1024))
; #define LDB(dst, b, h) _Pragma("unroll") for (int n = 0; n < 2; ++n) _Pragma("unroll") for (int k = 0; k < 2; ++k) \
;     dst[n][k] = *reinterpret_cast<const bf16x8*>((const char*)shm + boff + (((b) * 2 + (h)) * 16384 + n * 2048 + k * 1024))
; #define WAIT_V(n) asm volatile("s_waitcnt vmcnt(" #n ")" ::: "memory")
; #define WAIT_L(n) asm volatile("s_waitcnt lgkmcnt(" #n ")" ::: "memory")
; #define BAR __builtin_amdgcn_s_barrier()
; #define SCHED __builtin_amdgcn_sched_barrier(0)
; template <class Epi>
; __device__ __forceinline__ void gemm_phase(const bfr* __restrict__ A, int lda, const bfr* __restrict__ Bt, int K,
;                                            int nM, int nN, const Epi& epi, bfr* shm, int wv, int nMfull, int ksplit) {
;     ...
;     for (int t = 0; t < nt - 2; t += 2) {
;       LDB(B0, 0, 0); SCHED; LDA(At, 0, 0); STAGE(SA(1, 1), Ak, brow + G_HALF, t + 1);
;       WAIT_L(8); BAR; WAIT_L(0); MMA(0, 0, At, B0); BAR; SCHED;
;       LDB(B1, 0, 1); STAGE(SB(0, 0), Bk, bcol, t + 2);
;       BAR; WAIT_L(0); MMA(0, 1, At, B1); BAR;
;       LDA(At, 0, 1); STAGE(SA(0, 0), Ak, brow, t + 2);
;       BAR; WAIT_L(0); MMA(1, 0, At, B0); BAR; SCHED;
;       STAGE(SB(0, 1), Bk, bcol + G_HALF, t + 2);
;       WAIT_V(6); BAR; MMA(1, 1, At, B1); BAR;
;       LDB(B0, 1, 0); SCHED; LDA(At, 1, 0); STAGE(SA(0, 1), Ak, brow + G_HALF, t + 2);
;       WAIT_L(8); BAR; WAIT_L(0); MMA(0, 0, At, B0); BAR; SCHED;
;       LDB(B1, 1, 1); STAGE(SB(1, 0), Bk, bcol, t + 3);
;       BAR; WAIT_L(0); MMA(0, 1, At, B1); BAR;
;       LDA(At, 1, 1); STAGE(SA(1, 0), Ak, brow, t + 3);
;       BAR; WAIT_L(0); MMA(1, 0, At, B0); BAR; SCHED;
;       STAGE(SB(1, 1), Bk, bcol + G_HALF, t + 3);
;       WAIT_V(6); BAR; MMA(1, 1, At, B1); BAR;
;     }
.LBB0_1327:
	ds_read_b128 v[136:139], v143
	ds_read_b128 v[148:151], v143 offset:1024
	ds_read_b128 v[152:155], v143 offset:2048
	ds_read_b128 v[156:159], v143 offset:3072
	ds_read_b128 v[160:163], v142
	ds_read_b128 v[164:167], v142 offset:1024
	ds_read_b128 v[168:171], v142 offset:2048
	ds_read_b128 v[172:175], v142 offset:3072
	ds_read_b128 v[176:179], v142 offset:4096
	ds_read_b128 v[180:183], v142 offset:5120
	ds_read_b128 v[184:187], v142 offset:6144
	ds_read_b128 v[188:191], v142 offset:7168
	ds_read_b128 v[192:195], v143 offset:16384
	ds_read_b128 v[196:199], v143 offset:17408
	ds_read_b128 v[200:203], v143 offset:18432
	ds_read_b128 v[204:207], v143 offset:19456
	v_lshl_add_u64 v[140:141], s[52:53], 0, v[134:135]
	v_lshl_add_u64 v[208:209], s[50:51], 0, v[134:135]
	s_mov_b32 m0, s90
	s_mov_b64 s[54:55], 0x40080
	v_lshl_add_u64 v[212:213], v[140:141], 0, s[54:55]
	global_load_lds_dwordx4 v[212:213], off
	s_mov_b32 m0, s91
	s_mov_b64 s[54:55], 0x60080
	v_lshl_add_u64 v[214:215], v[140:141], 0, s[54:55]
	global_load_lds_dwordx4 v[214:215], off
	s_waitcnt lgkmcnt(0)
	s_barrier
	v_mfma_f32_16x16x32_bf16 v[124:127], v[160:163], v[136:139], v[124:127]
	v_mfma_f32_16x16x32_bf16 v[120:123], v[160:163], v[152:155], v[120:123]
	v_mfma_f32_16x16x32_bf16 v[116:119], v[168:171], v[136:139], v[116:119]
	v_mfma_f32_16x16x32_bf16 v[112:115], v[168:171], v[152:155], v[112:115]
	v_mfma_f32_16x16x32_bf16 v[108:111], v[176:179], v[136:139], v[108:111]
	v_mfma_f32_16x16x32_bf16 v[104:107], v[176:179], v[152:155], v[104:107]
	v_mfma_f32_16x16x32_bf16 v[100:103], v[184:187], v[136:139], v[100:103]
	v_mfma_f32_16x16x32_bf16 v[96:99], v[184:187], v[152:155], v[96:99]
	v_mfma_f32_16x16x32_bf16 v[124:127], v[164:167], v[148:151], v[124:127]
	v_mfma_f32_16x16x32_bf16 v[120:123], v[164:167], v[156:159], v[120:123]
	v_mfma_f32_16x16x32_bf16 v[116:119], v[172:175], v[148:151], v[116:119]
	v_mfma_f32_16x16x32_bf16 v[112:115], v[172:175], v[156:159], v[112:115]
	v_mfma_f32_16x16x32_bf16 v[108:111], v[180:183], v[148:151], v[108:111]
	v_mfma_f32_16x16x32_bf16 v[104:107], v[180:183], v[156:159], v[104:107]
	v_mfma_f32_16x16x32_bf16 v[100:103], v[188:191], v[148:151], v[100:103]
	v_mfma_f32_16x16x32_bf16 v[96:99], v[188:191], v[156:159], v[96:99]
	v_mfma_f32_16x16x32_bf16 v[92:95], v[160:163], v[192:195], v[92:95]
	v_mfma_f32_16x16x32_bf16 v[88:91], v[160:163], v[200:203], v[88:91]
	v_mfma_f32_16x16x32_bf16 v[84:87], v[168:171], v[192:195], v[84:87]
	v_mfma_f32_16x16x32_bf16 v[80:83], v[168:171], v[200:203], v[80:83]
	v_mfma_f32_16x16x32_bf16 v[76:79], v[176:179], v[192:195], v[76:79]
	v_mfma_f32_16x16x32_bf16 v[72:75], v[176:179], v[200:203], v[72:75]
	v_mfma_f32_16x16x32_bf16 v[68:71], v[184:187], v[192:195], v[68:71]
	v_mfma_f32_16x16x32_bf16 v[64:67], v[184:187], v[200:203], v[64:67]
	v_mfma_f32_16x16x32_bf16 v[92:95], v[164:167], v[196:199], v[92:95]
	v_mfma_f32_16x16x32_bf16 v[88:91], v[164:167], v[204:207], v[88:91]
	v_mfma_f32_16x16x32_bf16 v[84:87], v[172:175], v[196:199], v[84:87]
	v_mfma_f32_16x16x32_bf16 v[80:83], v[172:175], v[204:207], v[80:83]
	v_mfma_f32_16x16x32_bf16 v[76:79], v[180:183], v[196:199], v[76:79]
	v_mfma_f32_16x16x32_bf16 v[72:75], v[180:183], v[204:207], v[72:75]
	v_mfma_f32_16x16x32_bf16 v[68:71], v[188:191], v[196:199], v[68:71]
	v_mfma_f32_16x16x32_bf16 v[64:67], v[188:191], v[204:207], v[64:67]
	s_barrier
	ds_read_b128 v[160:163], v142 offset:16384
	ds_read_b128 v[164:167], v142 offset:17408
	ds_read_b128 v[168:171], v142 offset:18432
	ds_read_b128 v[172:175], v142 offset:19456
	ds_read_b128 v[176:179], v142 offset:20480
	ds_read_b128 v[180:183], v142 offset:21504
	ds_read_b128 v[184:187], v142 offset:22528
	ds_read_b128 v[188:191], v142 offset:23552
	s_mov_b32 m0, s7
	s_mov_b64 s[54:55], 0x2100100
	v_lshl_add_u64 v[216:217], v[208:209], 0, s[54:55]
	global_load_lds_dwordx4 v[216:217], off
	s_mov_b32 m0, s78
	s_mov_b64 s[54:55], 0x2120100
	v_lshl_add_u64 v[212:213], v[208:209], 0, s[54:55]
	global_load_lds_dwordx4 v[212:213], off
	s_mov_b32 m0, s6
	s_mov_b64 s[54:55], 0x100
	v_lshl_add_u64 v[214:215], v[140:141], 0, s[54:55]
	global_load_lds_dwordx4 v[214:215], off
	s_mov_b32 m0, s79
	v_lshl_add_u64 v[216:217], v[140:141], 0, s[16:17]
	global_load_lds_dwordx4 v[216:217], off
	s_mov_b32 m0, s80
	v_lshl_add_u64 v[212:213], v[208:209], 0, s[18:19]
	global_load_lds_dwordx4 v[212:213], off
	s_mov_b32 m0, s81
	v_lshl_add_u64 v[214:215], v[208:209], 0, s[20:21]
	global_load_lds_dwordx4 v[214:215], off
	s_waitcnt vmcnt(6)
	s_waitcnt lgkmcnt(0)
	s_barrier
	v_mfma_f32_16x16x32_bf16 v[60:63], v[160:163], v[136:139], v[60:63]
	v_mfma_f32_16x16x32_bf16 v[56:59], v[160:163], v[152:155], v[56:59]
	v_mfma_f32_16x16x32_bf16 v[52:55], v[168:171], v[136:139], v[52:55]
	v_mfma_f32_16x16x32_bf16 v[48:51], v[168:171], v[152:155], v[48:51]
	v_mfma_f32_16x16x32_bf16 v[44:47], v[176:179], v[136:139], v[44:47]
	v_mfma_f32_16x16x32_bf16 v[40:43], v[176:179], v[152:155], v[40:43]
	v_mfma_f32_16x16x32_bf16 v[36:39], v[184:187], v[136:139], v[36:39]
	v_mfma_f32_16x16x32_bf16 v[32:35], v[184:187], v[152:155], v[32:35]
	v_mfma_f32_16x16x32_bf16 v[60:63], v[164:167], v[148:151], v[60:63]
	v_mfma_f32_16x16x32_bf16 v[56:59], v[164:167], v[156:159], v[56:59]
	v_mfma_f32_16x16x32_bf16 v[52:55], v[172:175], v[148:151], v[52:55]
	v_mfma_f32_16x16x32_bf16 v[48:51], v[172:175], v[156:159], v[48:51]
	v_mfma_f32_16x16x32_bf16 v[44:47], v[180:183], v[148:151], v[44:47]
	v_mfma_f32_16x16x32_bf16 v[40:43], v[180:183], v[156:159], v[40:43]
	v_mfma_f32_16x16x32_bf16 v[36:39], v[188:191], v[148:151], v[36:39]
	v_mfma_f32_16x16x32_bf16 v[32:35], v[188:191], v[156:159], v[32:35]
	v_mfma_f32_16x16x32_bf16 v[28:31], v[160:163], v[192:195], v[28:31]
	v_mfma_f32_16x16x32_bf16 v[24:27], v[160:163], v[200:203], v[24:27]
	v_mfma_f32_16x16x32_bf16 v[20:23], v[168:171], v[192:195], v[20:23]
	v_mfma_f32_16x16x32_bf16 v[16:19], v[168:171], v[200:203], v[16:19]
	v_mfma_f32_16x16x32_bf16 v[12:15], v[176:179], v[192:195], v[12:15]
	v_mfma_f32_16x16x32_bf16 v[8:11], v[176:179], v[200:203], v[8:11]
	v_mfma_f32_16x16x32_bf16 v[4:7], v[184:187], v[192:195], v[4:7]
	v_mfma_f32_16x16x32_bf16 v[0:3], v[184:187], v[200:203], v[0:3]
	v_mfma_f32_16x16x32_bf16 v[28:31], v[164:167], v[196:199], v[28:31]
	v_mfma_f32_16x16x32_bf16 v[24:27], v[164:167], v[204:207], v[24:27]
	v_mfma_f32_16x16x32_bf16 v[20:23], v[172:175], v[196:199], v[20:23]
	v_mfma_f32_16x16x32_bf16 v[16:19], v[172:175], v[204:207], v[16:19]
	v_mfma_f32_16x16x32_bf16 v[12:15], v[180:183], v[196:199], v[12:15]
	v_mfma_f32_16x16x32_bf16 v[8:11], v[180:183], v[204:207], v[8:11]
	v_mfma_f32_16x16x32_bf16 v[4:7], v[188:191], v[196:199], v[4:7]
	v_mfma_f32_16x16x32_bf16 v[0:3], v[188:191], v[204:207], v[0:3]
	s_barrier
; #define STAGE(P, BASE, br, kt) do { const char* _g = (const char*)((BASE) + (size_t)(br) * K + (size_t)(kt) * G_BK); \
;     _Pragma("unroll") for (int _i = 0; _i < 2; ++_i) { \
;       __builtin_amdgcn_global_load_lds((const unsigned*)(_g + (size_t)_i * 128 * K + sg_off), (unsigned*)((char*)(P) + wid * 1024 + _i * 8192), 16, 0, 0); } } while (0)
; #define LDA(dst, b, h) _Pragma("unroll") for (int m = 0; m < 4; ++m) _Pragma("unroll") for (int k = 0; k < 2; ++k) \
;     dst[m][k] = *reinterpret_cast<const bf16x8*>((const char*)shm + aoff + (((b) * 2 + (h)) * 16384 + m * 2048 + k * 1024))
; #define LDB(dst, b, h) _Pragma("unroll") for (int n = 0; n < 2; ++n) _Pragma("unroll") for (int k = 0; k < 2; ++k) \
;     dst[n][k] = *reinterpret_cast<const bf16x8*>((const char*)shm + boff + (((b) * 2 + (h)) * 16384 + n * 2048 + k * 1024))
; #define WAIT_V(n) asm volatile("s_waitcnt vmcnt(" #n ")" ::: "memory")
; #define WAIT_L(n) asm volatile("s_waitcnt lgkmcnt(" #n ")" ::: "memory")
; #define BAR __builtin_amdgcn_s_barrier()
; #define SCHED __builtin_amdgcn_sched_barrier(0)
; template <class Epi>
; __device__ __forceinline__ void gemm_phase(const bfr* __restrict__ A, int lda, const bfr* __restrict__ Bt, int K,
;                                            int nM, int nN, const Epi& epi, bfr* shm, int wv, int nMfull, int ksplit) {
;     ...
;     for (int t = 0; t < nt - 2; t += 2) {
;       LDB(B0, 0, 0); SCHED; LDA(At, 0, 0); STAGE(SA(1, 1), Ak, brow + G_HALF, t + 1);
;       WAIT_L(8); BAR; WAIT_L(0); MMA(0, 0, At, B0); BAR; SCHED;
;       LDB(B1, 0, 1); STAGE(SB(0, 0), Bk, bcol, t + 2);
;       BAR; WAIT_L(0); MMA(0, 1, At, B1); BAR;
;       LDA(At, 0, 1); STAGE(SA(0, 0), Ak, brow, t + 2);
;       BAR; WAIT_L(0); MMA(1, 0, At, B0); BAR; SCHED;
;       STAGE(SB(0, 1), Bk, bcol + G_HALF, t + 2);
;       WAIT_V(6); BAR; MMA(1, 1, At, B1); BAR;
;       LDB(B0, 1, 0); SCHED; LDA(At, 1, 0); STAGE(SA(0, 1), Ak, brow + G_HALF, t + 2);
;       WAIT_L(8); BAR; WAIT_L(0); MMA(0, 0, At, B0); BAR; SCHED;
;       LDB(B1, 1, 1); STAGE(SB(1, 0), Bk, bcol, t + 3);
;       BAR; WAIT_L(0); MMA(0, 1, At, B1); BAR;
;       LDA(At, 1, 1); STAGE(SA(1, 0), Ak, brow, t + 3);
;       BAR; WAIT_L(0); MMA(1, 0, At, B0); BAR; SCHED;
;       STAGE(SB(1, 1), Bk, bcol + G_HALF, t + 3);
;       WAIT_V(6); BAR; MMA(1, 1, At, B1); BAR;
;     }
	ds_read_b128 v[136:139], v143 offset:32768
	ds_read_b128 v[148:151], v143 offset:33792
	ds_read_b128 v[152:155], v143 offset:34816
	ds_read_b128 v[156:159], v143 offset:35840
	ds_read_b128 v[160:163], v142 offset:32768
	ds_read_b128 v[164:167], v142 offset:33792
	ds_read_b128 v[168:171], v142 offset:34816
	ds_read_b128 v[172:175], v142 offset:35840
	ds_read_b128 v[176:179], v142 offset:36864
	ds_read_b128 v[180:183], v142 offset:37888
	ds_read_b128 v[184:187], v142 offset:38912
	ds_read_b128 v[188:191], v142 offset:39936
	ds_read_b128 v[192:195], v143 offset:49152
	ds_read_b128 v[196:199], v143 offset:50176
	ds_read_b128 v[200:203], v143 offset:51200
	ds_read_b128 v[204:207], v143 offset:52224
	s_mov_b32 m0, s82
	v_lshl_add_u64 v[216:217], v[140:141], 0, s[22:23]
	global_load_lds_dwordx4 v[216:217], off
	s_mov_b32 m0, s83
	v_lshl_add_u64 v[212:213], v[140:141], 0, s[24:25]
	global_load_lds_dwordx4 v[212:213], off
	s_waitcnt lgkmcnt(0)
	s_barrier
	v_mfma_f32_16x16x32_bf16 v[124:127], v[160:163], v[136:139], v[124:127]
	v_mfma_f32_16x16x32_bf16 v[120:123], v[160:163], v[152:155], v[120:123]
	v_mfma_f32_16x16x32_bf16 v[116:119], v[168:171], v[136:139], v[116:119]
	v_mfma_f32_16x16x32_bf16 v[112:115], v[168:171], v[152:155], v[112:115]
	v_mfma_f32_16x16x32_bf16 v[108:111], v[176:179], v[136:139], v[108:111]
	v_mfma_f32_16x16x32_bf16 v[104:107], v[176:179], v[152:155], v[104:107]
	v_mfma_f32_16x16x32_bf16 v[100:103], v[184:187], v[136:139], v[100:103]
	v_mfma_f32_16x16x32_bf16 v[96:99], v[184:187], v[152:155], v[96:99]
	v_mfma_f32_16x16x32_bf16 v[124:127], v[164:167], v[148:151], v[124:127]
	v_mfma_f32_16x16x32_bf16 v[120:123], v[164:167], v[156:159], v[120:123]
	v_mfma_f32_16x16x32_bf16 v[116:119], v[172:175], v[148:151], v[116:119]
	v_mfma_f32_16x16x32_bf16 v[112:115], v[172:175], v[156:159], v[112:115]
	v_mfma_f32_16x16x32_bf16 v[108:111], v[180:183], v[148:151], v[108:111]
	v_mfma_f32_16x16x32_bf16 v[104:107], v[180:183], v[156:159], v[104:107]
	v_mfma_f32_16x16x32_bf16 v[100:103], v[188:191], v[148:151], v[100:103]
	v_mfma_f32_16x16x32_bf16 v[96:99], v[188:191], v[156:159], v[96:99]
	v_mfma_f32_16x16x32_bf16 v[92:95], v[160:163], v[192:195], v[92:95]
	v_mfma_f32_16x16x32_bf16 v[88:91], v[160:163], v[200:203], v[88:91]
	v_mfma_f32_16x16x32_bf16 v[84:87], v[168:171], v[192:195], v[84:87]
	v_mfma_f32_16x16x32_bf16 v[80:83], v[168:171], v[200:203], v[80:83]
	v_mfma_f32_16x16x32_bf16 v[76:79], v[176:179], v[192:195], v[76:79]
	v_mfma_f32_16x16x32_bf16 v[72:75], v[176:179], v[200:203], v[72:75]
	v_mfma_f32_16x16x32_bf16 v[68:71], v[184:187], v[192:195], v[68:71]
	v_mfma_f32_16x16x32_bf16 v[64:67], v[184:187], v[200:203], v[64:67]
	v_mfma_f32_16x16x32_bf16 v[92:95], v[164:167], v[196:199], v[92:95]
	v_mfma_f32_16x16x32_bf16 v[88:91], v[164:167], v[204:207], v[88:91]
	v_mfma_f32_16x16x32_bf16 v[84:87], v[172:175], v[196:199], v[84:87]
	v_mfma_f32_16x16x32_bf16 v[80:83], v[172:175], v[204:207], v[80:83]
	v_mfma_f32_16x16x32_bf16 v[76:79], v[180:183], v[196:199], v[76:79]
	v_mfma_f32_16x16x32_bf16 v[72:75], v[180:183], v[204:207], v[72:75]
	v_mfma_f32_16x16x32_bf16 v[68:71], v[188:191], v[196:199], v[68:71]
	v_mfma_f32_16x16x32_bf16 v[64:67], v[188:191], v[204:207], v[64:67]
	s_barrier
	ds_read_b128 v[160:163], v142 offset:49152
	ds_read_b128 v[164:167], v142 offset:50176
	ds_read_b128 v[168:171], v142 offset:51200
	ds_read_b128 v[172:175], v142 offset:52224
	ds_read_b128 v[176:179], v142 offset:53248
	ds_read_b128 v[180:183], v142 offset:54272
	ds_read_b128 v[184:187], v142 offset:55296
	ds_read_b128 v[188:191], v142 offset:56320
	s_mov_b32 m0, s84
	v_lshl_add_u64 v[214:215], v[208:209], 0, s[26:27]
	global_load_lds_dwordx4 v[214:215], off
	s_mov_b32 m0, s85
	v_lshl_add_u64 v[216:217], v[208:209], 0, s[28:29]
	global_load_lds_dwordx4 v[216:217], off
	s_mov_b32 m0, s86
	v_lshl_add_u64 v[212:213], v[140:141], 0, s[30:31]
	global_load_lds_dwordx4 v[212:213], off
	s_mov_b32 m0, s87
	v_lshl_add_u64 v[214:215], v[140:141], 0, s[34:35]
	global_load_lds_dwordx4 v[214:215], off
	s_mov_b32 m0, s88
	v_lshl_add_u64 v[216:217], v[208:209], 0, s[36:37]
	global_load_lds_dwordx4 v[216:217], off
	s_mov_b32 m0, s89
	v_lshl_add_u64 v[212:213], v[208:209], 0, s[38:39]
	global_load_lds_dwordx4 v[212:213], off
	s_waitcnt vmcnt(6)
	s_waitcnt lgkmcnt(0)
	s_barrier
	v_mfma_f32_16x16x32_bf16 v[60:63], v[160:163], v[136:139], v[60:63]
	v_mfma_f32_16x16x32_bf16 v[56:59], v[160:163], v[152:155], v[56:59]
	v_mfma_f32_16x16x32_bf16 v[52:55], v[168:171], v[136:139], v[52:55]
	v_mfma_f32_16x16x32_bf16 v[48:51], v[168:171], v[152:155], v[48:51]
	v_mfma_f32_16x16x32_bf16 v[44:47], v[176:179], v[136:139], v[44:47]
	v_mfma_f32_16x16x32_bf16 v[40:43], v[176:179], v[152:155], v[40:43]
	v_mfma_f32_16x16x32_bf16 v[36:39], v[184:187], v[136:139], v[36:39]
	v_mfma_f32_16x16x32_bf16 v[32:35], v[184:187], v[152:155], v[32:35]
	v_mfma_f32_16x16x32_bf16 v[60:63], v[164:167], v[148:151], v[60:63]
	v_mfma_f32_16x16x32_bf16 v[56:59], v[164:167], v[156:159], v[56:59]
	v_mfma_f32_16x16x32_bf16 v[52:55], v[172:175], v[148:151], v[52:55]
	v_mfma_f32_16x16x32_bf16 v[48:51], v[172:175], v[156:159], v[48:51]
	v_mfma_f32_16x16x32_bf16 v[44:47], v[180:183], v[148:151], v[44:47]
	v_mfma_f32_16x16x32_bf16 v[40:43], v[180:183], v[156:159], v[40:43]
	v_mfma_f32_16x16x32_bf16 v[36:39], v[188:191], v[148:151], v[36:39]
	v_mfma_f32_16x16x32_bf16 v[32:35], v[188:191], v[156:159], v[32:35]
	v_mfma_f32_16x16x32_bf16 v[28:31], v[160:163], v[192:195], v[28:31]
	v_mfma_f32_16x16x32_bf16 v[24:27], v[160:163], v[200:203], v[24:27]
	v_mfma_f32_16x16x32_bf16 v[20:23], v[168:171], v[192:195], v[20:23]
	v_mfma_f32_16x16x32_bf16 v[16:19], v[168:171], v[200:203], v[16:19]
	v_mfma_f32_16x16x32_bf16 v[12:15], v[176:179], v[192:195], v[12:15]
	v_mfma_f32_16x16x32_bf16 v[8:11], v[176:179], v[200:203], v[8:11]
	v_mfma_f32_16x16x32_bf16 v[4:7], v[184:187], v[192:195], v[4:7]
	v_mfma_f32_16x16x32_bf16 v[0:3], v[184:187], v[200:203], v[0:3]
	v_mfma_f32_16x16x32_bf16 v[28:31], v[164:167], v[196:199], v[28:31]
	v_mfma_f32_16x16x32_bf16 v[24:27], v[164:167], v[204:207], v[24:27]
	v_mfma_f32_16x16x32_bf16 v[20:23], v[172:175], v[196:199], v[20:23]
	v_mfma_f32_16x16x32_bf16 v[16:19], v[172:175], v[204:207], v[16:19]
	v_mfma_f32_16x16x32_bf16 v[12:15], v[180:183], v[196:199], v[12:15]
	v_mfma_f32_16x16x32_bf16 v[8:11], v[180:183], v[204:207], v[8:11]
	v_mfma_f32_16x16x32_bf16 v[4:7], v[188:191], v[196:199], v[4:7]
	v_mfma_f32_16x16x32_bf16 v[0:3], v[188:191], v[204:207], v[0:3]
	s_add_i32 s1, s1, 2
	s_add_u32 s50, s50, 0x100
	s_addc_u32 s51, s51, 0
	s_add_u32 s52, s52, 0x100
	s_addc_u32 s53, s53, 0
	s_cmp_ge_i32 s1, s0
	s_barrier
	s_cbranch_scc0 .LBB0_1327

; #define STAGE(P, BASE, br, kt) do { const char* _g = (const char*)((BASE) + (size_t)(br) * K + (size_t)(kt) * G_BK); \
;     _Pragma("unroll") for (int _i = 0; _i < 2; ++_i) { \
;       __builtin_amdgcn_global_load_lds((const unsigned*)(_g + (size_t)_i * 128 * K + sg_off), (unsigned*)((char*)(P) + wid * 1024 + _i * 8192), 16, 0, 0); } } while (0)
; #define LDA(dst, b, h) _Pragma("unroll") for (int m = 0; m < 4; ++m) _Pragma("unroll") for (int k = 0; k < 2; ++k) \
;     dst[m][k] = *reinterpret_cast<const bf16x8*>((const char*)shm + aoff + (((b) * 2 + (h)) * 16384 + m * 2048 + k * 1024))
; #define LDB(dst, b, h) _Pragma("unroll") for (int n = 0; n < 2; ++n) _Pragma("unroll") for (int k = 0; k < 2; ++k) \
;     dst[n][k] = *reinterpret_cast<const bf16x8*>((const char*)shm + boff + (((b) * 2 + (h)) * 16384 + n * 2048 + k * 1024))
; #define WAIT_V(n) asm volatile("s_waitcnt vmcnt(" #n ")" ::: "memory")
; #define WAIT_L(n) asm volatile("s_waitcnt lgkmcnt(" #n ")" ::: "memory")
; #define BAR __builtin_amdgcn_s_barrier()
; #define SCHED __builtin_amdgcn_sched_barrier(0)
; template <class Epi>
; __device__ __forceinline__ void gemm_phase(const bfr* __restrict__ A, int lda, const bfr* __restrict__ Bt, int K,
;                                            int nM, int nN, const Epi& epi, bfr* shm, int wv, int nMfull, int ksplit) {
;     ...
;     for (int t = 0; t < nt - 2; t += 2) {
;       LDB(B0, 0, 0); SCHED; LDA(At, 0, 0); STAGE(SA(1, 1), Ak, brow + G_HALF, t + 1);
;       WAIT_L(8); BAR; WAIT_L(0); MMA(0, 0, At, B0); BAR; SCHED;
;       LDB(B1, 0, 1); STAGE(SB(0, 0), Bk, bcol, t + 2);
;       BAR; WAIT_L(0); MMA(0, 1, At, B1); BAR;
;       LDA(At, 0, 1); STAGE(SA(0, 0), Ak, brow, t + 2);
;       BAR; WAIT_L(0); MMA(1, 0, At, B0); BAR; SCHED;
;       STAGE(SB(0, 1), Bk, bcol + G_HALF, t + 2);
;       WAIT_V(6); BAR; MMA(1, 1, At, B1); BAR;
;       LDB(B0, 1, 0); SCHED; LDA(At, 1, 0); STAGE(SA(0, 1), Ak, brow + G_HALF, t + 2);
;       WAIT_L(8); BAR; WAIT_L(0); MMA(0, 0, At, B0); BAR; SCHED;
;       LDB(B1, 1, 1); STAGE(SB(1, 0), Bk, bcol, t + 3);
;       BAR; WAIT_L(0); MMA(0, 1, At, B1); BAR;
;       LDA(At, 1, 1); STAGE(SA(1, 0), Ak, brow, t + 3);
;       BAR; WAIT_L(0); MMA(1, 0, At, B0); BAR; SCHED;
;       STAGE(SB(1, 1), Bk, bcol + G_HALF, t + 3);
;       WAIT_V(6); BAR; MMA(1, 1, At, B1); BAR;
;     }
.LBB0_1368:
	ds_read_b128 v[136:139], v143
	ds_read_b128 v[148:151], v143 offset:1024
	ds_read_b128 v[152:155], v143 offset:2048
	ds_read_b128 v[156:159], v143 offset:3072
	ds_read_b128 v[160:163], v142
	ds_read_b128 v[164:167], v142 offset:1024
	ds_read_b128 v[168:171], v142 offset:2048
	ds_read_b128 v[172:175], v142 offset:3072
	ds_read_b128 v[176:179], v142 offset:4096
	ds_read_b128 v[180:183], v142 offset:5120
	ds_read_b128 v[184:187], v142 offset:6144
	ds_read_b128 v[188:191], v142 offset:7168
	ds_read_b128 v[192:195], v143 offset:16384
	ds_read_b128 v[196:199], v143 offset:17408
	ds_read_b128 v[200:203], v143 offset:18432
	ds_read_b128 v[204:207], v143 offset:19456
	v_lshl_add_u64 v[140:141], s[64:65], 0, v[134:135]
	v_lshl_add_u64 v[208:209], s[60:61], 0, v[134:135]
	s_mov_b32 m0, s47
	v_lshl_add_u64 v[212:213], v[140:141], 0, s[12:13]
	global_load_lds_dwordx4 v[212:213], off
	s_mov_b32 m0, s71
	v_lshl_add_u64 v[214:215], v[140:141], 0, s[14:15]
	global_load_lds_dwordx4 v[214:215], off
	s_waitcnt lgkmcnt(0)
	s_barrier
	v_mfma_f32_16x16x32_bf16 v[124:127], v[160:163], v[136:139], v[124:127]
	v_mfma_f32_16x16x32_bf16 v[120:123], v[160:163], v[152:155], v[120:123]
	v_mfma_f32_16x16x32_bf16 v[116:119], v[168:171], v[136:139], v[116:119]
	v_mfma_f32_16x16x32_bf16 v[112:115], v[168:171], v[152:155], v[112:115]
	v_mfma_f32_16x16x32_bf16 v[108:111], v[176:179], v[136:139], v[108:111]
	v_mfma_f32_16x16x32_bf16 v[104:107], v[176:179], v[152:155], v[104:107]
	v_mfma_f32_16x16x32_bf16 v[100:103], v[184:187], v[136:139], v[100:103]
	v_mfma_f32_16x16x32_bf16 v[96:99], v[184:187], v[152:155], v[96:99]
	v_mfma_f32_16x16x32_bf16 v[124:127], v[164:167], v[148:151], v[124:127]
	v_mfma_f32_16x16x32_bf16 v[120:123], v[164:167], v[156:159], v[120:123]
	v_mfma_f32_16x16x32_bf16 v[116:119], v[172:175], v[148:151], v[116:119]
	v_mfma_f32_16x16x32_bf16 v[112:115], v[172:175], v[156:159], v[112:115]
	v_mfma_f32_16x16x32_bf16 v[108:111], v[180:183], v[148:151], v[108:111]
	v_mfma_f32_16x16x32_bf16 v[104:107], v[180:183], v[156:159], v[104:107]
	v_mfma_f32_16x16x32_bf16 v[100:103], v[188:191], v[148:151], v[100:103]
	v_mfma_f32_16x16x32_bf16 v[96:99], v[188:191], v[156:159], v[96:99]
	v_mfma_f32_16x16x32_bf16 v[92:95], v[160:163], v[192:195], v[92:95]
	v_mfma_f32_16x16x32_bf16 v[88:91], v[160:163], v[200:203], v[88:91]
	v_mfma_f32_16x16x32_bf16 v[84:87], v[168:171], v[192:195], v[84:87]
	v_mfma_f32_16x16x32_bf16 v[80:83], v[168:171], v[200:203], v[80:83]
	v_mfma_f32_16x16x32_bf16 v[76:79], v[176:179], v[192:195], v[76:79]
	v_mfma_f32_16x16x32_bf16 v[72:75], v[176:179], v[200:203], v[72:75]
	v_mfma_f32_16x16x32_bf16 v[68:71], v[184:187], v[192:195], v[68:71]
	v_mfma_f32_16x16x32_bf16 v[64:67], v[184:187], v[200:203], v[64:67]
	v_mfma_f32_16x16x32_bf16 v[92:95], v[164:167], v[196:199], v[92:95]
	v_mfma_f32_16x16x32_bf16 v[88:91], v[164:167], v[204:207], v[88:91]
	v_mfma_f32_16x16x32_bf16 v[84:87], v[172:175], v[196:199], v[84:87]
	v_mfma_f32_16x16x32_bf16 v[80:83], v[172:175], v[204:207], v[80:83]
	v_mfma_f32_16x16x32_bf16 v[76:79], v[180:183], v[196:199], v[76:79]
	v_mfma_f32_16x16x32_bf16 v[72:75], v[180:183], v[204:207], v[72:75]
	v_mfma_f32_16x16x32_bf16 v[68:71], v[188:191], v[196:199], v[68:71]
	v_mfma_f32_16x16x32_bf16 v[64:67], v[188:191], v[204:207], v[64:67]
	s_barrier
	ds_read_b128 v[160:163], v142 offset:16384
	ds_read_b128 v[164:167], v142 offset:17408
	ds_read_b128 v[168:171], v142 offset:18432
	ds_read_b128 v[172:175], v142 offset:19456
	ds_read_b128 v[176:179], v142 offset:20480
	ds_read_b128 v[180:183], v142 offset:21504
	ds_read_b128 v[184:187], v142 offset:22528
	ds_read_b128 v[188:191], v142 offset:23552
	s_mov_b32 m0, s72
	s_mov_b64 s[96:97], 0x1080100
	v_lshl_add_u64 v[216:217], v[208:209], 0, s[96:97]
	global_load_lds_dwordx4 v[216:217], off
	s_mov_b32 m0, s73
	v_lshl_add_u64 v[212:213], v[208:209], 0, s[18:19]
	global_load_lds_dwordx4 v[212:213], off
	s_mov_b32 m0, s48
	v_lshl_add_u64 v[214:215], v[140:141], 0, s[24:25]
	global_load_lds_dwordx4 v[214:215], off
	s_mov_b32 m0, s74
	v_lshl_add_u64 v[216:217], v[140:141], 0, s[26:27]
	global_load_lds_dwordx4 v[216:217], off
	s_mov_b32 m0, s75
	v_lshl_add_u64 v[212:213], v[208:209], 0, s[28:29]
	global_load_lds_dwordx4 v[212:213], off
	s_mov_b32 m0, s62
	v_lshl_add_u64 v[214:215], v[208:209], 0, s[30:31]
	global_load_lds_dwordx4 v[214:215], off
	s_waitcnt vmcnt(6)
	s_waitcnt lgkmcnt(0)
	s_barrier
	v_mfma_f32_16x16x32_bf16 v[60:63], v[160:163], v[136:139], v[60:63]
	v_mfma_f32_16x16x32_bf16 v[56:59], v[160:163], v[152:155], v[56:59]
	v_mfma_f32_16x16x32_bf16 v[52:55], v[168:171], v[136:139], v[52:55]
	v_mfma_f32_16x16x32_bf16 v[48:51], v[168:171], v[152:155], v[48:51]
	v_mfma_f32_16x16x32_bf16 v[44:47], v[176:179], v[136:139], v[44:47]
	v_mfma_f32_16x16x32_bf16 v[40:43], v[176:179], v[152:155], v[40:43]
	v_mfma_f32_16x16x32_bf16 v[36:39], v[184:187], v[136:139], v[36:39]
	v_mfma_f32_16x16x32_bf16 v[32:35], v[184:187], v[152:155], v[32:35]
	v_mfma_f32_16x16x32_bf16 v[60:63], v[164:167], v[148:151], v[60:63]
	v_mfma_f32_16x16x32_bf16 v[56:59], v[164:167], v[156:159], v[56:59]
	v_mfma_f32_16x16x32_bf16 v[52:55], v[172:175], v[148:151], v[52:55]
	v_mfma_f32_16x16x32_bf16 v[48:51], v[172:175], v[156:159], v[48:51]
	v_mfma_f32_16x16x32_bf16 v[44:47], v[180:183], v[148:151], v[44:47]
	v_mfma_f32_16x16x32_bf16 v[40:43], v[180:183], v[156:159], v[40:43]
	v_mfma_f32_16x16x32_bf16 v[36:39], v[188:191], v[148:151], v[36:39]
	v_mfma_f32_16x16x32_bf16 v[32:35], v[188:191], v[156:159], v[32:35]
	v_mfma_f32_16x16x32_bf16 v[28:31], v[160:163], v[192:195], v[28:31]
	v_mfma_f32_16x16x32_bf16 v[24:27], v[160:163], v[200:203], v[24:27]
	v_mfma_f32_16x16x32_bf16 v[20:23], v[168:171], v[192:195], v[20:23]
	v_mfma_f32_16x16x32_bf16 v[16:19], v[168:171], v[200:203], v[16:19]
	v_mfma_f32_16x16x32_bf16 v[12:15], v[176:179], v[192:195], v[12:15]
	v_mfma_f32_16x16x32_bf16 v[8:11], v[176:179], v[200:203], v[8:11]
	v_mfma_f32_16x16x32_bf16 v[4:7], v[184:187], v[192:195], v[4:7]
	v_mfma_f32_16x16x32_bf16 v[0:3], v[184:187], v[200:203], v[0:3]
	v_mfma_f32_16x16x32_bf16 v[28:31], v[164:167], v[196:199], v[28:31]
	v_mfma_f32_16x16x32_bf16 v[24:27], v[164:167], v[204:207], v[24:27]
	v_mfma_f32_16x16x32_bf16 v[20:23], v[172:175], v[196:199], v[20:23]
	v_mfma_f32_16x16x32_bf16 v[16:19], v[172:175], v[204:207], v[16:19]
	v_mfma_f32_16x16x32_bf16 v[12:15], v[180:183], v[196:199], v[12:15]
	v_mfma_f32_16x16x32_bf16 v[8:11], v[180:183], v[204:207], v[8:11]
	v_mfma_f32_16x16x32_bf16 v[4:7], v[188:191], v[196:199], v[4:7]
	v_mfma_f32_16x16x32_bf16 v[0:3], v[188:191], v[204:207], v[0:3]
	s_barrier
; #define STAGE(P, BASE, br, kt) do { const char* _g = (const char*)((BASE) + (size_t)(br) * K + (size_t)(kt) * G_BK); \
;     _Pragma("unroll") for (int _i = 0; _i < 2; ++_i) { \
;       __builtin_amdgcn_global_load_lds((const unsigned*)(_g + (size_t)_i * 128 * K + sg_off), (unsigned*)((char*)(P) + wid * 1024 + _i * 8192), 16, 0, 0); } } while (0)
; #define LDA(dst, b, h) _Pragma("unroll") for (int m = 0; m < 4; ++m) _Pragma("unroll") for (int k = 0; k < 2; ++k) \
;     dst[m][k] = *reinterpret_cast<const bf16x8*>((const char*)shm + aoff + (((b) * 2 + (h)) * 16384 + m * 2048 + k * 1024))
; #define LDB(dst, b, h) _Pragma("unroll") for (int n = 0; n < 2; ++n) _Pragma("unroll") for (int k = 0; k < 2; ++k) \
;     dst[n][k] = *reinterpret_cast<const bf16x8*>((const char*)shm + boff + (((b) * 2 + (h)) * 16384 + n * 2048 + k * 1024))
; #define WAIT_V(n) asm volatile("s_waitcnt vmcnt(" #n ")" ::: "memory")
; #define WAIT_L(n) asm volatile("s_waitcnt lgkmcnt(" #n ")" ::: "memory")
; #define BAR __builtin_amdgcn_s_barrier()
; #define SCHED __builtin_amdgcn_sched_barrier(0)
; template <class Epi>
; __device__ __forceinline__ void gemm_phase(const bfr* __restrict__ A, int lda, const bfr* __restrict__ Bt, int K,
;                                            int nM, int nN, const Epi& epi, bfr* shm, int wv, int nMfull, int ksplit) {
;     ...
;     for (int t = 0; t < nt - 2; t += 2) {
;       LDB(B0, 0, 0); SCHED; LDA(At, 0, 0); STAGE(SA(1, 1), Ak, brow + G_HALF, t + 1);
;       WAIT_L(8); BAR; WAIT_L(0); MMA(0, 0, At, B0); BAR; SCHED;
;       LDB(B1, 0, 1); STAGE(SB(0, 0), Bk, bcol, t + 2);
;       BAR; WAIT_L(0); MMA(0, 1, At, B1); BAR;
;       LDA(At, 0, 1); STAGE(SA(0, 0), Ak, brow, t + 2);
;       BAR; WAIT_L(0); MMA(1, 0, At, B0); BAR; SCHED;
;       STAGE(SB(0, 1), Bk, bcol + G_HALF, t + 2);
;       WAIT_V(6); BAR; MMA(1, 1, At, B1); BAR;
;       LDB(B0, 1, 0); SCHED; LDA(At, 1, 0); STAGE(SA(0, 1), Ak, brow + G_HALF, t + 2);
;       WAIT_L(8); BAR; WAIT_L(0); MMA(0, 0, At, B0); BAR; SCHED;
;       LDB(B1, 1, 1); STAGE(SB(1, 0), Bk, bcol, t + 3);
;       BAR; WAIT_L(0); MMA(0, 1, At, B1); BAR;
;       LDA(At, 1, 1); STAGE(SA(1, 0), Ak, brow, t + 3);
;       BAR; WAIT_L(0); MMA(1, 0, At, B0); BAR; SCHED;
;       STAGE(SB(1, 1), Bk, bcol + G_HALF, t + 3);
;       WAIT_V(6); BAR; MMA(1, 1, At, B1); BAR;
;     }
	ds_read_b128 v[136:139], v143 offset:32768
	ds_read_b128 v[148:151], v143 offset:33792
	ds_read_b128 v[152:155], v143 offset:34816
	ds_read_b128 v[156:159], v143 offset:35840
	ds_read_b128 v[160:163], v142 offset:32768
	ds_read_b128 v[164:167], v142 offset:33792
	ds_read_b128 v[168:171], v142 offset:34816
	ds_read_b128 v[172:175], v142 offset:35840
	ds_read_b128 v[176:179], v142 offset:36864
	ds_read_b128 v[180:183], v142 offset:37888
	ds_read_b128 v[184:187], v142 offset:38912
	ds_read_b128 v[188:191], v142 offset:39936
	ds_read_b128 v[192:195], v143 offset:49152
	ds_read_b128 v[196:199], v143 offset:50176
	ds_read_b128 v[200:203], v143 offset:51200
	ds_read_b128 v[204:207], v143 offset:52224
	s_mov_b32 m0, s63
	v_lshl_add_u64 v[216:217], v[140:141], 0, s[8:9]
	global_load_lds_dwordx4 v[216:217], off
	s_mov_b32 m0, s66
	v_lshl_add_u64 v[212:213], v[140:141], 0, s[10:11]
	global_load_lds_dwordx4 v[212:213], off
	s_waitcnt lgkmcnt(0)
	s_barrier
	v_mfma_f32_16x16x32_bf16 v[124:127], v[160:163], v[136:139], v[124:127]
	v_mfma_f32_16x16x32_bf16 v[120:123], v[160:163], v[152:155], v[120:123]
	v_mfma_f32_16x16x32_bf16 v[116:119], v[168:171], v[136:139], v[116:119]
	v_mfma_f32_16x16x32_bf16 v[112:115], v[168:171], v[152:155], v[112:115]
	v_mfma_f32_16x16x32_bf16 v[108:111], v[176:179], v[136:139], v[108:111]
	v_mfma_f32_16x16x32_bf16 v[104:107], v[176:179], v[152:155], v[104:107]
	v_mfma_f32_16x16x32_bf16 v[100:103], v[184:187], v[136:139], v[100:103]
	v_mfma_f32_16x16x32_bf16 v[96:99], v[184:187], v[152:155], v[96:99]
	v_mfma_f32_16x16x32_bf16 v[124:127], v[164:167], v[148:151], v[124:127]
	v_mfma_f32_16x16x32_bf16 v[120:123], v[164:167], v[156:159], v[120:123]
	v_mfma_f32_16x16x32_bf16 v[116:119], v[172:175], v[148:151], v[116:119]
	v_mfma_f32_16x16x32_bf16 v[112:115], v[172:175], v[156:159], v[112:115]
	v_mfma_f32_16x16x32_bf16 v[108:111], v[180:183], v[148:151], v[108:111]
	v_mfma_f32_16x16x32_bf16 v[104:107], v[180:183], v[156:159], v[104:107]
	v_mfma_f32_16x16x32_bf16 v[100:103], v[188:191], v[148:151], v[100:103]
	v_mfma_f32_16x16x32_bf16 v[96:99], v[188:191], v[156:159], v[96:99]
	v_mfma_f32_16x16x32_bf16 v[92:95], v[160:163], v[192:195], v[92:95]
	v_mfma_f32_16x16x32_bf16 v[88:91], v[160:163], v[200:203], v[88:91]
	v_mfma_f32_16x16x32_bf16 v[84:87], v[168:171], v[192:195], v[84:87]
	v_mfma_f32_16x16x32_bf16 v[80:83], v[168:171], v[200:203], v[80:83]
	v_mfma_f32_16x16x32_bf16 v[76:79], v[176:179], v[192:195], v[76:79]
	v_mfma_f32_16x16x32_bf16 v[72:75], v[176:179], v[200:203], v[72:75]
	v_mfma_f32_16x16x32_bf16 v[68:71], v[184:187], v[192:195], v[68:71]
	v_mfma_f32_16x16x32_bf16 v[64:67], v[184:187], v[200:203], v[64:67]
	v_mfma_f32_16x16x32_bf16 v[92:95], v[164:167], v[196:199], v[92:95]
	v_mfma_f32_16x16x32_bf16 v[88:91], v[164:167], v[204:207], v[88:91]
	v_mfma_f32_16x16x32_bf16 v[84:87], v[172:175], v[196:199], v[84:87]
	v_mfma_f32_16x16x32_bf16 v[80:83], v[172:175], v[204:207], v[80:83]
	v_mfma_f32_16x16x32_bf16 v[76:79], v[180:183], v[196:199], v[76:79]
	v_mfma_f32_16x16x32_bf16 v[72:75], v[180:183], v[204:207], v[72:75]
	v_mfma_f32_16x16x32_bf16 v[68:71], v[188:191], v[196:199], v[68:71]
	v_mfma_f32_16x16x32_bf16 v[64:67], v[188:191], v[204:207], v[64:67]
	s_barrier
	ds_read_b128 v[160:163], v142 offset:49152
	ds_read_b128 v[164:167], v142 offset:50176
	ds_read_b128 v[168:171], v142 offset:51200
	ds_read_b128 v[172:175], v142 offset:52224
	ds_read_b128 v[176:179], v142 offset:53248
	ds_read_b128 v[180:183], v142 offset:54272
	ds_read_b128 v[184:187], v142 offset:55296
	ds_read_b128 v[188:191], v142 offset:56320
	s_mov_b32 m0, s67
	v_lshl_add_u64 v[214:215], v[208:209], 0, s[34:35]
	global_load_lds_dwordx4 v[214:215], off
	s_mov_b32 m0, s4
	v_lshl_add_u64 v[216:217], v[208:209], 0, s[36:37]
	global_load_lds_dwordx4 v[216:217], off
	s_mov_b32 m0, s5
	v_lshl_add_u64 v[212:213], v[140:141], 0, s[38:39]
	global_load_lds_dwordx4 v[212:213], off
	s_mov_b32 m0, s6
	v_lshl_add_u64 v[214:215], v[140:141], 0, s[40:41]
	global_load_lds_dwordx4 v[214:215], off
	s_mov_b32 m0, s7
	v_lshl_add_u64 v[216:217], v[208:209], 0, s[42:43]
	global_load_lds_dwordx4 v[216:217], off
	s_mov_b32 m0, s46
	v_lshl_add_u64 v[212:213], v[208:209], 0, s[44:45]
	global_load_lds_dwordx4 v[212:213], off
	s_waitcnt vmcnt(6)
	s_waitcnt lgkmcnt(0)
	s_barrier
	v_mfma_f32_16x16x32_bf16 v[60:63], v[160:163], v[136:139], v[60:63]
	v_mfma_f32_16x16x32_bf16 v[56:59], v[160:163], v[152:155], v[56:59]
	v_mfma_f32_16x16x32_bf16 v[52:55], v[168:171], v[136:139], v[52:55]
	v_mfma_f32_16x16x32_bf16 v[48:51], v[168:171], v[152:155], v[48:51]
	v_mfma_f32_16x16x32_bf16 v[44:47], v[176:179], v[136:139], v[44:47]
	v_mfma_f32_16x16x32_bf16 v[40:43], v[176:179], v[152:155], v[40:43]
	v_mfma_f32_16x16x32_bf16 v[36:39], v[184:187], v[136:139], v[36:39]
	v_mfma_f32_16x16x32_bf16 v[32:35], v[184:187], v[152:155], v[32:35]
	v_mfma_f32_16x16x32_bf16 v[60:63], v[164:167], v[148:151], v[60:63]
	v_mfma_f32_16x16x32_bf16 v[56:59], v[164:167], v[156:159], v[56:59]
	v_mfma_f32_16x16x32_bf16 v[52:55], v[172:175], v[148:151], v[52:55]
	v_mfma_f32_16x16x32_bf16 v[48:51], v[172:175], v[156:159], v[48:51]
	v_mfma_f32_16x16x32_bf16 v[44:47], v[180:183], v[148:151], v[44:47]
	v_mfma_f32_16x16x32_bf16 v[40:43], v[180:183], v[156:159], v[40:43]
	v_mfma_f32_16x16x32_bf16 v[36:39], v[188:191], v[148:151], v[36:39]
	v_mfma_f32_16x16x32_bf16 v[32:35], v[188:191], v[156:159], v[32:35]
	v_mfma_f32_16x16x32_bf16 v[28:31], v[160:163], v[192:195], v[28:31]
	v_mfma_f32_16x16x32_bf16 v[24:27], v[160:163], v[200:203], v[24:27]
	v_mfma_f32_16x16x32_bf16 v[20:23], v[168:171], v[192:195], v[20:23]
	v_mfma_f32_16x16x32_bf16 v[16:19], v[168:171], v[200:203], v[16:19]
	v_mfma_f32_16x16x32_bf16 v[12:15], v[176:179], v[192:195], v[12:15]
	v_mfma_f32_16x16x32_bf16 v[8:11], v[176:179], v[200:203], v[8:11]
	v_mfma_f32_16x16x32_bf16 v[4:7], v[184:187], v[192:195], v[4:7]
	v_mfma_f32_16x16x32_bf16 v[0:3], v[184:187], v[200:203], v[0:3]
	v_mfma_f32_16x16x32_bf16 v[28:31], v[164:167], v[196:199], v[28:31]
	v_mfma_f32_16x16x32_bf16 v[24:27], v[164:167], v[204:207], v[24:27]
	v_mfma_f32_16x16x32_bf16 v[20:23], v[172:175], v[196:199], v[20:23]
	v_mfma_f32_16x16x32_bf16 v[16:19], v[172:175], v[204:207], v[16:19]
	v_mfma_f32_16x16x32_bf16 v[12:15], v[180:183], v[196:199], v[12:15]
	v_mfma_f32_16x16x32_bf16 v[8:11], v[180:183], v[204:207], v[8:11]
	v_mfma_f32_16x16x32_bf16 v[4:7], v[188:191], v[196:199], v[4:7]
	v_mfma_f32_16x16x32_bf16 v[0:3], v[188:191], v[204:207], v[0:3]
	s_add_i32 s59, s59, 2
	s_add_u32 s60, s60, 0x100
	s_addc_u32 s61, s61, 0
	s_add_u32 s64, s64, 0x100
	s_addc_u32 s65, s65, 0
	s_cmp_ge_i32 s59, s57
	s_barrier
	s_cbranch_scc0 .LBB0_1368
